# hand-scheduled GDN/RWKV recurrence loops (fewer VALU, transposed DPP reduction), batched loads in lru_carry/conv_w/prep_rw2, pipelined residual epilogues of down/out GEMMs
# speedup vs baseline: 1.0308x; 1.0308x over previous
.LBB0_182:
	s_add_u32 s26, s38, 0x4000
	s_addc_u32 s27, s39, 0
	s_cmpk_eq_i32 s61, 0x54
	s_cselect_b32 s48, s0, s26
	s_cselect_b32 s49, s1, s27
	s_cselect_b32 s26, s24, s59
	s_cselect_b32 s27, s25, s60
	s_add_u32 s42, s48, 0x8000
	s_addc_u32 s43, s49, 0
	s_add_i32 s62, 0, 0x10000
	v_add_u32_e32 v134, s62, v155
	ds_read_b128 v[148:151], v134
	ds_read_b128 v[158:161], v134 offset:1024
	ds_read_b128 v[162:165], v134 offset:2048
	ds_read_b128 v[180:183], v134 offset:3072
	v_lshl_add_u64 v[134:135], s[38:39], 0, v[144:145]
	s_add_i32 m0, s7, 0xc000
	ds_read_b128 v[184:187], v157
	ds_read_b128 v[188:191], v157 offset:1024
	ds_read_b128 v[192:195], v157 offset:2048
	ds_read_b128 v[196:199], v157 offset:3072
	ds_read_b128 v[200:203], v157 offset:4096
	ds_read_b128 v[204:207], v157 offset:5120
	ds_read_b128 v[208:211], v157 offset:6144
	ds_read_b128 v[212:215], v157 offset:7168
	global_load_lds_dwordx4 v[134:135], off
	v_lshl_add_u64 v[134:135], s[38:39], 0, v[146:147]
	s_add_i32 m0, s7, 0xe000
	s_nop 0
	global_load_lds_dwordx4 v[134:135], off
	s_waitcnt lgkmcnt(8)
	s_barrier
	s_waitcnt lgkmcnt(0)
	s_setprio 1
	s_waitcnt lgkmcnt(0)
	v_mfma_f32_16x16x32_bf16 v[126:129], v[148:151], v[184:187], v[126:129]
	v_mfma_f32_16x16x32_bf16 v[122:125], v[162:165], v[184:187], v[122:125]
	v_mfma_f32_16x16x32_bf16 v[110:113], v[148:151], v[192:195], v[110:113]
	v_mfma_f32_16x16x32_bf16 v[106:109], v[162:165], v[192:195], v[106:109]
	v_mfma_f32_16x16x32_bf16 v[94:97], v[148:151], v[200:203], v[94:97]
	v_mfma_f32_16x16x32_bf16 v[90:93], v[162:165], v[200:203], v[90:93]
	v_mfma_f32_16x16x32_bf16 v[78:81], v[148:151], v[208:211], v[78:81]
	v_mfma_f32_16x16x32_bf16 v[74:77], v[162:165], v[208:211], v[74:77]
	v_mfma_f32_16x16x32_bf16 v[126:129], v[158:161], v[188:191], v[126:129]
	v_mfma_f32_16x16x32_bf16 v[122:125], v[180:183], v[188:191], v[122:125]
	v_mfma_f32_16x16x32_bf16 v[110:113], v[158:161], v[196:199], v[110:113]
	v_mfma_f32_16x16x32_bf16 v[106:109], v[180:183], v[196:199], v[106:109]
	v_mfma_f32_16x16x32_bf16 v[94:97], v[158:161], v[204:207], v[94:97]
	v_mfma_f32_16x16x32_bf16 v[90:93], v[180:183], v[204:207], v[90:93]
	v_mfma_f32_16x16x32_bf16 v[78:81], v[158:161], v[212:215], v[78:81]
	v_mfma_f32_16x16x32_bf16 v[74:77], v[180:183], v[212:215], v[74:77]
	s_setprio 0
	s_barrier
	s_add_i32 s64, 0, 0x14000
	v_add_u32_e32 v134, s64, v155
	s_add_i32 s62, s62, s6
	ds_read_b128 v[216:219], v134
	ds_read_b128 v[220:223], v134 offset:1024
	ds_read_b128 v[224:227], v134 offset:2048
	ds_read_b128 v[228:231], v134 offset:3072
	v_lshl_add_u64 v[134:135], s[26:27], 0, v[0:1]
	s_mov_b32 m0, s62
	v_lshl_add_u64 v[152:153], s[26:27], 0, v[138:139]
	global_load_lds_dwordx4 v[134:135], off
	s_add_i32 m0, s62, 0x2000
	s_nop 0
	global_load_lds_dwordx4 v[152:153], off
	s_barrier
	s_waitcnt lgkmcnt(0)
	s_setprio 1
	s_waitcnt lgkmcnt(0)
	v_mfma_f32_16x16x32_bf16 v[118:121], v[216:219], v[184:187], v[118:121]
	v_mfma_f32_16x16x32_bf16 v[114:117], v[224:227], v[184:187], v[114:117]
	v_mfma_f32_16x16x32_bf16 v[102:105], v[216:219], v[192:195], v[102:105]
	v_mfma_f32_16x16x32_bf16 v[98:101], v[224:227], v[192:195], v[98:101]
	v_mfma_f32_16x16x32_bf16 v[86:89], v[216:219], v[200:203], v[86:89]
	v_mfma_f32_16x16x32_bf16 v[82:85], v[224:227], v[200:203], v[82:85]
	v_mfma_f32_16x16x32_bf16 v[70:73], v[216:219], v[208:211], v[70:73]
	v_mfma_f32_16x16x32_bf16 v[66:69], v[224:227], v[208:211], v[66:69]
	v_mfma_f32_16x16x32_bf16 v[118:121], v[220:223], v[188:191], v[118:121]
	v_mfma_f32_16x16x32_bf16 v[114:117], v[228:231], v[188:191], v[114:117]
	v_mfma_f32_16x16x32_bf16 v[102:105], v[220:223], v[196:199], v[102:105]
	v_mfma_f32_16x16x32_bf16 v[98:101], v[228:231], v[196:199], v[98:101]
	v_mfma_f32_16x16x32_bf16 v[86:89], v[220:223], v[204:207], v[86:89]
	v_mfma_f32_16x16x32_bf16 v[82:85], v[228:231], v[204:207], v[82:85]
	v_mfma_f32_16x16x32_bf16 v[70:73], v[220:223], v[212:215], v[70:73]
	v_mfma_f32_16x16x32_bf16 v[66:69], v[228:231], v[212:215], v[66:69]
	s_setprio 0
	s_mov_b32 m0, s7
	v_lshl_add_u64 v[166:167], s[48:49], 0, v[142:143]
	s_barrier
	ds_read_b128 v[184:187], v157 offset:16384
	ds_read_b128 v[188:191], v157 offset:17408
	ds_read_b128 v[192:195], v157 offset:18432
	ds_read_b128 v[196:199], v157 offset:19456
	ds_read_b128 v[200:203], v157 offset:20480
	ds_read_b128 v[204:207], v157 offset:21504
	ds_read_b128 v[208:211], v157 offset:22528
	ds_read_b128 v[212:215], v157 offset:23552
	global_load_lds_dwordx4 v[166:167], off
	v_lshl_add_u64 v[166:167], s[48:49], 0, v[140:141]
	s_mov_b32 m0, s14
	s_nop 0
	global_load_lds_dwordx4 v[166:167], off
	s_barrier
	s_waitcnt lgkmcnt(0)
	s_setprio 1
	s_waitcnt lgkmcnt(0)
	v_mfma_f32_16x16x32_bf16 v[62:65], v[148:151], v[184:187], v[62:65]
	v_mfma_f32_16x16x32_bf16 v[58:61], v[162:165], v[184:187], v[58:61]
	v_mfma_f32_16x16x32_bf16 v[46:49], v[148:151], v[192:195], v[46:49]
	v_mfma_f32_16x16x32_bf16 v[42:45], v[162:165], v[192:195], v[42:45]
	v_mfma_f32_16x16x32_bf16 v[30:33], v[148:151], v[200:203], v[30:33]
	v_mfma_f32_16x16x32_bf16 v[26:29], v[162:165], v[200:203], v[26:29]
	v_mfma_f32_16x16x32_bf16 v[14:17], v[148:151], v[208:211], v[14:17]
	v_mfma_f32_16x16x32_bf16 v[10:13], v[162:165], v[208:211], v[10:13]
	v_mfma_f32_16x16x32_bf16 v[62:65], v[158:161], v[188:191], v[62:65]
	v_mfma_f32_16x16x32_bf16 v[58:61], v[180:183], v[188:191], v[58:61]
	v_mfma_f32_16x16x32_bf16 v[46:49], v[158:161], v[196:199], v[46:49]
	v_mfma_f32_16x16x32_bf16 v[42:45], v[180:183], v[196:199], v[42:45]
	v_mfma_f32_16x16x32_bf16 v[30:33], v[158:161], v[204:207], v[30:33]
	v_mfma_f32_16x16x32_bf16 v[26:29], v[180:183], v[204:207], v[26:29]
	v_mfma_f32_16x16x32_bf16 v[14:17], v[158:161], v[212:215], v[14:17]
	v_mfma_f32_16x16x32_bf16 v[10:13], v[180:183], v[212:215], v[10:13]
	s_setprio 0
	s_barrier
	s_add_u32 s62, s26, 0x160000
	s_addc_u32 s63, s27, 0
	s_add_i32 s64, s64, s6
	v_lshl_add_u64 v[148:149], s[62:63], 0, v[0:1]
	s_mov_b32 m0, s64
	s_nop 0
	global_load_lds_dwordx4 v[148:149], off
	v_lshl_add_u64 v[148:149], s[62:63], 0, v[138:139]
	s_add_i32 m0, s64, 0x2000
	s_nop 0
	global_load_lds_dwordx4 v[148:149], off
	s_waitcnt vmcnt(6)
	s_barrier
	s_setprio 1
	v_mfma_f32_16x16x32_bf16 v[54:57], v[216:219], v[184:187], v[54:57]
	v_mfma_f32_16x16x32_bf16 v[50:53], v[224:227], v[184:187], v[50:53]
	v_mfma_f32_16x16x32_bf16 v[38:41], v[216:219], v[192:195], v[38:41]
	v_mfma_f32_16x16x32_bf16 v[34:37], v[224:227], v[192:195], v[34:37]
	v_mfma_f32_16x16x32_bf16 v[22:25], v[216:219], v[200:203], v[22:25]
	v_mfma_f32_16x16x32_bf16 v[18:21], v[224:227], v[200:203], v[18:21]
	v_mfma_f32_16x16x32_bf16 v[6:9], v[216:219], v[208:211], v[6:9]
	v_mfma_f32_16x16x32_bf16 v[2:5], v[224:227], v[208:211], v[2:5]
	v_mfma_f32_16x16x32_bf16 v[54:57], v[220:223], v[188:191], v[54:57]
	v_mfma_f32_16x16x32_bf16 v[50:53], v[228:231], v[188:191], v[50:53]
	v_mfma_f32_16x16x32_bf16 v[38:41], v[220:223], v[196:199], v[38:41]
	v_mfma_f32_16x16x32_bf16 v[34:37], v[228:231], v[196:199], v[34:37]
	v_mfma_f32_16x16x32_bf16 v[22:25], v[220:223], v[204:207], v[22:25]
	v_mfma_f32_16x16x32_bf16 v[18:21], v[228:231], v[204:207], v[18:21]
	v_mfma_f32_16x16x32_bf16 v[6:9], v[220:223], v[212:215], v[6:9]
	v_mfma_f32_16x16x32_bf16 v[2:5], v[228:231], v[212:215], v[2:5]
	s_setprio 0
	s_add_i32 s62, 0, 0x18000
	v_add_u32_e32 v166, s62, v155
	s_barrier
	ds_read_b128 v[148:151], v166
	ds_read_b128 v[158:161], v166 offset:1024
	ds_read_b128 v[162:165], v166 offset:2048
	ds_read_b128 v[180:183], v166 offset:3072
	s_add_u32 s48, s48, 0x4000
	s_addc_u32 s49, s49, 0
	s_mov_b32 m0, s50
	v_lshl_add_u64 v[166:167], s[48:49], 0, v[142:143]
	ds_read_b128 v[184:187], v157 offset:32768
	ds_read_b128 v[188:191], v157 offset:33792
	ds_read_b128 v[192:195], v157 offset:34816
	ds_read_b128 v[196:199], v157 offset:35840
	ds_read_b128 v[200:203], v157 offset:36864
	ds_read_b128 v[204:207], v157 offset:37888
	ds_read_b128 v[208:211], v157 offset:38912
	ds_read_b128 v[212:215], v157 offset:39936
	global_load_lds_dwordx4 v[166:167], off
	v_lshl_add_u64 v[166:167], s[48:49], 0, v[140:141]
	s_mov_b32 m0, s51
	s_nop 0
	global_load_lds_dwordx4 v[166:167], off
	s_waitcnt lgkmcnt(8)
	s_barrier
	s_waitcnt lgkmcnt(0)
	s_setprio 1
	s_waitcnt lgkmcnt(0)
	v_mfma_f32_16x16x32_bf16 v[126:129], v[148:151], v[184:187], v[126:129]
	v_mfma_f32_16x16x32_bf16 v[122:125], v[162:165], v[184:187], v[122:125]
	v_mfma_f32_16x16x32_bf16 v[110:113], v[148:151], v[192:195], v[110:113]
	v_mfma_f32_16x16x32_bf16 v[106:109], v[162:165], v[192:195], v[106:109]
	v_mfma_f32_16x16x32_bf16 v[94:97], v[148:151], v[200:203], v[94:97]
	v_mfma_f32_16x16x32_bf16 v[90:93], v[162:165], v[200:203], v[90:93]
	v_mfma_f32_16x16x32_bf16 v[78:81], v[148:151], v[208:211], v[78:81]
	v_mfma_f32_16x16x32_bf16 v[74:77], v[162:165], v[208:211], v[74:77]
	v_mfma_f32_16x16x32_bf16 v[126:129], v[158:161], v[188:191], v[126:129]
	v_mfma_f32_16x16x32_bf16 v[122:125], v[180:183], v[188:191], v[122:125]
	v_mfma_f32_16x16x32_bf16 v[110:113], v[158:161], v[196:199], v[110:113]
	v_mfma_f32_16x16x32_bf16 v[106:109], v[180:183], v[196:199], v[106:109]
	v_mfma_f32_16x16x32_bf16 v[94:97], v[158:161], v[204:207], v[94:97]
	v_mfma_f32_16x16x32_bf16 v[90:93], v[180:183], v[204:207], v[90:93]
	v_mfma_f32_16x16x32_bf16 v[78:81], v[158:161], v[212:215], v[78:81]
	v_mfma_f32_16x16x32_bf16 v[74:77], v[180:183], v[212:215], v[74:77]
	s_setprio 0
	s_barrier
	s_add_i32 s48, 0, 0x1c000
	s_add_i32 s49, s62, s6
	v_add_u32_e32 v166, s48, v155
	v_lshl_add_u64 v[134:135], v[134:135], 0, s[10:11]
	s_mov_b32 m0, s49
	ds_read_b128 v[216:219], v166
	ds_read_b128 v[220:223], v166 offset:1024
	ds_read_b128 v[224:227], v166 offset:2048
	ds_read_b128 v[228:231], v166 offset:3072
	global_load_lds_dwordx4 v[134:135], off
	v_lshl_add_u64 v[134:135], v[152:153], 0, s[10:11]
	s_add_i32 m0, s49, 0x2000
	s_nop 0
	global_load_lds_dwordx4 v[134:135], off
	s_barrier
	s_waitcnt lgkmcnt(0)
	s_setprio 1
	s_waitcnt lgkmcnt(0)
	v_mfma_f32_16x16x32_bf16 v[118:121], v[216:219], v[184:187], v[118:121]
	v_mfma_f32_16x16x32_bf16 v[114:117], v[224:227], v[184:187], v[114:117]
	v_mfma_f32_16x16x32_bf16 v[102:105], v[216:219], v[192:195], v[102:105]
	v_mfma_f32_16x16x32_bf16 v[98:101], v[224:227], v[192:195], v[98:101]
	v_mfma_f32_16x16x32_bf16 v[86:89], v[216:219], v[200:203], v[86:89]
	v_mfma_f32_16x16x32_bf16 v[82:85], v[224:227], v[200:203], v[82:85]
	v_mfma_f32_16x16x32_bf16 v[70:73], v[216:219], v[208:211], v[70:73]
	v_mfma_f32_16x16x32_bf16 v[66:69], v[224:227], v[208:211], v[66:69]
	v_mfma_f32_16x16x32_bf16 v[118:121], v[220:223], v[188:191], v[118:121]
	v_mfma_f32_16x16x32_bf16 v[114:117], v[228:231], v[188:191], v[114:117]
	v_mfma_f32_16x16x32_bf16 v[102:105], v[220:223], v[196:199], v[102:105]
	v_mfma_f32_16x16x32_bf16 v[98:101], v[228:231], v[196:199], v[98:101]
	v_mfma_f32_16x16x32_bf16 v[86:89], v[220:223], v[204:207], v[86:89]
	v_mfma_f32_16x16x32_bf16 v[82:85], v[228:231], v[204:207], v[82:85]
	v_mfma_f32_16x16x32_bf16 v[70:73], v[220:223], v[212:215], v[70:73]
	v_mfma_f32_16x16x32_bf16 v[66:69], v[228:231], v[212:215], v[66:69]
	s_setprio 0
	s_mov_b32 m0, s52
	v_lshl_add_u64 v[134:135], s[42:43], 0, v[142:143]
	s_barrier
	ds_read_b128 v[184:187], v157 offset:49152
	ds_read_b128 v[188:191], v157 offset:50176
	ds_read_b128 v[192:195], v157 offset:51200
	ds_read_b128 v[196:199], v157 offset:52224
	ds_read_b128 v[200:203], v157 offset:53248
	ds_read_b128 v[204:207], v157 offset:54272
	ds_read_b128 v[208:211], v157 offset:55296
	ds_read_b128 v[212:215], v157 offset:56320
	global_load_lds_dwordx4 v[134:135], off
	v_lshl_add_u64 v[134:135], s[42:43], 0, v[140:141]
	s_mov_b32 m0, s53
	s_nop 0
	global_load_lds_dwordx4 v[134:135], off
	s_barrier
	s_waitcnt lgkmcnt(0)
	s_setprio 1
	s_waitcnt lgkmcnt(0)
	v_mfma_f32_16x16x32_bf16 v[62:65], v[148:151], v[184:187], v[62:65]
	v_mfma_f32_16x16x32_bf16 v[58:61], v[162:165], v[184:187], v[58:61]
	v_mfma_f32_16x16x32_bf16 v[46:49], v[148:151], v[192:195], v[46:49]
	v_mfma_f32_16x16x32_bf16 v[42:45], v[162:165], v[192:195], v[42:45]
	v_mfma_f32_16x16x32_bf16 v[30:33], v[148:151], v[200:203], v[30:33]
	v_mfma_f32_16x16x32_bf16 v[26:29], v[162:165], v[200:203], v[26:29]
	v_mfma_f32_16x16x32_bf16 v[14:17], v[148:151], v[208:211], v[14:17]
	v_mfma_f32_16x16x32_bf16 v[10:13], v[162:165], v[208:211], v[10:13]
	v_mfma_f32_16x16x32_bf16 v[62:65], v[158:161], v[188:191], v[62:65]
	v_mfma_f32_16x16x32_bf16 v[58:61], v[180:183], v[188:191], v[58:61]
	v_mfma_f32_16x16x32_bf16 v[46:49], v[158:161], v[196:199], v[46:49]
	v_mfma_f32_16x16x32_bf16 v[42:45], v[180:183], v[196:199], v[42:45]
	v_mfma_f32_16x16x32_bf16 v[30:33], v[158:161], v[204:207], v[30:33]
	v_mfma_f32_16x16x32_bf16 v[26:29], v[180:183], v[204:207], v[26:29]
	v_mfma_f32_16x16x32_bf16 v[14:17], v[158:161], v[212:215], v[14:17]
	v_mfma_f32_16x16x32_bf16 v[10:13], v[180:183], v[212:215], v[10:13]
	s_setprio 0
	s_barrier
	s_add_u32 s26, s26, 0x160080
	s_addc_u32 s27, s27, 0
	s_add_i32 s42, s48, s6
	v_lshl_add_u64 v[134:135], s[26:27], 0, v[0:1]
	s_mov_b32 m0, s42
	s_nop 0
	global_load_lds_dwordx4 v[134:135], off
	v_lshl_add_u64 v[134:135], s[26:27], 0, v[138:139]
	s_add_i32 m0, s42, 0x2000
	s_nop 0
	global_load_lds_dwordx4 v[134:135], off
	s_waitcnt vmcnt(6)
	s_barrier
	s_setprio 1
	v_mfma_f32_16x16x32_bf16 v[54:57], v[216:219], v[184:187], v[54:57]
	v_mfma_f32_16x16x32_bf16 v[50:53], v[224:227], v[184:187], v[50:53]
	v_mfma_f32_16x16x32_bf16 v[38:41], v[216:219], v[192:195], v[38:41]
	v_mfma_f32_16x16x32_bf16 v[34:37], v[224:227], v[192:195], v[34:37]
	v_mfma_f32_16x16x32_bf16 v[22:25], v[216:219], v[200:203], v[22:25]
	v_mfma_f32_16x16x32_bf16 v[18:21], v[224:227], v[200:203], v[18:21]
	v_mfma_f32_16x16x32_bf16 v[6:9], v[216:219], v[208:211], v[6:9]
	v_mfma_f32_16x16x32_bf16 v[2:5], v[224:227], v[208:211], v[2:5]
	v_mfma_f32_16x16x32_bf16 v[54:57], v[220:223], v[188:191], v[54:57]
	v_mfma_f32_16x16x32_bf16 v[50:53], v[228:231], v[188:191], v[50:53]
	v_mfma_f32_16x16x32_bf16 v[38:41], v[220:223], v[196:199], v[38:41]
	v_mfma_f32_16x16x32_bf16 v[34:37], v[228:231], v[196:199], v[34:37]
	v_mfma_f32_16x16x32_bf16 v[22:25], v[220:223], v[204:207], v[22:25]
	v_mfma_f32_16x16x32_bf16 v[18:21], v[228:231], v[204:207], v[18:21]
	v_mfma_f32_16x16x32_bf16 v[6:9], v[220:223], v[212:215], v[6:9]
	v_mfma_f32_16x16x32_bf16 v[2:5], v[228:231], v[212:215], v[2:5]
	s_setprio 0
	s_add_i32 s61, s61, 2
	s_add_u32 s59, s59, 0x100
	s_addc_u32 s60, s60, 0
	s_add_u32 s38, s38, 0x10000
	s_addc_u32 s39, s39, 0
	s_cmpk_gt_u32 s61, 0x55
	s_barrier
	s_cbranch_scc0 .LBB0_182
	v_lshl_add_u32 v152, s58, 8, v154
	v_lshl_or_b32 v150, s57, 8, v156
	v_ashrrev_i32_e32 v153, 31, v152
	v_ashrrev_i32_e32 v151, 31, v150
	v_lshlrev_b64 v[134:135], 11, v[152:153]
	v_lshl_add_u64 v[134:135], v[134:135], 0, v[150:151]
	v_lshlrev_b64 v[148:149], 2, v[134:135]
	v_lshl_add_u64 v[134:135], s[22:23], 0, v[148:149]
	v_lshl_add_u64 v[158:159], s[76:77], 0, v[148:149]
	v_readlane_b32 s62, v254, 34
	v_readlane_b32 s64, v254, 36
	v_readlane_b32 s60, v254, 39
	s_and_b64 vcc, exec, s[40:41]
	s_mov_b32 s57, s55
	s_mov_b32 s58, s56
	s_mov_b64 s[38:39], s[0:1]
	v_readlane_b32 s63, v254, 35
	v_readlane_b32 s65, v254, 37
	v_readlane_b32 s61, v254, 40
	v_mov_b64_e32 v[162:163], v[134:135]
	v_mov_b64_e32 v[152:153], v[158:159]
	global_load_dwordx4 v[180:183], v[162:163], off
	global_load_dwordx4 v[184:187], v[162:163], off offset:16
	global_load_dwordx4 v[188:191], v[162:163], off offset:512
	global_load_dwordx4 v[192:195], v[162:163], off offset:528
	s_mov_b64 s[26:27], 0x20000
	v_lshl_add_u64 v[164:165], v[134:135], 0, s[26:27]
	v_lshl_add_u64 v[160:161], v[158:159], 0, s[26:27]
	global_load_dwordx4 v[196:199], v[164:165], off
	global_load_dwordx4 v[200:203], v[164:165], off offset:16
	global_load_dwordx4 v[204:207], v[164:165], off offset:512
	global_load_dwordx4 v[208:211], v[164:165], off offset:528
	s_mov_b64 s[26:27], 0x40000
	v_lshl_add_u64 v[150:151], v[134:135], 0, s[26:27]
	v_lshl_add_u64 v[148:149], v[158:159], 0, s[26:27]
	global_load_dwordx4 v[212:215], v[150:151], off
	global_load_dwordx4 v[216:219], v[150:151], off offset:16
	global_load_dwordx4 v[220:223], v[150:151], off offset:512
	global_load_dwordx4 v[224:227], v[150:151], off offset:528
	s_waitcnt vmcnt(8)
	v_pk_fma_f32 v[126:127], v[126:127], 0.5, v[180:181] op_sel_hi:[1,0,1]
	v_pk_fma_f32 v[128:129], v[128:129], 0.5, v[182:183] op_sel_hi:[1,0,1]
	v_pk_fma_f32 v[122:123], v[122:123], 0.5, v[184:185] op_sel_hi:[1,0,1]
	v_pk_fma_f32 v[124:125], v[124:125], 0.5, v[186:187] op_sel_hi:[1,0,1]
	v_pk_fma_f32 v[118:119], v[118:119], 0.5, v[188:189] op_sel_hi:[1,0,1]
	v_pk_fma_f32 v[120:121], v[120:121], 0.5, v[190:191] op_sel_hi:[1,0,1]
	v_pk_fma_f32 v[114:115], v[114:115], 0.5, v[192:193] op_sel_hi:[1,0,1]
	v_pk_fma_f32 v[116:117], v[116:117], 0.5, v[194:195] op_sel_hi:[1,0,1]
	global_store_dwordx4 v[152:153], v[126:129], off
	global_store_dwordx4 v[152:153], v[122:125], off offset:16
	global_store_dwordx4 v[152:153], v[118:121], off offset:512
	global_store_dwordx4 v[152:153], v[114:117], off offset:528
	s_mov_b64 s[26:27], 0x60000
	v_lshl_add_u64 v[228:229], v[134:135], 0, s[26:27]
	v_lshl_add_u64 v[230:231], v[158:159], 0, s[26:27]
	global_load_dwordx4 v[180:183], v[228:229], off
	global_load_dwordx4 v[184:187], v[228:229], off offset:16
	global_load_dwordx4 v[188:191], v[228:229], off offset:512
	global_load_dwordx4 v[192:195], v[228:229], off offset:528
	s_waitcnt vmcnt(12)
	v_pk_fma_f32 v[110:111], v[110:111], 0.5, v[196:197] op_sel_hi:[1,0,1]
	v_pk_fma_f32 v[112:113], v[112:113], 0.5, v[198:199] op_sel_hi:[1,0,1]
	v_pk_fma_f32 v[106:107], v[106:107], 0.5, v[200:201] op_sel_hi:[1,0,1]
	v_pk_fma_f32 v[108:109], v[108:109], 0.5, v[202:203] op_sel_hi:[1,0,1]
	v_pk_fma_f32 v[102:103], v[102:103], 0.5, v[204:205] op_sel_hi:[1,0,1]
	v_pk_fma_f32 v[104:105], v[104:105], 0.5, v[206:207] op_sel_hi:[1,0,1]
	v_pk_fma_f32 v[98:99], v[98:99], 0.5, v[208:209] op_sel_hi:[1,0,1]
	v_pk_fma_f32 v[100:101], v[100:101], 0.5, v[210:211] op_sel_hi:[1,0,1]
	global_store_dwordx4 v[160:161], v[110:113], off
	global_store_dwordx4 v[160:161], v[106:109], off offset:16
	global_store_dwordx4 v[160:161], v[102:105], off offset:512
	global_store_dwordx4 v[160:161], v[98:101], off offset:528
	s_mov_b64 s[26:27], 0x100000
	v_lshl_add_u64 v[162:163], v[134:135], 0, s[26:27]
	v_lshl_add_u64 v[152:153], v[158:159], 0, s[26:27]
	global_load_dwordx4 v[196:199], v[162:163], off
	global_load_dwordx4 v[200:203], v[162:163], off offset:16
	global_load_dwordx4 v[204:207], v[162:163], off offset:512
	global_load_dwordx4 v[208:211], v[162:163], off offset:528
	s_waitcnt vmcnt(16)
	v_pk_fma_f32 v[94:95], v[94:95], 0.5, v[212:213] op_sel_hi:[1,0,1]
	v_pk_fma_f32 v[96:97], v[96:97], 0.5, v[214:215] op_sel_hi:[1,0,1]
	v_pk_fma_f32 v[90:91], v[90:91], 0.5, v[216:217] op_sel_hi:[1,0,1]
	v_pk_fma_f32 v[92:93], v[92:93], 0.5, v[218:219] op_sel_hi:[1,0,1]
	v_pk_fma_f32 v[86:87], v[86:87], 0.5, v[220:221] op_sel_hi:[1,0,1]
	v_pk_fma_f32 v[88:89], v[88:89], 0.5, v[222:223] op_sel_hi:[1,0,1]
	v_pk_fma_f32 v[82:83], v[82:83], 0.5, v[224:225] op_sel_hi:[1,0,1]
	v_pk_fma_f32 v[84:85], v[84:85], 0.5, v[226:227] op_sel_hi:[1,0,1]
	global_store_dwordx4 v[148:149], v[94:97], off
	global_store_dwordx4 v[148:149], v[90:93], off offset:16
	global_store_dwordx4 v[148:149], v[86:89], off offset:512
	global_store_dwordx4 v[148:149], v[82:85], off offset:528
	s_mov_b64 s[26:27], 0x120000
	v_lshl_add_u64 v[164:165], v[134:135], 0, s[26:27]
	v_lshl_add_u64 v[160:161], v[158:159], 0, s[26:27]
	global_load_dwordx4 v[212:215], v[164:165], off
	global_load_dwordx4 v[216:219], v[164:165], off offset:16
	global_load_dwordx4 v[220:223], v[164:165], off offset:512
	global_load_dwordx4 v[224:227], v[164:165], off offset:528
	s_waitcnt vmcnt(16)
	v_pk_fma_f32 v[78:79], v[78:79], 0.5, v[180:181] op_sel_hi:[1,0,1]
	v_pk_fma_f32 v[80:81], v[80:81], 0.5, v[182:183] op_sel_hi:[1,0,1]
	v_pk_fma_f32 v[74:75], v[74:75], 0.5, v[184:185] op_sel_hi:[1,0,1]
	v_pk_fma_f32 v[76:77], v[76:77], 0.5, v[186:187] op_sel_hi:[1,0,1]
	v_pk_fma_f32 v[70:71], v[70:71], 0.5, v[188:189] op_sel_hi:[1,0,1]
	v_pk_fma_f32 v[72:73], v[72:73], 0.5, v[190:191] op_sel_hi:[1,0,1]
	v_pk_fma_f32 v[66:67], v[66:67], 0.5, v[192:193] op_sel_hi:[1,0,1]
	v_pk_fma_f32 v[68:69], v[68:69], 0.5, v[194:195] op_sel_hi:[1,0,1]
	global_store_dwordx4 v[230:231], v[78:81], off
	global_store_dwordx4 v[230:231], v[74:77], off offset:16
	global_store_dwordx4 v[230:231], v[70:73], off offset:512
	global_store_dwordx4 v[230:231], v[66:69], off offset:528
	s_mov_b64 s[26:27], 0x140000
	v_lshl_add_u64 v[150:151], v[134:135], 0, s[26:27]
	v_lshl_add_u64 v[148:149], v[158:159], 0, s[26:27]
	global_load_dwordx4 v[180:183], v[150:151], off
	global_load_dwordx4 v[184:187], v[150:151], off offset:16
	global_load_dwordx4 v[188:191], v[150:151], off offset:512
	global_load_dwordx4 v[192:195], v[150:151], off offset:528
	s_waitcnt vmcnt(16)
	v_pk_fma_f32 v[62:63], v[62:63], 0.5, v[196:197] op_sel_hi:[1,0,1]
	v_pk_fma_f32 v[64:65], v[64:65], 0.5, v[198:199] op_sel_hi:[1,0,1]
	v_pk_fma_f32 v[58:59], v[58:59], 0.5, v[200:201] op_sel_hi:[1,0,1]
	v_pk_fma_f32 v[60:61], v[60:61], 0.5, v[202:203] op_sel_hi:[1,0,1]
	v_pk_fma_f32 v[54:55], v[54:55], 0.5, v[204:205] op_sel_hi:[1,0,1]
	v_pk_fma_f32 v[56:57], v[56:57], 0.5, v[206:207] op_sel_hi:[1,0,1]
	v_pk_fma_f32 v[50:51], v[50:51], 0.5, v[208:209] op_sel_hi:[1,0,1]
	v_pk_fma_f32 v[52:53], v[52:53], 0.5, v[210:211] op_sel_hi:[1,0,1]
	global_store_dwordx4 v[152:153], v[62:65], off
	global_store_dwordx4 v[152:153], v[58:61], off offset:16
	global_store_dwordx4 v[152:153], v[54:57], off offset:512
	global_store_dwordx4 v[152:153], v[50:53], off offset:528
	s_mov_b64 s[26:27], 0x160000
	v_lshl_add_u64 v[228:229], v[134:135], 0, s[26:27]
	v_lshl_add_u64 v[230:231], v[158:159], 0, s[26:27]
	global_load_dwordx4 v[196:199], v[228:229], off
	global_load_dwordx4 v[200:203], v[228:229], off offset:16
	global_load_dwordx4 v[204:207], v[228:229], off offset:512
	global_load_dwordx4 v[208:211], v[228:229], off offset:528
	s_waitcnt vmcnt(16)
	v_pk_fma_f32 v[46:47], v[46:47], 0.5, v[212:213] op_sel_hi:[1,0,1]
	v_pk_fma_f32 v[48:49], v[48:49], 0.5, v[214:215] op_sel_hi:[1,0,1]
	v_pk_fma_f32 v[42:43], v[42:43], 0.5, v[216:217] op_sel_hi:[1,0,1]
	v_pk_fma_f32 v[44:45], v[44:45], 0.5, v[218:219] op_sel_hi:[1,0,1]
	v_pk_fma_f32 v[38:39], v[38:39], 0.5, v[220:221] op_sel_hi:[1,0,1]
	v_pk_fma_f32 v[40:41], v[40:41], 0.5, v[222:223] op_sel_hi:[1,0,1]
	v_pk_fma_f32 v[34:35], v[34:35], 0.5, v[224:225] op_sel_hi:[1,0,1]
	v_pk_fma_f32 v[36:37], v[36:37], 0.5, v[226:227] op_sel_hi:[1,0,1]
	global_store_dwordx4 v[160:161], v[46:49], off
	global_store_dwordx4 v[160:161], v[42:45], off offset:16
	global_store_dwordx4 v[160:161], v[38:41], off offset:512
	global_store_dwordx4 v[160:161], v[34:37], off offset:528
	s_waitcnt vmcnt(12)
	v_pk_fma_f32 v[30:31], v[30:31], 0.5, v[180:181] op_sel_hi:[1,0,1]
	v_pk_fma_f32 v[32:33], v[32:33], 0.5, v[182:183] op_sel_hi:[1,0,1]
	v_pk_fma_f32 v[26:27], v[26:27], 0.5, v[184:185] op_sel_hi:[1,0,1]
	v_pk_fma_f32 v[28:29], v[28:29], 0.5, v[186:187] op_sel_hi:[1,0,1]
	v_pk_fma_f32 v[22:23], v[22:23], 0.5, v[188:189] op_sel_hi:[1,0,1]
	v_pk_fma_f32 v[24:25], v[24:25], 0.5, v[190:191] op_sel_hi:[1,0,1]
	v_pk_fma_f32 v[18:19], v[18:19], 0.5, v[192:193] op_sel_hi:[1,0,1]
	v_pk_fma_f32 v[20:21], v[20:21], 0.5, v[194:195] op_sel_hi:[1,0,1]
	global_store_dwordx4 v[148:149], v[30:33], off
	global_store_dwordx4 v[148:149], v[26:29], off offset:16
	global_store_dwordx4 v[148:149], v[22:25], off offset:512
	global_store_dwordx4 v[148:149], v[18:21], off offset:528
	s_waitcnt vmcnt(8)
	v_pk_fma_f32 v[14:15], v[14:15], 0.5, v[196:197] op_sel_hi:[1,0,1]
	v_pk_fma_f32 v[16:17], v[16:17], 0.5, v[198:199] op_sel_hi:[1,0,1]
	v_pk_fma_f32 v[10:11], v[10:11], 0.5, v[200:201] op_sel_hi:[1,0,1]
	v_pk_fma_f32 v[12:13], v[12:13], 0.5, v[202:203] op_sel_hi:[1,0,1]
	v_pk_fma_f32 v[6:7], v[6:7], 0.5, v[204:205] op_sel_hi:[1,0,1]
	v_pk_fma_f32 v[8:9], v[8:9], 0.5, v[206:207] op_sel_hi:[1,0,1]
	v_pk_fma_f32 v[2:3], v[2:3], 0.5, v[208:209] op_sel_hi:[1,0,1]
	v_pk_fma_f32 v[4:5], v[4:5], 0.5, v[210:211] op_sel_hi:[1,0,1]
	global_store_dwordx4 v[230:231], v[14:17], off
	global_store_dwordx4 v[230:231], v[10:13], off offset:16
	global_store_dwordx4 v[230:231], v[6:9], off offset:512
	global_store_dwordx4 v[230:231], v[2:5], off offset:528
	s_mov_b64 s[26:27], s[24:25]
	s_cbranch_vccz .LBB0_171
	s_waitcnt vmcnt(0)
	v_readlane_b32 s52, v254, 26
	v_readlane_b32 s56, v254, 30
	v_readlane_b32 s54, v254, 32
	s_cmpk_gt_u32 s4, 0xff
	v_readlane_b32 s53, v254, 27
	v_readlane_b32 s57, v254, 31
	v_readlane_b32 s55, v254, 33
	s_mov_b64 s[58:59], s[84:85]
	s_cbranch_scc1 .LBB0_186
	s_barrier

.LBB0_420:
	s_lshl_b32 s7, s4, 5
	v_add_u32_e32 v2, s7, v160
	v_mad_i64_i32 v[40:41], s[0:1], v2, s35, v[66:67]
	global_load_ushort v8, v[40:41], off
	v_add_u32_e32 v2, -1, v2
	v_mad_i64_i32 v[42:43], s[0:1], v2, s35, v[66:67]
	global_load_ushort v9, v[42:43], off
	v_add_u32_e32 v2, s7, v161
	v_mad_i64_i32 v[44:45], s[0:1], v2, s35, v[66:67]
	global_load_ushort v10, v[44:45], off
	v_add_u32_e32 v2, -1, v2
	v_mad_i64_i32 v[46:47], s[0:1], v2, s35, v[66:67]
	global_load_ushort v11, v[46:47], off
	v_add_u32_e32 v2, s7, v162
	v_mad_i64_i32 v[40:41], s[0:1], v2, s35, v[66:67]
	global_load_ushort v12, v[40:41], off
	v_add_u32_e32 v2, -1, v2
	v_mad_i64_i32 v[42:43], s[0:1], v2, s35, v[66:67]
	global_load_ushort v13, v[42:43], off
	v_add_u32_e32 v2, s7, v163
	v_mad_i64_i32 v[44:45], s[0:1], v2, s35, v[66:67]
	global_load_ushort v14, v[44:45], off
	v_add_u32_e32 v2, -1, v2
	v_mad_i64_i32 v[46:47], s[0:1], v2, s35, v[66:67]
	global_load_ushort v15, v[46:47], off
	v_add_u32_e32 v2, s7, v164
	v_mad_i64_i32 v[40:41], s[0:1], v2, s35, v[66:67]
	global_load_ushort v16, v[40:41], off
	v_add_u32_e32 v2, -1, v2
	v_mad_i64_i32 v[42:43], s[0:1], v2, s35, v[66:67]
	global_load_ushort v17, v[42:43], off
	v_add_u32_e32 v2, s7, v165
	v_mad_i64_i32 v[44:45], s[0:1], v2, s35, v[66:67]
	global_load_ushort v18, v[44:45], off
	v_add_u32_e32 v2, -1, v2
	v_mad_i64_i32 v[46:47], s[0:1], v2, s35, v[66:67]
	global_load_ushort v19, v[46:47], off
	v_add_u32_e32 v2, s7, v166
	v_mad_i64_i32 v[40:41], s[0:1], v2, s35, v[66:67]
	global_load_ushort v20, v[40:41], off
	v_add_u32_e32 v2, -1, v2
	v_mad_i64_i32 v[42:43], s[0:1], v2, s35, v[66:67]
	global_load_ushort v21, v[42:43], off
	v_add_u32_e32 v2, s7, v167
	v_mad_i64_i32 v[44:45], s[0:1], v2, s35, v[66:67]
	global_load_ushort v22, v[44:45], off
	v_add_u32_e32 v2, -1, v2
	v_mad_i64_i32 v[46:47], s[0:1], v2, s35, v[66:67]
	global_load_ushort v23, v[46:47], off
	v_add_u32_e32 v2, s7, v180
	v_mad_i64_i32 v[40:41], s[0:1], v2, s35, v[66:67]
	global_load_ushort v24, v[40:41], off
	v_add_u32_e32 v2, -1, v2
	v_mad_i64_i32 v[42:43], s[0:1], v2, s35, v[66:67]
	global_load_ushort v25, v[42:43], off
	v_add_u32_e32 v2, s7, v181
	v_mad_i64_i32 v[44:45], s[0:1], v2, s35, v[66:67]
	global_load_ushort v26, v[44:45], off
	v_add_u32_e32 v2, -1, v2
	v_mad_i64_i32 v[46:47], s[0:1], v2, s35, v[66:67]
	global_load_ushort v27, v[46:47], off
	v_add_u32_e32 v2, s7, v182
	v_mad_i64_i32 v[40:41], s[0:1], v2, s35, v[66:67]
	global_load_ushort v28, v[40:41], off
	v_add_u32_e32 v2, -1, v2
	v_mad_i64_i32 v[42:43], s[0:1], v2, s35, v[66:67]
	global_load_ushort v29, v[42:43], off
	v_add_u32_e32 v2, s7, v183
	v_mad_i64_i32 v[44:45], s[0:1], v2, s35, v[66:67]
	global_load_ushort v30, v[44:45], off
	v_add_u32_e32 v2, -1, v2
	v_mad_i64_i32 v[46:47], s[0:1], v2, s35, v[66:67]
	global_load_ushort v31, v[46:47], off
	v_add_u32_e32 v2, s7, v184
	v_mad_i64_i32 v[40:41], s[0:1], v2, s35, v[66:67]
	global_load_ushort v32, v[40:41], off
	v_add_u32_e32 v2, -1, v2
	v_mad_i64_i32 v[42:43], s[0:1], v2, s35, v[66:67]
	global_load_ushort v33, v[42:43], off
	v_add_u32_e32 v2, s7, v185
	v_mad_i64_i32 v[44:45], s[0:1], v2, s35, v[66:67]
	global_load_ushort v34, v[44:45], off
	v_add_u32_e32 v2, -1, v2
	v_mad_i64_i32 v[46:47], s[0:1], v2, s35, v[66:67]
	global_load_ushort v35, v[46:47], off
	v_add_u32_e32 v2, s7, v186
	v_mad_i64_i32 v[40:41], s[0:1], v2, s35, v[66:67]
	global_load_ushort v36, v[40:41], off
	v_add_u32_e32 v2, -1, v2
	v_mad_i64_i32 v[42:43], s[0:1], v2, s35, v[66:67]
	global_load_ushort v37, v[42:43], off
	v_add_u32_e32 v2, s7, v187
	v_mad_i64_i32 v[44:45], s[0:1], v2, s35, v[66:67]
	global_load_ushort v38, v[44:45], off
	v_add_u32_e32 v2, -1, v2
	v_mad_i64_i32 v[46:47], s[0:1], v2, s35, v[66:67]
	global_load_ushort v39, v[46:47], off
	s_waitcnt vmcnt(0)
	v_add_u32_e32 v2, s7, v160
	v_mad_i64_i32 v[6:7], s[0:1], v2, s35, v[66:67]
	flat_load_dword v4, v[68:69]
	v_mov_b32_e32 v5, v8
	v_and_b32_e32 v6, 0x3fff, v2
	v_ashrrev_i32_e32 v3, 31, v2
	v_cmp_ne_u32_e64 s[0:1], 0, v6
	v_mov_b32_e32 v6, 0
	s_and_saveexec_b64 s[22:23], s[0:1]
	s_cbranch_execz .LBB0_422
	v_add_u32_e32 v6, -1, v2
	v_mad_i64_i32 v[6:7], s[0:1], v6, s35, v[66:67]
	v_mov_b32_e32 v6, v9
	v_lshlrev_b32_e32 v6, 16, v6

.LBB0_428:
	s_or_b64 exec, exec, s[22:23]
	v_add_u32_e32 v2, s7, v161
	v_mad_i64_i32 v[6:7], s[0:1], v2, s35, v[66:67]
	v_mov_b32_e32 v5, v10
	v_and_b32_e32 v6, 0x3fff, v2
	v_ashrrev_i32_e32 v3, 31, v2
	v_cmp_ne_u32_e64 s[0:1], 0, v6
	v_mov_b32_e32 v6, 0
	s_and_saveexec_b64 s[22:23], s[0:1]
	s_cbranch_execz .LBB0_430
	v_add_u32_e32 v6, -1, v2
	v_mad_i64_i32 v[6:7], s[0:1], v6, s35, v[66:67]
	v_mov_b32_e32 v6, v11
	v_lshlrev_b32_e32 v6, 16, v6
.LBB0_430:
	s_or_b64 exec, exec, s[22:23]
	v_lshlrev_b32_e32 v5, 16, v5
	v_sub_f32_e32 v6, v6, v5
	v_fmac_f32_e32 v5, v4, v6
	s_and_saveexec_b64 s[0:1], s[52:53]
	s_xor_b64 s[0:1], exec, s[0:1]
	s_cbranch_execz .LBB0_432
	v_mul_f32_e32 v5, 0xbfb8aa3b, v5
	v_exp_f32_e32 v5, v5
	v_lshlrev_b64 v[2:3], 8, v[2:3]
	v_lshl_add_u64 v[2:3], v[70:71], 0, v[2:3]
	v_add_f32_e32 v5, 1.0, v5
	v_rcp_f32_e32 v5, v5
	s_nop 0
	v_bfe_u32 v6, v5, 16, 1
	v_add3_u32 v5, v5, v6, s30
	global_store_short_d16_hi v[2:3], v5, off offset:-256

.LBB0_436:
	s_or_b64 exec, exec, s[22:23]
	v_add_u32_e32 v2, s7, v162
	v_mad_i64_i32 v[6:7], s[0:1], v2, s35, v[66:67]
	v_mov_b32_e32 v5, v12
	v_and_b32_e32 v6, 0x3fff, v2
	v_ashrrev_i32_e32 v3, 31, v2
	v_cmp_ne_u32_e64 s[0:1], 0, v6
	v_mov_b32_e32 v6, 0
	s_and_saveexec_b64 s[22:23], s[0:1]
	s_cbranch_execz .LBB0_438
	v_add_u32_e32 v6, -1, v2
	v_mad_i64_i32 v[6:7], s[0:1], v6, s35, v[66:67]
	v_mov_b32_e32 v6, v13
	v_lshlrev_b32_e32 v6, 16, v6

.LBB0_444:
	s_or_b64 exec, exec, s[22:23]
	v_add_u32_e32 v2, s7, v163
	v_mad_i64_i32 v[6:7], s[0:1], v2, s35, v[66:67]
	v_mov_b32_e32 v5, v14
	v_and_b32_e32 v6, 0x3fff, v2
	v_ashrrev_i32_e32 v3, 31, v2
	v_cmp_ne_u32_e64 s[0:1], 0, v6
	v_mov_b32_e32 v6, 0
	s_and_saveexec_b64 s[22:23], s[0:1]
	s_cbranch_execz .LBB0_446
	v_add_u32_e32 v6, -1, v2
	v_mad_i64_i32 v[6:7], s[0:1], v6, s35, v[66:67]
	v_mov_b32_e32 v6, v15
	v_lshlrev_b32_e32 v6, 16, v6

.LBB0_452:
	s_or_b64 exec, exec, s[22:23]
	v_add_u32_e32 v2, s7, v164
	v_mad_i64_i32 v[6:7], s[0:1], v2, s35, v[66:67]
	v_mov_b32_e32 v5, v16
	v_and_b32_e32 v6, 0x3fff, v2
	v_ashrrev_i32_e32 v3, 31, v2
	v_cmp_ne_u32_e64 s[0:1], 0, v6
	v_mov_b32_e32 v6, 0
	s_and_saveexec_b64 s[22:23], s[0:1]
	s_cbranch_execz .LBB0_454
	v_add_u32_e32 v6, -1, v2
	v_mad_i64_i32 v[6:7], s[0:1], v6, s35, v[66:67]
	v_mov_b32_e32 v6, v17
	v_lshlrev_b32_e32 v6, 16, v6

.LBB0_460:
	s_or_b64 exec, exec, s[22:23]
	v_add_u32_e32 v2, s7, v165
	v_mad_i64_i32 v[6:7], s[0:1], v2, s35, v[66:67]
	v_mov_b32_e32 v5, v18
	v_and_b32_e32 v6, 0x3fff, v2
	v_ashrrev_i32_e32 v3, 31, v2
	v_cmp_ne_u32_e64 s[0:1], 0, v6
	v_mov_b32_e32 v6, 0
	s_and_saveexec_b64 s[22:23], s[0:1]
	s_cbranch_execz .LBB0_462
	v_add_u32_e32 v6, -1, v2
	v_mad_i64_i32 v[6:7], s[0:1], v6, s35, v[66:67]
	v_mov_b32_e32 v6, v19
	v_lshlrev_b32_e32 v6, 16, v6

.LBB0_468:
	s_or_b64 exec, exec, s[22:23]
	v_add_u32_e32 v2, s7, v166
	v_mad_i64_i32 v[6:7], s[0:1], v2, s35, v[66:67]
	v_mov_b32_e32 v5, v20
	v_and_b32_e32 v6, 0x3fff, v2
	v_ashrrev_i32_e32 v3, 31, v2
	v_cmp_ne_u32_e64 s[0:1], 0, v6
	v_mov_b32_e32 v6, 0
	s_and_saveexec_b64 s[22:23], s[0:1]
	s_cbranch_execz .LBB0_470
	v_add_u32_e32 v6, -1, v2
	v_mad_i64_i32 v[6:7], s[0:1], v6, s35, v[66:67]
	v_mov_b32_e32 v6, v21
	v_lshlrev_b32_e32 v6, 16, v6

.LBB0_476:
	s_or_b64 exec, exec, s[22:23]
	v_add_u32_e32 v2, s7, v167
	v_mad_i64_i32 v[6:7], s[0:1], v2, s35, v[66:67]
	v_mov_b32_e32 v5, v22
	v_and_b32_e32 v6, 0x3fff, v2
	v_ashrrev_i32_e32 v3, 31, v2
	v_cmp_ne_u32_e64 s[0:1], 0, v6
	v_mov_b32_e32 v6, 0
	s_and_saveexec_b64 s[22:23], s[0:1]
	s_cbranch_execz .LBB0_478
	v_add_u32_e32 v6, -1, v2
	v_mad_i64_i32 v[6:7], s[0:1], v6, s35, v[66:67]
	v_mov_b32_e32 v6, v23
	v_lshlrev_b32_e32 v6, 16, v6

.LBB0_484:
	s_or_b64 exec, exec, s[22:23]
	v_add_u32_e32 v2, s7, v180
	v_mad_i64_i32 v[6:7], s[0:1], v2, s35, v[66:67]
	v_mov_b32_e32 v5, v24
	v_and_b32_e32 v6, 0x3fff, v2
	v_ashrrev_i32_e32 v3, 31, v2
	v_cmp_ne_u32_e64 s[0:1], 0, v6
	v_mov_b32_e32 v6, 0
	s_and_saveexec_b64 s[22:23], s[0:1]
	s_cbranch_execz .LBB0_486
	v_add_u32_e32 v6, -1, v2
	v_mad_i64_i32 v[6:7], s[0:1], v6, s35, v[66:67]
	v_mov_b32_e32 v6, v25
	v_lshlrev_b32_e32 v6, 16, v6

.LBB0_492:
	s_or_b64 exec, exec, s[22:23]
	v_add_u32_e32 v2, s7, v181
	v_mad_i64_i32 v[6:7], s[0:1], v2, s35, v[66:67]
	v_mov_b32_e32 v5, v26
	v_and_b32_e32 v6, 0x3fff, v2
	v_ashrrev_i32_e32 v3, 31, v2
	v_cmp_ne_u32_e64 s[0:1], 0, v6
	v_mov_b32_e32 v6, 0
	s_and_saveexec_b64 s[22:23], s[0:1]
	s_cbranch_execz .LBB0_494
	v_add_u32_e32 v6, -1, v2
	v_mad_i64_i32 v[6:7], s[0:1], v6, s35, v[66:67]
	v_mov_b32_e32 v6, v27
	v_lshlrev_b32_e32 v6, 16, v6

.LBB0_500:
	s_or_b64 exec, exec, s[22:23]
	v_add_u32_e32 v2, s7, v182
	v_mad_i64_i32 v[6:7], s[0:1], v2, s35, v[66:67]
	v_mov_b32_e32 v5, v28
	v_and_b32_e32 v6, 0x3fff, v2
	v_ashrrev_i32_e32 v3, 31, v2
	v_cmp_ne_u32_e64 s[0:1], 0, v6
	v_mov_b32_e32 v6, 0
	s_and_saveexec_b64 s[22:23], s[0:1]
	s_cbranch_execz .LBB0_502
	v_add_u32_e32 v6, -1, v2
	v_mad_i64_i32 v[6:7], s[0:1], v6, s35, v[66:67]
	v_mov_b32_e32 v6, v29
	v_lshlrev_b32_e32 v6, 16, v6

.LBB0_508:
	s_or_b64 exec, exec, s[22:23]
	v_add_u32_e32 v2, s7, v183
	v_mad_i64_i32 v[6:7], s[0:1], v2, s35, v[66:67]
	v_mov_b32_e32 v5, v30
	v_and_b32_e32 v6, 0x3fff, v2
	v_ashrrev_i32_e32 v3, 31, v2
	v_cmp_ne_u32_e64 s[0:1], 0, v6
	v_mov_b32_e32 v6, 0
	s_and_saveexec_b64 s[22:23], s[0:1]
	s_cbranch_execz .LBB0_510
	v_add_u32_e32 v6, -1, v2
	v_mad_i64_i32 v[6:7], s[0:1], v6, s35, v[66:67]
	v_mov_b32_e32 v6, v31
	v_lshlrev_b32_e32 v6, 16, v6

.LBB0_516:
	s_or_b64 exec, exec, s[22:23]
	v_add_u32_e32 v2, s7, v184
	v_mad_i64_i32 v[6:7], s[0:1], v2, s35, v[66:67]
	v_mov_b32_e32 v5, v32
	v_and_b32_e32 v6, 0x3fff, v2
	v_ashrrev_i32_e32 v3, 31, v2
	v_cmp_ne_u32_e64 s[0:1], 0, v6
	v_mov_b32_e32 v6, 0
	s_and_saveexec_b64 s[22:23], s[0:1]
	s_cbranch_execz .LBB0_518
	v_add_u32_e32 v6, -1, v2
	v_mad_i64_i32 v[6:7], s[0:1], v6, s35, v[66:67]
	v_mov_b32_e32 v6, v33
	v_lshlrev_b32_e32 v6, 16, v6

.LBB0_524:
	s_or_b64 exec, exec, s[22:23]
	v_add_u32_e32 v2, s7, v185
	v_mad_i64_i32 v[6:7], s[0:1], v2, s35, v[66:67]
	v_mov_b32_e32 v5, v34
	v_and_b32_e32 v6, 0x3fff, v2
	v_ashrrev_i32_e32 v3, 31, v2
	v_cmp_ne_u32_e64 s[0:1], 0, v6
	v_mov_b32_e32 v6, 0
	s_and_saveexec_b64 s[22:23], s[0:1]
	s_cbranch_execz .LBB0_526
	v_add_u32_e32 v6, -1, v2
	v_mad_i64_i32 v[6:7], s[0:1], v6, s35, v[66:67]
	v_mov_b32_e32 v6, v35
	v_lshlrev_b32_e32 v6, 16, v6

.LBB0_532:
	s_or_b64 exec, exec, s[22:23]
	v_add_u32_e32 v2, s7, v186
	v_mad_i64_i32 v[6:7], s[0:1], v2, s35, v[66:67]
	v_mov_b32_e32 v5, v36
	v_and_b32_e32 v6, 0x3fff, v2
	v_ashrrev_i32_e32 v3, 31, v2
	v_cmp_ne_u32_e64 s[0:1], 0, v6
	v_mov_b32_e32 v6, 0
	s_and_saveexec_b64 s[22:23], s[0:1]
	s_cbranch_execz .LBB0_534
	v_add_u32_e32 v6, -1, v2
	v_mad_i64_i32 v[6:7], s[0:1], v6, s35, v[66:67]
	v_mov_b32_e32 v6, v37
	v_lshlrev_b32_e32 v6, 16, v6

.LBB0_540:
	s_or_b64 exec, exec, s[22:23]
	v_add_u32_e32 v2, s7, v187
	v_mad_i64_i32 v[6:7], s[0:1], v2, s35, v[66:67]
	v_mov_b32_e32 v5, v38
	v_and_b32_e32 v6, 0x3fff, v2
	v_ashrrev_i32_e32 v3, 31, v2
	v_cmp_ne_u32_e64 s[0:1], 0, v6
	v_mov_b32_e32 v6, 0
	s_and_saveexec_b64 s[22:23], s[0:1]
	s_cbranch_execz .LBB0_542
	v_add_u32_e32 v6, -1, v2
	v_mad_i64_i32 v[6:7], s[0:1], v6, s35, v[66:67]
	v_mov_b32_e32 v6, v39
	v_lshlrev_b32_e32 v6, 16, v6
.LBB0_542:
	s_or_b64 exec, exec, s[22:23]
	v_lshlrev_b32_e32 v5, 16, v5
	v_sub_f32_e32 v6, v6, v5
	v_fmac_f32_e32 v5, v4, v6
	s_and_saveexec_b64 s[0:1], s[52:53]
	s_xor_b64 s[0:1], exec, s[0:1]
	s_cbranch_execz .LBB0_544
	v_mul_f32_e32 v4, 0xbfb8aa3b, v5
	v_exp_f32_e32 v4, v4
	v_lshlrev_b64 v[2:3], 8, v[2:3]
	v_lshl_add_u64 v[2:3], v[70:71], 0, v[2:3]
	v_add_f32_e32 v4, 1.0, v4
	v_rcp_f32_e32 v4, v4
	s_nop 0
	v_bfe_u32 v5, v4, 16, 1
	v_add3_u32 v4, v4, v5, s30
	global_store_short_d16_hi v[2:3], v4, off offset:-256

.LBB0_806:
	v_add_u32_e32 v8, s22, v2
	v_add_u32_e32 v0, 0x7e00, v8
	v_lshlrev_b32_e32 v4, 1, v0
	global_load_ushort v9, v4, s[96:97]
	global_load_ushort v10, v4, s[74:75]
	v_add_u32_e32 v5, 0x10000, v4
	global_load_ushort v11, v5, s[96:97]
	global_load_ushort v12, v5, s[74:75]
	v_add_u32_e32 v6, 0x20000, v4
	global_load_ushort v13, v6, s[96:97]
	global_load_ushort v14, v6, s[74:75]
	v_add_u32_e32 v7, 0x30000, v4
	global_load_ushort v15, v7, s[96:97]
	global_load_ushort v16, v7, s[74:75]
	v_add_u32_e32 v0, 0x40000, v4
	global_load_ushort v17, v0, s[96:97]
	global_load_ushort v18, v0, s[74:75]
	v_add_u32_e32 v5, 0x50000, v4
	global_load_ushort v19, v5, s[96:97]
	global_load_ushort v20, v5, s[74:75]
	v_add_u32_e32 v6, 0x60000, v4
	global_load_ushort v21, v6, s[96:97]
	global_load_ushort v22, v6, s[74:75]
	v_add_u32_e32 v7, 0x70000, v4
	global_load_ushort v23, v7, s[96:97]
	global_load_ushort v24, v7, s[74:75]
	s_movk_i32 s24, 0x2000
	s_add_i32 s23, s23, 8
	s_add_i32 s22, s22, 0x40000
	s_waitcnt vmcnt(0)
	v_lshlrev_b32_e32 v9, 16, v9
	v_lshlrev_b32_e32 v10, 16, v10
	v_lshlrev_b32_e32 v11, 16, v11
	v_lshlrev_b32_e32 v12, 16, v12
	v_lshlrev_b32_e32 v13, 16, v13
	v_lshlrev_b32_e32 v14, 16, v14
	v_lshlrev_b32_e32 v15, 16, v15
	v_lshlrev_b32_e32 v16, 16, v16
	v_lshlrev_b32_e32 v17, 16, v17
	v_lshlrev_b32_e32 v18, 16, v18
	v_lshlrev_b32_e32 v19, 16, v19
	v_lshlrev_b32_e32 v20, 16, v20
	v_lshlrev_b32_e32 v21, 16, v21
	v_lshlrev_b32_e32 v22, 16, v22
	v_lshlrev_b32_e32 v23, 16, v23
	v_lshlrev_b32_e32 v24, 16, v24
	v_fmac_f32_e32 v10, v3, v9
	v_fmac_f32_e32 v12, v10, v11
	v_fmac_f32_e32 v14, v12, v13
	v_fmac_f32_e32 v16, v14, v15
	v_fmac_f32_e32 v18, v16, v17
	v_fmac_f32_e32 v20, v18, v19
	v_fmac_f32_e32 v22, v20, v21
	v_add_u32_e32 v0, s14, v2
	v_lshl_add_u64 v[4:5], v[0:1], 2, s[52:53]
	v_add_co_u32_e32 v6, vcc, s25, v4
	global_store_dword v[4:5], v3, off
	s_nop 0
	v_addc_co_u32_e32 v7, vcc, 0, v5, vcc
	v_add_co_u32_e32 v8, vcc, s24, v4
	global_store_dword v[4:5], v10, off offset:2048
	s_nop 0
	v_addc_co_u32_e32 v9, vcc, 0, v5, vcc
	v_add_co_u32_e32 v4, vcc, 0x3000, v4
	v_fmac_f32_e32 v24, v22, v23
	s_addk_i32 s14, 0x1000
	v_addc_co_u32_e32 v5, vcc, 0, v5, vcc
	s_cmpk_lt_u32 s23, 0xf8
	v_mov_b32_e32 v3, v24
	global_store_dword v[8:9], v12, off offset:-4096
	global_store_dword v[6:7], v14, off offset:2048
	global_store_dword v[8:9], v16, off
	global_store_dword v[8:9], v18, off offset:2048
	global_store_dword v[4:5], v20, off
	global_store_dword v[4:5], v22, off offset:2048
	s_cbranch_scc1 .LBB0_806
	buffer_wbl2 sc1
	s_waitcnt vmcnt(0)
	buffer_inv sc1
	s_and_b64 exec, exec, s[66:67]
	s_cbranch_execz .LBB0_810
	s_mov_b64 s[22:23], exec
	v_mbcnt_lo_u32_b32 v0, s22, 0
	v_mbcnt_hi_u32_b32 v0, s23, v0
	v_cmp_eq_u32_e32 vcc, 0, v0
	s_and_b64 s[24:25], exec, vcc
	s_mov_b64 exec, s[24:25]
	s_cbranch_execz .LBB0_810
	s_bcnt1_i32_b64 s14, s[22:23]
	v_readlane_b32 s22, v252, 31
	v_mov_b32_e32 v0, s14
	v_readlane_b32 s23, v252, 32
	s_nop 4
	global_atomic_add v1, v0, s[22:23]

.LBB0_824:
	s_add_i32 s39, s14, 1
	s_and_saveexec_b64 s[24:25], s[44:45]
	s_xor_b64 s[24:25], exec, s[24:25]
	s_cbranch_execz .LBB0_826
	s_and_b32 s26, s39, 1
	s_mul_i32 s27, s26, 0xc200
	s_add_i32 s27, s27, 0
	v_add_u32_e32 v0, s27, v41
	v_add_u32_e32 v43, s27, v51
	v_mov_b32_e32 v53, s27
	v_lshl_add_u32 v54, s26, 11, v39
	v_add_u32_e32 v55, 0x400, v54
	ds_read_b128 v[56:59], v0 offset:4096
	ds_read_b128 v[60:63], v0 offset:4352
	ds_read_b128 v[64:67], v0 offset:5632
	ds_read_b128 v[68:71], v0 offset:5888
	ds_read2st64_b32 v[104:105], v43 offset0:20 offset1:26
	ds_read_b128 v[108:111], v53 offset:53248
	ds_read_b128 v[112:115], v53 offset:53264
	ds_read_b128 v[88:91], v0 offset:4608
	ds_read_b128 v[92:95], v0 offset:4864
	ds_read_b128 v[96:99], v0 offset:6144
	ds_read_b128 v[100:103], v0 offset:6400
	s_waitcnt lgkmcnt(0)
	v_pk_mul_f32 v[124:125], v[2:3], v[56:57]
	ds_read_b128 v[72:75], v0 offset:7168
	v_pk_mul_f32 v[126:127], v[2:3], v[88:89]
	ds_read_b128 v[76:79], v0 offset:7424
	v_pk_mul_f32 v[128:129], v[2:3], v[64:65]
	ds_read_b128 v[80:83], v0 offset:8704
	v_pk_mul_f32 v[134:135], v[2:3], v[96:97]
	ds_read_b128 v[84:87], v0 offset:8960
	v_pk_fma_f32 v[124:125], v[4:5], v[58:59], v[124:125]
	ds_read2st64_b32 v[106:107], v43 offset0:32 offset1:38
	v_pk_fma_f32 v[126:127], v[4:5], v[90:91], v[126:127]
	ds_read_b128 v[116:119], v53 offset:53280
	v_pk_fma_f32 v[128:129], v[4:5], v[66:67], v[128:129]
	ds_read_b128 v[120:123], v53 offset:53296
	v_pk_fma_f32 v[134:135], v[4:5], v[98:99], v[134:135]
	v_pk_fma_f32 v[124:125], v[6:7], v[60:61], v[124:125]
	v_pk_fma_f32 v[126:127], v[6:7], v[92:93], v[126:127]
	v_pk_fma_f32 v[128:129], v[6:7], v[68:69], v[128:129]
	v_pk_fma_f32 v[134:135], v[6:7], v[100:101], v[134:135]
	v_pk_fma_f32 v[124:125], v[8:9], v[62:63], v[124:125]
	v_pk_fma_f32 v[126:127], v[8:9], v[94:95], v[126:127]
	v_pk_fma_f32 v[128:129], v[8:9], v[70:71], v[128:129]
	v_pk_fma_f32 v[134:135], v[8:9], v[102:103], v[134:135]
	v_add_f32_e32 v124, v124, v125
	v_add_f32_e32 v126, v126, v127
	v_add_f32_e32 v128, v128, v129
	v_add_f32_e32 v134, v134, v135
	v_mul_f32_e32 v142, v108, v112
	v_add_f32_dpp v125, v124, v124 row_mirror row_mask:0xf bank_mask:0xf
	v_add_f32_dpp v125, v126, v126 row_mirror row_mask:0xf bank_mask:0xc
	v_add_f32_dpp v127, v128, v128 row_mirror row_mask:0xf bank_mask:0xf
	v_add_f32_dpp v127, v134, v134 row_mirror row_mask:0xf bank_mask:0xc
	v_add_f32_dpp v129, v125, v125 row_half_mirror row_mask:0xf bank_mask:0xf
	v_pk_mul_f32 v[2:3], v[2:3], v[142:143] op_sel_hi:[1,0]
	v_pk_mul_f32 v[4:5], v[4:5], v[142:143] op_sel_hi:[1,0]
	v_add_f32_dpp v129, v127, v127 row_half_mirror row_mask:0xf bank_mask:0xa
	v_pk_mul_f32 v[6:7], v[6:7], v[142:143] op_sel_hi:[1,0]
	v_pk_mul_f32 v[8:9], v[8:9], v[142:143] op_sel_hi:[1,0]
	v_add_f32_dpp v129, v129, v129 quad_perm:[1,0,3,2] row_mask:0xf bank_mask:0xf
	ds_read_b128 v[88:91], v0 offset:7680
	ds_read_b128 v[92:95], v0 offset:7936
	v_add_f32_dpp v129, v129, v129 quad_perm:[2,3,0,1] row_mask:0xf bank_mask:0xf
	ds_read_b128 v[96:99], v0 offset:9216
	ds_read_b128 v[100:103], v0 offset:9472
	v_fmac_f32_dpp v104, -v129, v108 row_newbcast:0 row_mask:0xf bank_mask:0xf
	v_mul_f32_dpp v141, v129, v108 row_newbcast:4 row_mask:0xf bank_mask:0xf
	v_mul_f32_e32 v138, v109, v104
	v_mul_f32_dpp v139, v129, v108 row_newbcast:8 row_mask:0xf bank_mask:0xf
	v_fmac_f32_e32 v141, v111, v138
	v_mul_f32_dpp v143, v129, v108 row_newbcast:12 row_mask:0xf bank_mask:0xf
	v_fma_f32 v105, -v112, v141, v105
	v_mul_f32_e32 v144, v112, v138
	v_mul_f32_e32 v140, v113, v105
	v_fmac_f32_e32 v139, v110, v138
	v_pk_fma_f32 v[2:3], v[56:57], v[144:145], v[2:3] op_sel_hi:[1,0,1]
	v_fmac_f32_e32 v143, v115, v138
	v_pk_fma_f32 v[4:5], v[58:59], v[144:145], v[4:5] op_sel_hi:[1,0,1]
	v_pk_fma_f32 v[6:7], v[60:61], v[144:145], v[6:7] op_sel_hi:[1,0,1]
	v_pk_fma_f32 v[8:9], v[62:63], v[144:145], v[8:9] op_sel_hi:[1,0,1]
	v_pk_fma_f32 v[2:3], v[64:65], v[140:141], v[2:3] op_sel_hi:[1,0,1]
	v_pk_fma_f32 v[4:5], v[66:67], v[140:141], v[4:5] op_sel_hi:[1,0,1]
	v_pk_fma_f32 v[6:7], v[68:69], v[140:141], v[6:7] op_sel_hi:[1,0,1]
	v_pk_fma_f32 v[8:9], v[70:71], v[140:141], v[8:9] op_sel_hi:[1,0,1]
	s_waitcnt lgkmcnt(0)
	v_pk_mul_f32 v[124:125], v[2:3], v[72:73]
	v_mul_f32_e32 v143, v143, v112
	v_pk_mul_f32 v[126:127], v[2:3], v[88:89]
	v_fmac_f32_e32 v143, v114, v140
	v_pk_mul_f32 v[128:129], v[2:3], v[80:81]
	ds_write2_b32 v54, v139, v143 offset0:0 offset1:16
	v_pk_mul_f32 v[134:135], v[2:3], v[96:97]
	ds_read_b128 v[56:59], v0 offset:10240
	v_pk_fma_f32 v[124:125], v[4:5], v[74:75], v[124:125]
	ds_read_b128 v[60:63], v0 offset:10496
	v_pk_fma_f32 v[126:127], v[4:5], v[90:91], v[126:127]
	ds_read_b128 v[64:67], v0 offset:11776
	v_pk_fma_f32 v[128:129], v[4:5], v[82:83], v[128:129]
	ds_read_b128 v[68:71], v0 offset:12032
	v_pk_fma_f32 v[134:135], v[4:5], v[98:99], v[134:135]
	ds_read2st64_b32 v[104:105], v43 offset0:44 offset1:50
	v_pk_fma_f32 v[124:125], v[6:7], v[76:77], v[124:125]
	ds_read_b128 v[108:111], v53 offset:53312
	v_pk_fma_f32 v[126:127], v[6:7], v[92:93], v[126:127]
	ds_read_b128 v[112:115], v53 offset:53328
	v_pk_fma_f32 v[128:129], v[6:7], v[84:85], v[128:129]
	v_pk_fma_f32 v[134:135], v[6:7], v[100:101], v[134:135]
	v_pk_fma_f32 v[124:125], v[8:9], v[78:79], v[124:125]
	v_pk_fma_f32 v[126:127], v[8:9], v[94:95], v[126:127]
	v_pk_fma_f32 v[128:129], v[8:9], v[86:87], v[128:129]
	v_pk_fma_f32 v[134:135], v[8:9], v[102:103], v[134:135]
	v_add_f32_e32 v124, v124, v125
	v_add_f32_e32 v126, v126, v127
	v_add_f32_e32 v128, v128, v129
	v_add_f32_e32 v134, v134, v135
	v_mul_f32_e32 v142, v116, v120
	v_add_f32_dpp v125, v124, v124 row_mirror row_mask:0xf bank_mask:0xf
	v_add_f32_dpp v125, v126, v126 row_mirror row_mask:0xf bank_mask:0xc
	v_add_f32_dpp v127, v128, v128 row_mirror row_mask:0xf bank_mask:0xf
	v_add_f32_dpp v127, v134, v134 row_mirror row_mask:0xf bank_mask:0xc
	v_add_f32_dpp v129, v125, v125 row_half_mirror row_mask:0xf bank_mask:0xf
	v_pk_mul_f32 v[2:3], v[2:3], v[142:143] op_sel_hi:[1,0]
	v_pk_mul_f32 v[4:5], v[4:5], v[142:143] op_sel_hi:[1,0]
	v_add_f32_dpp v129, v127, v127 row_half_mirror row_mask:0xf bank_mask:0xa
	v_pk_mul_f32 v[6:7], v[6:7], v[142:143] op_sel_hi:[1,0]
	v_pk_mul_f32 v[8:9], v[8:9], v[142:143] op_sel_hi:[1,0]
	v_add_f32_dpp v129, v129, v129 quad_perm:[1,0,3,2] row_mask:0xf bank_mask:0xf
	ds_read_b128 v[88:91], v0 offset:10752
	ds_read_b128 v[92:95], v0 offset:11008
	v_add_f32_dpp v129, v129, v129 quad_perm:[2,3,0,1] row_mask:0xf bank_mask:0xf
	ds_read_b128 v[96:99], v0 offset:12288
	ds_read_b128 v[100:103], v0 offset:12544
	v_fmac_f32_dpp v106, -v129, v116 row_newbcast:0 row_mask:0xf bank_mask:0xf
	v_mul_f32_dpp v141, v129, v116 row_newbcast:4 row_mask:0xf bank_mask:0xf
	v_mul_f32_e32 v138, v117, v106
	v_mul_f32_dpp v139, v129, v116 row_newbcast:8 row_mask:0xf bank_mask:0xf
	v_fmac_f32_e32 v141, v119, v138
	v_mul_f32_dpp v143, v129, v116 row_newbcast:12 row_mask:0xf bank_mask:0xf
	v_fma_f32 v107, -v120, v141, v107
	v_mul_f32_e32 v144, v120, v138
	v_mul_f32_e32 v140, v121, v107
	v_fmac_f32_e32 v139, v118, v138
	v_pk_fma_f32 v[2:3], v[72:73], v[144:145], v[2:3] op_sel_hi:[1,0,1]
	v_fmac_f32_e32 v143, v123, v138
	v_pk_fma_f32 v[4:5], v[74:75], v[144:145], v[4:5] op_sel_hi:[1,0,1]
	v_pk_fma_f32 v[6:7], v[76:77], v[144:145], v[6:7] op_sel_hi:[1,0,1]
	v_pk_fma_f32 v[8:9], v[78:79], v[144:145], v[8:9] op_sel_hi:[1,0,1]
	v_pk_fma_f32 v[2:3], v[80:81], v[140:141], v[2:3] op_sel_hi:[1,0,1]
	v_pk_fma_f32 v[4:5], v[82:83], v[140:141], v[4:5] op_sel_hi:[1,0,1]
	v_pk_fma_f32 v[6:7], v[84:85], v[140:141], v[6:7] op_sel_hi:[1,0,1]
	v_pk_fma_f32 v[8:9], v[86:87], v[140:141], v[8:9] op_sel_hi:[1,0,1]
	s_waitcnt lgkmcnt(0)
	v_pk_mul_f32 v[124:125], v[2:3], v[56:57]
	v_mul_f32_e32 v143, v143, v120
	v_pk_mul_f32 v[126:127], v[2:3], v[88:89]
	v_fmac_f32_e32 v143, v122, v140
	v_pk_mul_f32 v[128:129], v[2:3], v[64:65]
	ds_write2_b32 v54, v139, v143 offset0:32 offset1:48
	v_pk_mul_f32 v[134:135], v[2:3], v[96:97]
	ds_read_b128 v[72:75], v0 offset:13312
	v_pk_fma_f32 v[124:125], v[4:5], v[58:59], v[124:125]
	ds_read_b128 v[76:79], v0 offset:13568
	v_pk_fma_f32 v[126:127], v[4:5], v[90:91], v[126:127]
	ds_read_b128 v[80:83], v0 offset:14848
	v_pk_fma_f32 v[128:129], v[4:5], v[66:67], v[128:129]
	ds_read_b128 v[84:87], v0 offset:15104
	v_pk_fma_f32 v[134:135], v[4:5], v[98:99], v[134:135]
	ds_read2st64_b32 v[106:107], v43 offset0:56 offset1:62
	v_pk_fma_f32 v[124:125], v[6:7], v[60:61], v[124:125]
	ds_read_b128 v[116:119], v53 offset:53344
	v_pk_fma_f32 v[126:127], v[6:7], v[92:93], v[126:127]
	ds_read_b128 v[120:123], v53 offset:53360
	v_pk_fma_f32 v[128:129], v[6:7], v[68:69], v[128:129]
	v_pk_fma_f32 v[134:135], v[6:7], v[100:101], v[134:135]
	v_pk_fma_f32 v[124:125], v[8:9], v[62:63], v[124:125]
	v_pk_fma_f32 v[126:127], v[8:9], v[94:95], v[126:127]
	v_pk_fma_f32 v[128:129], v[8:9], v[70:71], v[128:129]
	v_pk_fma_f32 v[134:135], v[8:9], v[102:103], v[134:135]
	v_add_f32_e32 v124, v124, v125
	v_add_f32_e32 v126, v126, v127
	v_add_f32_e32 v128, v128, v129
	v_add_f32_e32 v134, v134, v135
	v_mul_f32_e32 v142, v108, v112
	v_add_f32_dpp v125, v124, v124 row_mirror row_mask:0xf bank_mask:0xf
	v_add_f32_dpp v125, v126, v126 row_mirror row_mask:0xf bank_mask:0xc
	v_add_f32_dpp v127, v128, v128 row_mirror row_mask:0xf bank_mask:0xf
	v_add_f32_dpp v127, v134, v134 row_mirror row_mask:0xf bank_mask:0xc
	v_add_f32_dpp v129, v125, v125 row_half_mirror row_mask:0xf bank_mask:0xf
	v_pk_mul_f32 v[2:3], v[2:3], v[142:143] op_sel_hi:[1,0]
	v_pk_mul_f32 v[4:5], v[4:5], v[142:143] op_sel_hi:[1,0]
	v_add_f32_dpp v129, v127, v127 row_half_mirror row_mask:0xf bank_mask:0xa
	v_pk_mul_f32 v[6:7], v[6:7], v[142:143] op_sel_hi:[1,0]
	v_pk_mul_f32 v[8:9], v[8:9], v[142:143] op_sel_hi:[1,0]
	v_add_f32_dpp v129, v129, v129 quad_perm:[1,0,3,2] row_mask:0xf bank_mask:0xf
	ds_read_b128 v[88:91], v0 offset:13824
	ds_read_b128 v[92:95], v0 offset:14080
	v_add_f32_dpp v129, v129, v129 quad_perm:[2,3,0,1] row_mask:0xf bank_mask:0xf
	ds_read_b128 v[96:99], v0 offset:15360
	ds_read_b128 v[100:103], v0 offset:15616
	v_fmac_f32_dpp v104, -v129, v108 row_newbcast:0 row_mask:0xf bank_mask:0xf
	v_mul_f32_dpp v141, v129, v108 row_newbcast:4 row_mask:0xf bank_mask:0xf
	v_mul_f32_e32 v138, v109, v104
	v_mul_f32_dpp v139, v129, v108 row_newbcast:8 row_mask:0xf bank_mask:0xf
	v_fmac_f32_e32 v141, v111, v138
	v_mul_f32_dpp v143, v129, v108 row_newbcast:12 row_mask:0xf bank_mask:0xf
	v_fma_f32 v105, -v112, v141, v105
	v_mul_f32_e32 v144, v112, v138
	v_mul_f32_e32 v140, v113, v105
	v_fmac_f32_e32 v139, v110, v138
	v_pk_fma_f32 v[2:3], v[56:57], v[144:145], v[2:3] op_sel_hi:[1,0,1]
	v_fmac_f32_e32 v143, v115, v138
	v_pk_fma_f32 v[4:5], v[58:59], v[144:145], v[4:5] op_sel_hi:[1,0,1]
	v_pk_fma_f32 v[6:7], v[60:61], v[144:145], v[6:7] op_sel_hi:[1,0,1]
	v_pk_fma_f32 v[8:9], v[62:63], v[144:145], v[8:9] op_sel_hi:[1,0,1]
	v_pk_fma_f32 v[2:3], v[64:65], v[140:141], v[2:3] op_sel_hi:[1,0,1]
	v_pk_fma_f32 v[4:5], v[66:67], v[140:141], v[4:5] op_sel_hi:[1,0,1]
	v_pk_fma_f32 v[6:7], v[68:69], v[140:141], v[6:7] op_sel_hi:[1,0,1]
	v_pk_fma_f32 v[8:9], v[70:71], v[140:141], v[8:9] op_sel_hi:[1,0,1]
	s_waitcnt lgkmcnt(0)
	v_pk_mul_f32 v[124:125], v[2:3], v[72:73]
	v_mul_f32_e32 v143, v143, v112
	v_pk_mul_f32 v[126:127], v[2:3], v[88:89]
	v_fmac_f32_e32 v143, v114, v140
	v_pk_mul_f32 v[128:129], v[2:3], v[80:81]
	ds_write2_b32 v54, v139, v143 offset0:64 offset1:80
	v_pk_mul_f32 v[134:135], v[2:3], v[96:97]
	ds_read_b128 v[56:59], v0 offset:16384
	v_pk_fma_f32 v[124:125], v[4:5], v[74:75], v[124:125]
	ds_read_b128 v[60:63], v0 offset:16640
	v_pk_fma_f32 v[126:127], v[4:5], v[90:91], v[126:127]
	ds_read_b128 v[64:67], v0 offset:17920
	v_pk_fma_f32 v[128:129], v[4:5], v[82:83], v[128:129]
	ds_read_b128 v[68:71], v0 offset:18176
	v_pk_fma_f32 v[134:135], v[4:5], v[98:99], v[134:135]
	ds_read2st64_b32 v[104:105], v43 offset0:68 offset1:74
	v_pk_fma_f32 v[124:125], v[6:7], v[76:77], v[124:125]
	ds_read_b128 v[108:111], v53 offset:53376
	v_pk_fma_f32 v[126:127], v[6:7], v[92:93], v[126:127]
	ds_read_b128 v[112:115], v53 offset:53392
	v_pk_fma_f32 v[128:129], v[6:7], v[84:85], v[128:129]
	v_pk_fma_f32 v[134:135], v[6:7], v[100:101], v[134:135]
	v_pk_fma_f32 v[124:125], v[8:9], v[78:79], v[124:125]
	v_pk_fma_f32 v[126:127], v[8:9], v[94:95], v[126:127]
	v_pk_fma_f32 v[128:129], v[8:9], v[86:87], v[128:129]
	v_pk_fma_f32 v[134:135], v[8:9], v[102:103], v[134:135]
	v_add_f32_e32 v124, v124, v125
	v_add_f32_e32 v126, v126, v127
	v_add_f32_e32 v128, v128, v129
	v_add_f32_e32 v134, v134, v135
	v_mul_f32_e32 v142, v116, v120
	v_add_f32_dpp v125, v124, v124 row_mirror row_mask:0xf bank_mask:0xf
	v_add_f32_dpp v125, v126, v126 row_mirror row_mask:0xf bank_mask:0xc
	v_add_f32_dpp v127, v128, v128 row_mirror row_mask:0xf bank_mask:0xf
	v_add_f32_dpp v127, v134, v134 row_mirror row_mask:0xf bank_mask:0xc
	v_add_f32_dpp v129, v125, v125 row_half_mirror row_mask:0xf bank_mask:0xf
	v_pk_mul_f32 v[2:3], v[2:3], v[142:143] op_sel_hi:[1,0]
	v_pk_mul_f32 v[4:5], v[4:5], v[142:143] op_sel_hi:[1,0]
	v_add_f32_dpp v129, v127, v127 row_half_mirror row_mask:0xf bank_mask:0xa
	v_pk_mul_f32 v[6:7], v[6:7], v[142:143] op_sel_hi:[1,0]
	v_pk_mul_f32 v[8:9], v[8:9], v[142:143] op_sel_hi:[1,0]
	v_add_f32_dpp v129, v129, v129 quad_perm:[1,0,3,2] row_mask:0xf bank_mask:0xf
	ds_read_b128 v[88:91], v0 offset:16896
	ds_read_b128 v[92:95], v0 offset:17152
	v_add_f32_dpp v129, v129, v129 quad_perm:[2,3,0,1] row_mask:0xf bank_mask:0xf
	ds_read_b128 v[96:99], v0 offset:18432
	ds_read_b128 v[100:103], v0 offset:18688
	v_fmac_f32_dpp v106, -v129, v116 row_newbcast:0 row_mask:0xf bank_mask:0xf
	v_mul_f32_dpp v141, v129, v116 row_newbcast:4 row_mask:0xf bank_mask:0xf
	v_mul_f32_e32 v138, v117, v106
	v_mul_f32_dpp v139, v129, v116 row_newbcast:8 row_mask:0xf bank_mask:0xf
	v_fmac_f32_e32 v141, v119, v138
	v_mul_f32_dpp v143, v129, v116 row_newbcast:12 row_mask:0xf bank_mask:0xf
	v_fma_f32 v107, -v120, v141, v107
	v_mul_f32_e32 v144, v120, v138
	v_mul_f32_e32 v140, v121, v107
	v_fmac_f32_e32 v139, v118, v138
	v_pk_fma_f32 v[2:3], v[72:73], v[144:145], v[2:3] op_sel_hi:[1,0,1]
	v_fmac_f32_e32 v143, v123, v138
	v_pk_fma_f32 v[4:5], v[74:75], v[144:145], v[4:5] op_sel_hi:[1,0,1]
	v_pk_fma_f32 v[6:7], v[76:77], v[144:145], v[6:7] op_sel_hi:[1,0,1]
	v_pk_fma_f32 v[8:9], v[78:79], v[144:145], v[8:9] op_sel_hi:[1,0,1]
	v_pk_fma_f32 v[2:3], v[80:81], v[140:141], v[2:3] op_sel_hi:[1,0,1]
	v_pk_fma_f32 v[4:5], v[82:83], v[140:141], v[4:5] op_sel_hi:[1,0,1]
	v_pk_fma_f32 v[6:7], v[84:85], v[140:141], v[6:7] op_sel_hi:[1,0,1]
	v_pk_fma_f32 v[8:9], v[86:87], v[140:141], v[8:9] op_sel_hi:[1,0,1]
	s_waitcnt lgkmcnt(0)
	v_pk_mul_f32 v[124:125], v[2:3], v[56:57]
	v_mul_f32_e32 v143, v143, v120
	v_pk_mul_f32 v[126:127], v[2:3], v[88:89]
	v_fmac_f32_e32 v143, v122, v140
	v_pk_mul_f32 v[128:129], v[2:3], v[64:65]
	ds_write2_b32 v54, v139, v143 offset0:96 offset1:112
	v_pk_mul_f32 v[134:135], v[2:3], v[96:97]
	ds_read_b128 v[72:75], v0 offset:19456
	v_pk_fma_f32 v[124:125], v[4:5], v[58:59], v[124:125]
	ds_read_b128 v[76:79], v0 offset:19712
	v_pk_fma_f32 v[126:127], v[4:5], v[90:91], v[126:127]
	ds_read_b128 v[80:83], v0 offset:20992
	v_pk_fma_f32 v[128:129], v[4:5], v[66:67], v[128:129]
	ds_read_b128 v[84:87], v0 offset:21248
	v_pk_fma_f32 v[134:135], v[4:5], v[98:99], v[134:135]
	ds_read2st64_b32 v[106:107], v43 offset0:80 offset1:86
	v_pk_fma_f32 v[124:125], v[6:7], v[60:61], v[124:125]
	ds_read_b128 v[116:119], v53 offset:53408
	v_pk_fma_f32 v[126:127], v[6:7], v[92:93], v[126:127]
	ds_read_b128 v[120:123], v53 offset:53424
	v_pk_fma_f32 v[128:129], v[6:7], v[68:69], v[128:129]
	v_pk_fma_f32 v[134:135], v[6:7], v[100:101], v[134:135]
	v_pk_fma_f32 v[124:125], v[8:9], v[62:63], v[124:125]
	v_pk_fma_f32 v[126:127], v[8:9], v[94:95], v[126:127]
	v_pk_fma_f32 v[128:129], v[8:9], v[70:71], v[128:129]
	v_pk_fma_f32 v[134:135], v[8:9], v[102:103], v[134:135]
	v_add_f32_e32 v124, v124, v125
	v_add_f32_e32 v126, v126, v127
	v_add_f32_e32 v128, v128, v129
	v_add_f32_e32 v134, v134, v135
	v_mul_f32_e32 v142, v108, v112
	v_add_f32_dpp v125, v124, v124 row_mirror row_mask:0xf bank_mask:0xf
	v_add_f32_dpp v125, v126, v126 row_mirror row_mask:0xf bank_mask:0xc
	v_add_f32_dpp v127, v128, v128 row_mirror row_mask:0xf bank_mask:0xf
	v_add_f32_dpp v127, v134, v134 row_mirror row_mask:0xf bank_mask:0xc
	v_add_f32_dpp v129, v125, v125 row_half_mirror row_mask:0xf bank_mask:0xf
	v_pk_mul_f32 v[2:3], v[2:3], v[142:143] op_sel_hi:[1,0]
	v_pk_mul_f32 v[4:5], v[4:5], v[142:143] op_sel_hi:[1,0]
	v_add_f32_dpp v129, v127, v127 row_half_mirror row_mask:0xf bank_mask:0xa
	v_pk_mul_f32 v[6:7], v[6:7], v[142:143] op_sel_hi:[1,0]
	v_pk_mul_f32 v[8:9], v[8:9], v[142:143] op_sel_hi:[1,0]
	v_add_f32_dpp v129, v129, v129 quad_perm:[1,0,3,2] row_mask:0xf bank_mask:0xf
	ds_read_b128 v[88:91], v0 offset:19968
	ds_read_b128 v[92:95], v0 offset:20224
	v_add_f32_dpp v129, v129, v129 quad_perm:[2,3,0,1] row_mask:0xf bank_mask:0xf
	ds_read_b128 v[96:99], v0 offset:21504
	ds_read_b128 v[100:103], v0 offset:21760
	v_fmac_f32_dpp v104, -v129, v108 row_newbcast:0 row_mask:0xf bank_mask:0xf
	v_mul_f32_dpp v141, v129, v108 row_newbcast:4 row_mask:0xf bank_mask:0xf
	v_mul_f32_e32 v138, v109, v104
	v_mul_f32_dpp v139, v129, v108 row_newbcast:8 row_mask:0xf bank_mask:0xf
	v_fmac_f32_e32 v141, v111, v138
	v_mul_f32_dpp v143, v129, v108 row_newbcast:12 row_mask:0xf bank_mask:0xf
	v_fma_f32 v105, -v112, v141, v105
	v_mul_f32_e32 v144, v112, v138
	v_mul_f32_e32 v140, v113, v105
	v_fmac_f32_e32 v139, v110, v138
	v_pk_fma_f32 v[2:3], v[56:57], v[144:145], v[2:3] op_sel_hi:[1,0,1]
	v_fmac_f32_e32 v143, v115, v138
	v_pk_fma_f32 v[4:5], v[58:59], v[144:145], v[4:5] op_sel_hi:[1,0,1]
	v_pk_fma_f32 v[6:7], v[60:61], v[144:145], v[6:7] op_sel_hi:[1,0,1]
	v_pk_fma_f32 v[8:9], v[62:63], v[144:145], v[8:9] op_sel_hi:[1,0,1]
	v_pk_fma_f32 v[2:3], v[64:65], v[140:141], v[2:3] op_sel_hi:[1,0,1]
	v_pk_fma_f32 v[4:5], v[66:67], v[140:141], v[4:5] op_sel_hi:[1,0,1]
	v_pk_fma_f32 v[6:7], v[68:69], v[140:141], v[6:7] op_sel_hi:[1,0,1]
	v_pk_fma_f32 v[8:9], v[70:71], v[140:141], v[8:9] op_sel_hi:[1,0,1]
	s_waitcnt lgkmcnt(0)
	v_pk_mul_f32 v[124:125], v[2:3], v[72:73]
	v_mul_f32_e32 v143, v143, v112
	v_pk_mul_f32 v[126:127], v[2:3], v[88:89]
	v_fmac_f32_e32 v143, v114, v140
	v_pk_mul_f32 v[128:129], v[2:3], v[80:81]
	ds_write2_b32 v54, v139, v143 offset0:128 offset1:144
	v_pk_mul_f32 v[134:135], v[2:3], v[96:97]
	ds_read_b128 v[56:59], v0 offset:22528
	v_pk_fma_f32 v[124:125], v[4:5], v[74:75], v[124:125]
	ds_read_b128 v[60:63], v0 offset:22784
	v_pk_fma_f32 v[126:127], v[4:5], v[90:91], v[126:127]
	ds_read_b128 v[64:67], v0 offset:24064
	v_pk_fma_f32 v[128:129], v[4:5], v[82:83], v[128:129]
	ds_read_b128 v[68:71], v0 offset:24320
	v_pk_fma_f32 v[134:135], v[4:5], v[98:99], v[134:135]
	ds_read2st64_b32 v[104:105], v43 offset0:92 offset1:98
	v_pk_fma_f32 v[124:125], v[6:7], v[76:77], v[124:125]
	ds_read_b128 v[108:111], v53 offset:53440
	v_pk_fma_f32 v[126:127], v[6:7], v[92:93], v[126:127]
	ds_read_b128 v[112:115], v53 offset:53456
	v_pk_fma_f32 v[128:129], v[6:7], v[84:85], v[128:129]
	v_pk_fma_f32 v[134:135], v[6:7], v[100:101], v[134:135]
	v_pk_fma_f32 v[124:125], v[8:9], v[78:79], v[124:125]
	v_pk_fma_f32 v[126:127], v[8:9], v[94:95], v[126:127]
	v_pk_fma_f32 v[128:129], v[8:9], v[86:87], v[128:129]
	v_pk_fma_f32 v[134:135], v[8:9], v[102:103], v[134:135]
	v_add_f32_e32 v124, v124, v125
	v_add_f32_e32 v126, v126, v127
	v_add_f32_e32 v128, v128, v129
	v_add_f32_e32 v134, v134, v135
	v_mul_f32_e32 v142, v116, v120
	v_add_f32_dpp v125, v124, v124 row_mirror row_mask:0xf bank_mask:0xf
	v_add_f32_dpp v125, v126, v126 row_mirror row_mask:0xf bank_mask:0xc
	v_add_f32_dpp v127, v128, v128 row_mirror row_mask:0xf bank_mask:0xf
	v_add_f32_dpp v127, v134, v134 row_mirror row_mask:0xf bank_mask:0xc
	v_add_f32_dpp v129, v125, v125 row_half_mirror row_mask:0xf bank_mask:0xf
	v_pk_mul_f32 v[2:3], v[2:3], v[142:143] op_sel_hi:[1,0]
	v_pk_mul_f32 v[4:5], v[4:5], v[142:143] op_sel_hi:[1,0]
	v_add_f32_dpp v129, v127, v127 row_half_mirror row_mask:0xf bank_mask:0xa
	v_pk_mul_f32 v[6:7], v[6:7], v[142:143] op_sel_hi:[1,0]
	v_pk_mul_f32 v[8:9], v[8:9], v[142:143] op_sel_hi:[1,0]
	v_add_f32_dpp v129, v129, v129 quad_perm:[1,0,3,2] row_mask:0xf bank_mask:0xf
	ds_read_b128 v[88:91], v0 offset:23040
	ds_read_b128 v[92:95], v0 offset:23296
	v_add_f32_dpp v129, v129, v129 quad_perm:[2,3,0,1] row_mask:0xf bank_mask:0xf
	ds_read_b128 v[96:99], v0 offset:24576
	ds_read_b128 v[100:103], v0 offset:24832
	v_fmac_f32_dpp v106, -v129, v116 row_newbcast:0 row_mask:0xf bank_mask:0xf
	v_mul_f32_dpp v141, v129, v116 row_newbcast:4 row_mask:0xf bank_mask:0xf
	v_mul_f32_e32 v138, v117, v106
	v_mul_f32_dpp v139, v129, v116 row_newbcast:8 row_mask:0xf bank_mask:0xf
	v_fmac_f32_e32 v141, v119, v138
	v_mul_f32_dpp v143, v129, v116 row_newbcast:12 row_mask:0xf bank_mask:0xf
	v_fma_f32 v107, -v120, v141, v107
	v_mul_f32_e32 v144, v120, v138
	v_mul_f32_e32 v140, v121, v107
	v_fmac_f32_e32 v139, v118, v138
	v_pk_fma_f32 v[2:3], v[72:73], v[144:145], v[2:3] op_sel_hi:[1,0,1]
	v_fmac_f32_e32 v143, v123, v138
	v_pk_fma_f32 v[4:5], v[74:75], v[144:145], v[4:5] op_sel_hi:[1,0,1]
	v_pk_fma_f32 v[6:7], v[76:77], v[144:145], v[6:7] op_sel_hi:[1,0,1]
	v_pk_fma_f32 v[8:9], v[78:79], v[144:145], v[8:9] op_sel_hi:[1,0,1]
	v_pk_fma_f32 v[2:3], v[80:81], v[140:141], v[2:3] op_sel_hi:[1,0,1]
	v_pk_fma_f32 v[4:5], v[82:83], v[140:141], v[4:5] op_sel_hi:[1,0,1]
	v_pk_fma_f32 v[6:7], v[84:85], v[140:141], v[6:7] op_sel_hi:[1,0,1]
	v_pk_fma_f32 v[8:9], v[86:87], v[140:141], v[8:9] op_sel_hi:[1,0,1]
	s_waitcnt lgkmcnt(0)
	v_pk_mul_f32 v[124:125], v[2:3], v[56:57]
	v_mul_f32_e32 v143, v143, v120
	v_pk_mul_f32 v[126:127], v[2:3], v[88:89]
	v_fmac_f32_e32 v143, v122, v140
	v_pk_mul_f32 v[128:129], v[2:3], v[64:65]
	ds_write2_b32 v54, v139, v143 offset0:160 offset1:176
	v_pk_mul_f32 v[134:135], v[2:3], v[96:97]
	ds_read_b128 v[72:75], v0 offset:25600
	v_pk_fma_f32 v[124:125], v[4:5], v[58:59], v[124:125]
	ds_read_b128 v[76:79], v0 offset:25856
	v_pk_fma_f32 v[126:127], v[4:5], v[90:91], v[126:127]
	ds_read_b128 v[80:83], v0 offset:27136
	v_pk_fma_f32 v[128:129], v[4:5], v[66:67], v[128:129]
	ds_read_b128 v[84:87], v0 offset:27392
	v_pk_fma_f32 v[134:135], v[4:5], v[98:99], v[134:135]
	ds_read2st64_b32 v[106:107], v43 offset0:104 offset1:110
	v_pk_fma_f32 v[124:125], v[6:7], v[60:61], v[124:125]
	ds_read_b128 v[116:119], v53 offset:53472
	v_pk_fma_f32 v[126:127], v[6:7], v[92:93], v[126:127]
	ds_read_b128 v[120:123], v53 offset:53488
	v_pk_fma_f32 v[128:129], v[6:7], v[68:69], v[128:129]
	v_pk_fma_f32 v[134:135], v[6:7], v[100:101], v[134:135]
	v_pk_fma_f32 v[124:125], v[8:9], v[62:63], v[124:125]
	v_pk_fma_f32 v[126:127], v[8:9], v[94:95], v[126:127]
	v_pk_fma_f32 v[128:129], v[8:9], v[70:71], v[128:129]
	v_pk_fma_f32 v[134:135], v[8:9], v[102:103], v[134:135]
	v_add_f32_e32 v124, v124, v125
	v_add_f32_e32 v126, v126, v127
	v_add_f32_e32 v128, v128, v129
	v_add_f32_e32 v134, v134, v135
	v_mul_f32_e32 v142, v108, v112
	v_add_f32_dpp v125, v124, v124 row_mirror row_mask:0xf bank_mask:0xf
	v_add_f32_dpp v125, v126, v126 row_mirror row_mask:0xf bank_mask:0xc
	v_add_f32_dpp v127, v128, v128 row_mirror row_mask:0xf bank_mask:0xf
	v_add_f32_dpp v127, v134, v134 row_mirror row_mask:0xf bank_mask:0xc
	v_add_f32_dpp v129, v125, v125 row_half_mirror row_mask:0xf bank_mask:0xf
	v_pk_mul_f32 v[2:3], v[2:3], v[142:143] op_sel_hi:[1,0]
	v_pk_mul_f32 v[4:5], v[4:5], v[142:143] op_sel_hi:[1,0]
	v_add_f32_dpp v129, v127, v127 row_half_mirror row_mask:0xf bank_mask:0xa
	v_pk_mul_f32 v[6:7], v[6:7], v[142:143] op_sel_hi:[1,0]
	v_pk_mul_f32 v[8:9], v[8:9], v[142:143] op_sel_hi:[1,0]
	v_add_f32_dpp v129, v129, v129 quad_perm:[1,0,3,2] row_mask:0xf bank_mask:0xf
	ds_read_b128 v[88:91], v0 offset:26112
	ds_read_b128 v[92:95], v0 offset:26368
	v_add_f32_dpp v129, v129, v129 quad_perm:[2,3,0,1] row_mask:0xf bank_mask:0xf
	ds_read_b128 v[96:99], v0 offset:27648
	ds_read_b128 v[100:103], v0 offset:27904
	v_fmac_f32_dpp v104, -v129, v108 row_newbcast:0 row_mask:0xf bank_mask:0xf
	v_mul_f32_dpp v141, v129, v108 row_newbcast:4 row_mask:0xf bank_mask:0xf
	v_mul_f32_e32 v138, v109, v104
	v_mul_f32_dpp v139, v129, v108 row_newbcast:8 row_mask:0xf bank_mask:0xf
	v_fmac_f32_e32 v141, v111, v138
	v_mul_f32_dpp v143, v129, v108 row_newbcast:12 row_mask:0xf bank_mask:0xf
	v_fma_f32 v105, -v112, v141, v105
	v_mul_f32_e32 v144, v112, v138
	v_mul_f32_e32 v140, v113, v105
	v_fmac_f32_e32 v139, v110, v138
	v_pk_fma_f32 v[2:3], v[56:57], v[144:145], v[2:3] op_sel_hi:[1,0,1]
	v_fmac_f32_e32 v143, v115, v138
	v_pk_fma_f32 v[4:5], v[58:59], v[144:145], v[4:5] op_sel_hi:[1,0,1]
	v_pk_fma_f32 v[6:7], v[60:61], v[144:145], v[6:7] op_sel_hi:[1,0,1]
	v_pk_fma_f32 v[8:9], v[62:63], v[144:145], v[8:9] op_sel_hi:[1,0,1]
	v_pk_fma_f32 v[2:3], v[64:65], v[140:141], v[2:3] op_sel_hi:[1,0,1]
	v_pk_fma_f32 v[4:5], v[66:67], v[140:141], v[4:5] op_sel_hi:[1,0,1]
	v_pk_fma_f32 v[6:7], v[68:69], v[140:141], v[6:7] op_sel_hi:[1,0,1]
	v_pk_fma_f32 v[8:9], v[70:71], v[140:141], v[8:9] op_sel_hi:[1,0,1]
	s_waitcnt lgkmcnt(0)
	v_pk_mul_f32 v[124:125], v[2:3], v[72:73]
	v_mul_f32_e32 v143, v143, v112
	v_pk_mul_f32 v[126:127], v[2:3], v[88:89]
	v_fmac_f32_e32 v143, v114, v140
	v_pk_mul_f32 v[128:129], v[2:3], v[80:81]
	ds_write2_b32 v54, v139, v143 offset0:192 offset1:208
	v_pk_mul_f32 v[134:135], v[2:3], v[96:97]
	ds_read_b128 v[56:59], v0 offset:28672
	v_pk_fma_f32 v[124:125], v[4:5], v[74:75], v[124:125]
	ds_read_b128 v[60:63], v0 offset:28928
	v_pk_fma_f32 v[126:127], v[4:5], v[90:91], v[126:127]
	ds_read_b128 v[64:67], v0 offset:30208
	v_pk_fma_f32 v[128:129], v[4:5], v[82:83], v[128:129]
	ds_read_b128 v[68:71], v0 offset:30464
	v_pk_fma_f32 v[134:135], v[4:5], v[98:99], v[134:135]
	ds_read2st64_b32 v[104:105], v43 offset0:116 offset1:122
	v_pk_fma_f32 v[124:125], v[6:7], v[76:77], v[124:125]
	ds_read_b128 v[108:111], v53 offset:53504
	v_pk_fma_f32 v[126:127], v[6:7], v[92:93], v[126:127]
	ds_read_b128 v[112:115], v53 offset:53520
	v_pk_fma_f32 v[128:129], v[6:7], v[84:85], v[128:129]
	v_pk_fma_f32 v[134:135], v[6:7], v[100:101], v[134:135]
	v_pk_fma_f32 v[124:125], v[8:9], v[78:79], v[124:125]
	v_pk_fma_f32 v[126:127], v[8:9], v[94:95], v[126:127]
	v_pk_fma_f32 v[128:129], v[8:9], v[86:87], v[128:129]
	v_pk_fma_f32 v[134:135], v[8:9], v[102:103], v[134:135]
	v_add_f32_e32 v124, v124, v125
	v_add_f32_e32 v126, v126, v127
	v_add_f32_e32 v128, v128, v129
	v_add_f32_e32 v134, v134, v135
	v_mul_f32_e32 v142, v116, v120
	v_add_f32_dpp v125, v124, v124 row_mirror row_mask:0xf bank_mask:0xf
	v_add_f32_dpp v125, v126, v126 row_mirror row_mask:0xf bank_mask:0xc
	v_add_f32_dpp v127, v128, v128 row_mirror row_mask:0xf bank_mask:0xf
	v_add_f32_dpp v127, v134, v134 row_mirror row_mask:0xf bank_mask:0xc
	v_add_f32_dpp v129, v125, v125 row_half_mirror row_mask:0xf bank_mask:0xf
	v_pk_mul_f32 v[2:3], v[2:3], v[142:143] op_sel_hi:[1,0]
	v_pk_mul_f32 v[4:5], v[4:5], v[142:143] op_sel_hi:[1,0]
	v_add_f32_dpp v129, v127, v127 row_half_mirror row_mask:0xf bank_mask:0xa
	v_pk_mul_f32 v[6:7], v[6:7], v[142:143] op_sel_hi:[1,0]
	v_pk_mul_f32 v[8:9], v[8:9], v[142:143] op_sel_hi:[1,0]
	v_add_f32_dpp v129, v129, v129 quad_perm:[1,0,3,2] row_mask:0xf bank_mask:0xf
	ds_read_b128 v[88:91], v0 offset:29184
	ds_read_b128 v[92:95], v0 offset:29440
	v_add_f32_dpp v129, v129, v129 quad_perm:[2,3,0,1] row_mask:0xf bank_mask:0xf
	ds_read_b128 v[96:99], v0 offset:30720
	ds_read_b128 v[100:103], v0 offset:30976
	v_fmac_f32_dpp v106, -v129, v116 row_newbcast:0 row_mask:0xf bank_mask:0xf
	v_mul_f32_dpp v141, v129, v116 row_newbcast:4 row_mask:0xf bank_mask:0xf
	v_mul_f32_e32 v138, v117, v106
	v_mul_f32_dpp v139, v129, v116 row_newbcast:8 row_mask:0xf bank_mask:0xf
	v_fmac_f32_e32 v141, v119, v138
	v_mul_f32_dpp v143, v129, v116 row_newbcast:12 row_mask:0xf bank_mask:0xf
	v_fma_f32 v107, -v120, v141, v107
	v_mul_f32_e32 v144, v120, v138
	v_mul_f32_e32 v140, v121, v107
	v_fmac_f32_e32 v139, v118, v138
	v_pk_fma_f32 v[2:3], v[72:73], v[144:145], v[2:3] op_sel_hi:[1,0,1]
	v_fmac_f32_e32 v143, v123, v138
	v_pk_fma_f32 v[4:5], v[74:75], v[144:145], v[4:5] op_sel_hi:[1,0,1]
	v_pk_fma_f32 v[6:7], v[76:77], v[144:145], v[6:7] op_sel_hi:[1,0,1]
	v_pk_fma_f32 v[8:9], v[78:79], v[144:145], v[8:9] op_sel_hi:[1,0,1]
	v_pk_fma_f32 v[2:3], v[80:81], v[140:141], v[2:3] op_sel_hi:[1,0,1]
	v_pk_fma_f32 v[4:5], v[82:83], v[140:141], v[4:5] op_sel_hi:[1,0,1]
	v_pk_fma_f32 v[6:7], v[84:85], v[140:141], v[6:7] op_sel_hi:[1,0,1]
	v_pk_fma_f32 v[8:9], v[86:87], v[140:141], v[8:9] op_sel_hi:[1,0,1]
	s_waitcnt lgkmcnt(0)
	v_pk_mul_f32 v[124:125], v[2:3], v[56:57]
	v_mul_f32_e32 v143, v143, v120
	v_pk_mul_f32 v[126:127], v[2:3], v[88:89]
	v_fmac_f32_e32 v143, v122, v140
	v_pk_mul_f32 v[128:129], v[2:3], v[64:65]
	ds_write2_b32 v54, v139, v143 offset0:224 offset1:240
	v_pk_mul_f32 v[134:135], v[2:3], v[96:97]
	ds_read_b128 v[72:75], v0 offset:31744
	v_pk_fma_f32 v[124:125], v[4:5], v[58:59], v[124:125]
	ds_read_b128 v[76:79], v0 offset:32000
	v_pk_fma_f32 v[126:127], v[4:5], v[90:91], v[126:127]
	ds_read_b128 v[80:83], v0 offset:33280
	v_pk_fma_f32 v[128:129], v[4:5], v[66:67], v[128:129]
	ds_read_b128 v[84:87], v0 offset:33536
	v_pk_fma_f32 v[134:135], v[4:5], v[98:99], v[134:135]
	ds_read2st64_b32 v[106:107], v43 offset0:128 offset1:134
	v_pk_fma_f32 v[124:125], v[6:7], v[60:61], v[124:125]
	ds_read_b128 v[116:119], v53 offset:53536
	v_pk_fma_f32 v[126:127], v[6:7], v[92:93], v[126:127]
	ds_read_b128 v[120:123], v53 offset:53552
	v_pk_fma_f32 v[128:129], v[6:7], v[68:69], v[128:129]
	v_pk_fma_f32 v[134:135], v[6:7], v[100:101], v[134:135]
	v_pk_fma_f32 v[124:125], v[8:9], v[62:63], v[124:125]
	v_pk_fma_f32 v[126:127], v[8:9], v[94:95], v[126:127]
	v_pk_fma_f32 v[128:129], v[8:9], v[70:71], v[128:129]
	v_pk_fma_f32 v[134:135], v[8:9], v[102:103], v[134:135]
	v_add_f32_e32 v124, v124, v125
	v_add_f32_e32 v126, v126, v127
	v_add_f32_e32 v128, v128, v129
	v_add_f32_e32 v134, v134, v135
	v_mul_f32_e32 v142, v108, v112
	v_add_f32_dpp v125, v124, v124 row_mirror row_mask:0xf bank_mask:0xf
	v_add_f32_dpp v125, v126, v126 row_mirror row_mask:0xf bank_mask:0xc
	v_add_f32_dpp v127, v128, v128 row_mirror row_mask:0xf bank_mask:0xf
	v_add_f32_dpp v127, v134, v134 row_mirror row_mask:0xf bank_mask:0xc
	v_add_f32_dpp v129, v125, v125 row_half_mirror row_mask:0xf bank_mask:0xf
	v_pk_mul_f32 v[2:3], v[2:3], v[142:143] op_sel_hi:[1,0]
	v_pk_mul_f32 v[4:5], v[4:5], v[142:143] op_sel_hi:[1,0]
	v_add_f32_dpp v129, v127, v127 row_half_mirror row_mask:0xf bank_mask:0xa
	v_pk_mul_f32 v[6:7], v[6:7], v[142:143] op_sel_hi:[1,0]
	v_pk_mul_f32 v[8:9], v[8:9], v[142:143] op_sel_hi:[1,0]
	v_add_f32_dpp v129, v129, v129 quad_perm:[1,0,3,2] row_mask:0xf bank_mask:0xf
	ds_read_b128 v[88:91], v0 offset:32256
	ds_read_b128 v[92:95], v0 offset:32512
	v_add_f32_dpp v129, v129, v129 quad_perm:[2,3,0,1] row_mask:0xf bank_mask:0xf
	ds_read_b128 v[96:99], v0 offset:33792
	ds_read_b128 v[100:103], v0 offset:34048
	v_fmac_f32_dpp v104, -v129, v108 row_newbcast:0 row_mask:0xf bank_mask:0xf
	v_mul_f32_dpp v141, v129, v108 row_newbcast:4 row_mask:0xf bank_mask:0xf
	v_mul_f32_e32 v138, v109, v104
	v_mul_f32_dpp v139, v129, v108 row_newbcast:8 row_mask:0xf bank_mask:0xf
	v_fmac_f32_e32 v141, v111, v138
	v_mul_f32_dpp v143, v129, v108 row_newbcast:12 row_mask:0xf bank_mask:0xf
	v_fma_f32 v105, -v112, v141, v105
	v_mul_f32_e32 v144, v112, v138
	v_mul_f32_e32 v140, v113, v105
	v_fmac_f32_e32 v139, v110, v138
	v_pk_fma_f32 v[2:3], v[56:57], v[144:145], v[2:3] op_sel_hi:[1,0,1]
	v_fmac_f32_e32 v143, v115, v138
	v_pk_fma_f32 v[4:5], v[58:59], v[144:145], v[4:5] op_sel_hi:[1,0,1]
	v_pk_fma_f32 v[6:7], v[60:61], v[144:145], v[6:7] op_sel_hi:[1,0,1]
	v_pk_fma_f32 v[8:9], v[62:63], v[144:145], v[8:9] op_sel_hi:[1,0,1]
	v_pk_fma_f32 v[2:3], v[64:65], v[140:141], v[2:3] op_sel_hi:[1,0,1]
	v_pk_fma_f32 v[4:5], v[66:67], v[140:141], v[4:5] op_sel_hi:[1,0,1]
	v_pk_fma_f32 v[6:7], v[68:69], v[140:141], v[6:7] op_sel_hi:[1,0,1]
	v_pk_fma_f32 v[8:9], v[70:71], v[140:141], v[8:9] op_sel_hi:[1,0,1]
	s_waitcnt lgkmcnt(0)
	v_pk_mul_f32 v[124:125], v[2:3], v[72:73]
	v_mul_f32_e32 v143, v143, v112
	v_pk_mul_f32 v[126:127], v[2:3], v[88:89]
	v_fmac_f32_e32 v143, v114, v140
	v_pk_mul_f32 v[128:129], v[2:3], v[80:81]
	ds_write2_b32 v55, v139, v143 offset0:0 offset1:16
	v_pk_mul_f32 v[134:135], v[2:3], v[96:97]
	ds_read_b128 v[56:59], v0 offset:34816
	v_pk_fma_f32 v[124:125], v[4:5], v[74:75], v[124:125]
	ds_read_b128 v[60:63], v0 offset:35072
	v_pk_fma_f32 v[126:127], v[4:5], v[90:91], v[126:127]
	ds_read_b128 v[64:67], v0 offset:36352
	v_pk_fma_f32 v[128:129], v[4:5], v[82:83], v[128:129]
	ds_read_b128 v[68:71], v0 offset:36608
	v_pk_fma_f32 v[134:135], v[4:5], v[98:99], v[134:135]
	ds_read2st64_b32 v[104:105], v43 offset0:140 offset1:146
	v_pk_fma_f32 v[124:125], v[6:7], v[76:77], v[124:125]
	ds_read_b128 v[108:111], v53 offset:53568
	v_pk_fma_f32 v[126:127], v[6:7], v[92:93], v[126:127]
	ds_read_b128 v[112:115], v53 offset:53584
	v_pk_fma_f32 v[128:129], v[6:7], v[84:85], v[128:129]
	v_pk_fma_f32 v[134:135], v[6:7], v[100:101], v[134:135]
	v_pk_fma_f32 v[124:125], v[8:9], v[78:79], v[124:125]
	v_pk_fma_f32 v[126:127], v[8:9], v[94:95], v[126:127]
	v_pk_fma_f32 v[128:129], v[8:9], v[86:87], v[128:129]
	v_pk_fma_f32 v[134:135], v[8:9], v[102:103], v[134:135]
	v_add_f32_e32 v124, v124, v125
	v_add_f32_e32 v126, v126, v127
	v_add_f32_e32 v128, v128, v129
	v_add_f32_e32 v134, v134, v135
	v_mul_f32_e32 v142, v116, v120
	v_add_f32_dpp v125, v124, v124 row_mirror row_mask:0xf bank_mask:0xf
	v_add_f32_dpp v125, v126, v126 row_mirror row_mask:0xf bank_mask:0xc
	v_add_f32_dpp v127, v128, v128 row_mirror row_mask:0xf bank_mask:0xf
	v_add_f32_dpp v127, v134, v134 row_mirror row_mask:0xf bank_mask:0xc
	v_add_f32_dpp v129, v125, v125 row_half_mirror row_mask:0xf bank_mask:0xf
	v_pk_mul_f32 v[2:3], v[2:3], v[142:143] op_sel_hi:[1,0]
	v_pk_mul_f32 v[4:5], v[4:5], v[142:143] op_sel_hi:[1,0]
	v_add_f32_dpp v129, v127, v127 row_half_mirror row_mask:0xf bank_mask:0xa
	v_pk_mul_f32 v[6:7], v[6:7], v[142:143] op_sel_hi:[1,0]
	v_pk_mul_f32 v[8:9], v[8:9], v[142:143] op_sel_hi:[1,0]
	v_add_f32_dpp v129, v129, v129 quad_perm:[1,0,3,2] row_mask:0xf bank_mask:0xf
	ds_read_b128 v[88:91], v0 offset:35328
	ds_read_b128 v[92:95], v0 offset:35584
	v_add_f32_dpp v129, v129, v129 quad_perm:[2,3,0,1] row_mask:0xf bank_mask:0xf
	ds_read_b128 v[96:99], v0 offset:36864
	ds_read_b128 v[100:103], v0 offset:37120
	v_fmac_f32_dpp v106, -v129, v116 row_newbcast:0 row_mask:0xf bank_mask:0xf
	v_mul_f32_dpp v141, v129, v116 row_newbcast:4 row_mask:0xf bank_mask:0xf
	v_mul_f32_e32 v138, v117, v106
	v_mul_f32_dpp v139, v129, v116 row_newbcast:8 row_mask:0xf bank_mask:0xf
	v_fmac_f32_e32 v141, v119, v138
	v_mul_f32_dpp v143, v129, v116 row_newbcast:12 row_mask:0xf bank_mask:0xf
	v_fma_f32 v107, -v120, v141, v107
	v_mul_f32_e32 v144, v120, v138
	v_mul_f32_e32 v140, v121, v107
	v_fmac_f32_e32 v139, v118, v138
	v_pk_fma_f32 v[2:3], v[72:73], v[144:145], v[2:3] op_sel_hi:[1,0,1]
	v_fmac_f32_e32 v143, v123, v138
	v_pk_fma_f32 v[4:5], v[74:75], v[144:145], v[4:5] op_sel_hi:[1,0,1]
	v_pk_fma_f32 v[6:7], v[76:77], v[144:145], v[6:7] op_sel_hi:[1,0,1]
	v_pk_fma_f32 v[8:9], v[78:79], v[144:145], v[8:9] op_sel_hi:[1,0,1]
	v_pk_fma_f32 v[2:3], v[80:81], v[140:141], v[2:3] op_sel_hi:[1,0,1]
	v_pk_fma_f32 v[4:5], v[82:83], v[140:141], v[4:5] op_sel_hi:[1,0,1]
	v_pk_fma_f32 v[6:7], v[84:85], v[140:141], v[6:7] op_sel_hi:[1,0,1]
	v_pk_fma_f32 v[8:9], v[86:87], v[140:141], v[8:9] op_sel_hi:[1,0,1]
	s_waitcnt lgkmcnt(0)
	v_pk_mul_f32 v[124:125], v[2:3], v[56:57]
	v_mul_f32_e32 v143, v143, v120
	v_pk_mul_f32 v[126:127], v[2:3], v[88:89]
	v_fmac_f32_e32 v143, v122, v140
	v_pk_mul_f32 v[128:129], v[2:3], v[64:65]
	ds_write2_b32 v55, v139, v143 offset0:32 offset1:48
	v_pk_mul_f32 v[134:135], v[2:3], v[96:97]
	ds_read_b128 v[72:75], v0 offset:37888
	v_pk_fma_f32 v[124:125], v[4:5], v[58:59], v[124:125]
	ds_read_b128 v[76:79], v0 offset:38144
	v_pk_fma_f32 v[126:127], v[4:5], v[90:91], v[126:127]
	ds_read_b128 v[80:83], v0 offset:39424
	v_pk_fma_f32 v[128:129], v[4:5], v[66:67], v[128:129]
	ds_read_b128 v[84:87], v0 offset:39680
	v_pk_fma_f32 v[134:135], v[4:5], v[98:99], v[134:135]
	ds_read2st64_b32 v[106:107], v43 offset0:152 offset1:158
	v_pk_fma_f32 v[124:125], v[6:7], v[60:61], v[124:125]
	ds_read_b128 v[116:119], v53 offset:53600
	v_pk_fma_f32 v[126:127], v[6:7], v[92:93], v[126:127]
	ds_read_b128 v[120:123], v53 offset:53616
	v_pk_fma_f32 v[128:129], v[6:7], v[68:69], v[128:129]
	v_pk_fma_f32 v[134:135], v[6:7], v[100:101], v[134:135]
	v_pk_fma_f32 v[124:125], v[8:9], v[62:63], v[124:125]
	v_pk_fma_f32 v[126:127], v[8:9], v[94:95], v[126:127]
	v_pk_fma_f32 v[128:129], v[8:9], v[70:71], v[128:129]
	v_pk_fma_f32 v[134:135], v[8:9], v[102:103], v[134:135]
	v_add_f32_e32 v124, v124, v125
	v_add_f32_e32 v126, v126, v127
	v_add_f32_e32 v128, v128, v129
	v_add_f32_e32 v134, v134, v135
	v_mul_f32_e32 v142, v108, v112
	v_add_f32_dpp v125, v124, v124 row_mirror row_mask:0xf bank_mask:0xf
	v_add_f32_dpp v125, v126, v126 row_mirror row_mask:0xf bank_mask:0xc
	v_add_f32_dpp v127, v128, v128 row_mirror row_mask:0xf bank_mask:0xf
	v_add_f32_dpp v127, v134, v134 row_mirror row_mask:0xf bank_mask:0xc
	v_add_f32_dpp v129, v125, v125 row_half_mirror row_mask:0xf bank_mask:0xf
	v_pk_mul_f32 v[2:3], v[2:3], v[142:143] op_sel_hi:[1,0]
	v_pk_mul_f32 v[4:5], v[4:5], v[142:143] op_sel_hi:[1,0]
	v_add_f32_dpp v129, v127, v127 row_half_mirror row_mask:0xf bank_mask:0xa
	v_pk_mul_f32 v[6:7], v[6:7], v[142:143] op_sel_hi:[1,0]
	v_pk_mul_f32 v[8:9], v[8:9], v[142:143] op_sel_hi:[1,0]
	v_add_f32_dpp v129, v129, v129 quad_perm:[1,0,3,2] row_mask:0xf bank_mask:0xf
	ds_read_b128 v[88:91], v0 offset:38400
	ds_read_b128 v[92:95], v0 offset:38656
	v_add_f32_dpp v129, v129, v129 quad_perm:[2,3,0,1] row_mask:0xf bank_mask:0xf
	ds_read_b128 v[96:99], v0 offset:39936
	ds_read_b128 v[100:103], v0 offset:40192
	v_fmac_f32_dpp v104, -v129, v108 row_newbcast:0 row_mask:0xf bank_mask:0xf
	v_mul_f32_dpp v141, v129, v108 row_newbcast:4 row_mask:0xf bank_mask:0xf
	v_mul_f32_e32 v138, v109, v104
	v_mul_f32_dpp v139, v129, v108 row_newbcast:8 row_mask:0xf bank_mask:0xf
	v_fmac_f32_e32 v141, v111, v138
	v_mul_f32_dpp v143, v129, v108 row_newbcast:12 row_mask:0xf bank_mask:0xf
	v_fma_f32 v105, -v112, v141, v105
	v_mul_f32_e32 v144, v112, v138
	v_mul_f32_e32 v140, v113, v105
	v_fmac_f32_e32 v139, v110, v138
	v_pk_fma_f32 v[2:3], v[56:57], v[144:145], v[2:3] op_sel_hi:[1,0,1]
	v_fmac_f32_e32 v143, v115, v138
	v_pk_fma_f32 v[4:5], v[58:59], v[144:145], v[4:5] op_sel_hi:[1,0,1]
	v_pk_fma_f32 v[6:7], v[60:61], v[144:145], v[6:7] op_sel_hi:[1,0,1]
	v_pk_fma_f32 v[8:9], v[62:63], v[144:145], v[8:9] op_sel_hi:[1,0,1]
	v_pk_fma_f32 v[2:3], v[64:65], v[140:141], v[2:3] op_sel_hi:[1,0,1]
	v_pk_fma_f32 v[4:5], v[66:67], v[140:141], v[4:5] op_sel_hi:[1,0,1]
	v_pk_fma_f32 v[6:7], v[68:69], v[140:141], v[6:7] op_sel_hi:[1,0,1]
	v_pk_fma_f32 v[8:9], v[70:71], v[140:141], v[8:9] op_sel_hi:[1,0,1]
	s_waitcnt lgkmcnt(0)
	v_pk_mul_f32 v[124:125], v[2:3], v[72:73]
	v_mul_f32_e32 v143, v143, v112
	v_pk_mul_f32 v[126:127], v[2:3], v[88:89]
	v_fmac_f32_e32 v143, v114, v140
	v_pk_mul_f32 v[128:129], v[2:3], v[80:81]
	ds_write2_b32 v55, v139, v143 offset0:64 offset1:80
	v_pk_mul_f32 v[134:135], v[2:3], v[96:97]
	ds_read_b128 v[56:59], v0 offset:40960
	v_pk_fma_f32 v[124:125], v[4:5], v[74:75], v[124:125]
	ds_read_b128 v[60:63], v0 offset:41216
	v_pk_fma_f32 v[126:127], v[4:5], v[90:91], v[126:127]
	ds_read_b128 v[64:67], v0 offset:42496
	v_pk_fma_f32 v[128:129], v[4:5], v[82:83], v[128:129]
	ds_read_b128 v[68:71], v0 offset:42752
	v_pk_fma_f32 v[134:135], v[4:5], v[98:99], v[134:135]
	ds_read2st64_b32 v[104:105], v43 offset0:164 offset1:170
	v_pk_fma_f32 v[124:125], v[6:7], v[76:77], v[124:125]
	ds_read_b128 v[108:111], v53 offset:53632
	v_pk_fma_f32 v[126:127], v[6:7], v[92:93], v[126:127]
	ds_read_b128 v[112:115], v53 offset:53648
	v_pk_fma_f32 v[128:129], v[6:7], v[84:85], v[128:129]
	v_pk_fma_f32 v[134:135], v[6:7], v[100:101], v[134:135]
	v_pk_fma_f32 v[124:125], v[8:9], v[78:79], v[124:125]
	v_pk_fma_f32 v[126:127], v[8:9], v[94:95], v[126:127]
	v_pk_fma_f32 v[128:129], v[8:9], v[86:87], v[128:129]
	v_pk_fma_f32 v[134:135], v[8:9], v[102:103], v[134:135]
	v_add_f32_e32 v124, v124, v125
	v_add_f32_e32 v126, v126, v127
	v_add_f32_e32 v128, v128, v129
	v_add_f32_e32 v134, v134, v135
	v_mul_f32_e32 v142, v116, v120
	v_add_f32_dpp v125, v124, v124 row_mirror row_mask:0xf bank_mask:0xf
	v_add_f32_dpp v125, v126, v126 row_mirror row_mask:0xf bank_mask:0xc
	v_add_f32_dpp v127, v128, v128 row_mirror row_mask:0xf bank_mask:0xf
	v_add_f32_dpp v127, v134, v134 row_mirror row_mask:0xf bank_mask:0xc
	v_add_f32_dpp v129, v125, v125 row_half_mirror row_mask:0xf bank_mask:0xf
	v_pk_mul_f32 v[2:3], v[2:3], v[142:143] op_sel_hi:[1,0]
	v_pk_mul_f32 v[4:5], v[4:5], v[142:143] op_sel_hi:[1,0]
	v_add_f32_dpp v129, v127, v127 row_half_mirror row_mask:0xf bank_mask:0xa
	v_pk_mul_f32 v[6:7], v[6:7], v[142:143] op_sel_hi:[1,0]
	v_pk_mul_f32 v[8:9], v[8:9], v[142:143] op_sel_hi:[1,0]
	v_add_f32_dpp v129, v129, v129 quad_perm:[1,0,3,2] row_mask:0xf bank_mask:0xf
	ds_read_b128 v[88:91], v0 offset:41472
	ds_read_b128 v[92:95], v0 offset:41728
	v_add_f32_dpp v129, v129, v129 quad_perm:[2,3,0,1] row_mask:0xf bank_mask:0xf
	ds_read_b128 v[96:99], v0 offset:43008
	ds_read_b128 v[100:103], v0 offset:43264
	v_fmac_f32_dpp v106, -v129, v116 row_newbcast:0 row_mask:0xf bank_mask:0xf
	v_mul_f32_dpp v141, v129, v116 row_newbcast:4 row_mask:0xf bank_mask:0xf
	v_mul_f32_e32 v138, v117, v106
	v_mul_f32_dpp v139, v129, v116 row_newbcast:8 row_mask:0xf bank_mask:0xf
	v_fmac_f32_e32 v141, v119, v138
	v_mul_f32_dpp v143, v129, v116 row_newbcast:12 row_mask:0xf bank_mask:0xf
	v_fma_f32 v107, -v120, v141, v107
	v_mul_f32_e32 v144, v120, v138
	v_mul_f32_e32 v140, v121, v107
	v_fmac_f32_e32 v139, v118, v138
	v_pk_fma_f32 v[2:3], v[72:73], v[144:145], v[2:3] op_sel_hi:[1,0,1]
	v_fmac_f32_e32 v143, v123, v138
	v_pk_fma_f32 v[4:5], v[74:75], v[144:145], v[4:5] op_sel_hi:[1,0,1]
	v_pk_fma_f32 v[6:7], v[76:77], v[144:145], v[6:7] op_sel_hi:[1,0,1]
	v_pk_fma_f32 v[8:9], v[78:79], v[144:145], v[8:9] op_sel_hi:[1,0,1]
	v_pk_fma_f32 v[2:3], v[80:81], v[140:141], v[2:3] op_sel_hi:[1,0,1]
	v_pk_fma_f32 v[4:5], v[82:83], v[140:141], v[4:5] op_sel_hi:[1,0,1]
	v_pk_fma_f32 v[6:7], v[84:85], v[140:141], v[6:7] op_sel_hi:[1,0,1]
	v_pk_fma_f32 v[8:9], v[86:87], v[140:141], v[8:9] op_sel_hi:[1,0,1]
	s_waitcnt lgkmcnt(0)
	v_pk_mul_f32 v[124:125], v[2:3], v[56:57]
	v_mul_f32_e32 v143, v143, v120
	v_pk_mul_f32 v[126:127], v[2:3], v[88:89]
	v_fmac_f32_e32 v143, v122, v140
	v_pk_mul_f32 v[128:129], v[2:3], v[64:65]
	ds_write2_b32 v55, v139, v143 offset0:96 offset1:112
	v_pk_mul_f32 v[134:135], v[2:3], v[96:97]
	ds_read_b128 v[72:75], v0 offset:44032
	v_pk_fma_f32 v[124:125], v[4:5], v[58:59], v[124:125]
	ds_read_b128 v[76:79], v0 offset:44288
	v_pk_fma_f32 v[126:127], v[4:5], v[90:91], v[126:127]
	ds_read_b128 v[80:83], v0 offset:45568
	v_pk_fma_f32 v[128:129], v[4:5], v[66:67], v[128:129]
	ds_read_b128 v[84:87], v0 offset:45824
	v_pk_fma_f32 v[134:135], v[4:5], v[98:99], v[134:135]
	ds_read2st64_b32 v[106:107], v43 offset0:176 offset1:182
	v_pk_fma_f32 v[124:125], v[6:7], v[60:61], v[124:125]
	ds_read_b128 v[116:119], v53 offset:53664
	v_pk_fma_f32 v[126:127], v[6:7], v[92:93], v[126:127]
	ds_read_b128 v[120:123], v53 offset:53680
	v_pk_fma_f32 v[128:129], v[6:7], v[68:69], v[128:129]
	v_pk_fma_f32 v[134:135], v[6:7], v[100:101], v[134:135]
	v_pk_fma_f32 v[124:125], v[8:9], v[62:63], v[124:125]
	v_pk_fma_f32 v[126:127], v[8:9], v[94:95], v[126:127]
	v_pk_fma_f32 v[128:129], v[8:9], v[70:71], v[128:129]
	v_pk_fma_f32 v[134:135], v[8:9], v[102:103], v[134:135]
	v_add_f32_e32 v124, v124, v125
	v_add_f32_e32 v126, v126, v127
	v_add_f32_e32 v128, v128, v129
	v_add_f32_e32 v134, v134, v135
	v_mul_f32_e32 v142, v108, v112
	v_add_f32_dpp v125, v124, v124 row_mirror row_mask:0xf bank_mask:0xf
	v_add_f32_dpp v125, v126, v126 row_mirror row_mask:0xf bank_mask:0xc
	v_add_f32_dpp v127, v128, v128 row_mirror row_mask:0xf bank_mask:0xf
	v_add_f32_dpp v127, v134, v134 row_mirror row_mask:0xf bank_mask:0xc
	v_add_f32_dpp v129, v125, v125 row_half_mirror row_mask:0xf bank_mask:0xf
	v_pk_mul_f32 v[2:3], v[2:3], v[142:143] op_sel_hi:[1,0]
	v_pk_mul_f32 v[4:5], v[4:5], v[142:143] op_sel_hi:[1,0]
	v_add_f32_dpp v129, v127, v127 row_half_mirror row_mask:0xf bank_mask:0xa
	v_pk_mul_f32 v[6:7], v[6:7], v[142:143] op_sel_hi:[1,0]
	v_pk_mul_f32 v[8:9], v[8:9], v[142:143] op_sel_hi:[1,0]
	v_add_f32_dpp v129, v129, v129 quad_perm:[1,0,3,2] row_mask:0xf bank_mask:0xf
	ds_read_b128 v[88:91], v0 offset:44544
	ds_read_b128 v[92:95], v0 offset:44800
	v_add_f32_dpp v129, v129, v129 quad_perm:[2,3,0,1] row_mask:0xf bank_mask:0xf
	ds_read_b128 v[96:99], v0 offset:46080
	ds_read_b128 v[100:103], v0 offset:46336
	v_fmac_f32_dpp v104, -v129, v108 row_newbcast:0 row_mask:0xf bank_mask:0xf
	v_mul_f32_dpp v141, v129, v108 row_newbcast:4 row_mask:0xf bank_mask:0xf
	v_mul_f32_e32 v138, v109, v104
	v_mul_f32_dpp v139, v129, v108 row_newbcast:8 row_mask:0xf bank_mask:0xf
	v_fmac_f32_e32 v141, v111, v138
	v_mul_f32_dpp v143, v129, v108 row_newbcast:12 row_mask:0xf bank_mask:0xf
	v_fma_f32 v105, -v112, v141, v105
	v_mul_f32_e32 v144, v112, v138
	v_mul_f32_e32 v140, v113, v105
	v_fmac_f32_e32 v139, v110, v138
	v_pk_fma_f32 v[2:3], v[56:57], v[144:145], v[2:3] op_sel_hi:[1,0,1]
	v_fmac_f32_e32 v143, v115, v138
	v_pk_fma_f32 v[4:5], v[58:59], v[144:145], v[4:5] op_sel_hi:[1,0,1]
	v_pk_fma_f32 v[6:7], v[60:61], v[144:145], v[6:7] op_sel_hi:[1,0,1]
	v_pk_fma_f32 v[8:9], v[62:63], v[144:145], v[8:9] op_sel_hi:[1,0,1]
	v_pk_fma_f32 v[2:3], v[64:65], v[140:141], v[2:3] op_sel_hi:[1,0,1]
	v_pk_fma_f32 v[4:5], v[66:67], v[140:141], v[4:5] op_sel_hi:[1,0,1]
	v_pk_fma_f32 v[6:7], v[68:69], v[140:141], v[6:7] op_sel_hi:[1,0,1]
	v_pk_fma_f32 v[8:9], v[70:71], v[140:141], v[8:9] op_sel_hi:[1,0,1]
	s_waitcnt lgkmcnt(0)
	v_pk_mul_f32 v[124:125], v[2:3], v[72:73]
	v_mul_f32_e32 v143, v143, v112
	v_pk_mul_f32 v[126:127], v[2:3], v[88:89]
	v_fmac_f32_e32 v143, v114, v140
	v_pk_mul_f32 v[128:129], v[2:3], v[80:81]
	ds_write2_b32 v55, v139, v143 offset0:128 offset1:144
	v_pk_mul_f32 v[134:135], v[2:3], v[96:97]
	ds_read_b128 v[56:59], v0 offset:47104
	v_pk_fma_f32 v[124:125], v[4:5], v[74:75], v[124:125]
	ds_read_b128 v[60:63], v0 offset:47360
	v_pk_fma_f32 v[126:127], v[4:5], v[90:91], v[126:127]
	ds_read_b128 v[64:67], v0 offset:48640
	v_pk_fma_f32 v[128:129], v[4:5], v[82:83], v[128:129]
	ds_read_b128 v[68:71], v0 offset:48896
	v_pk_fma_f32 v[134:135], v[4:5], v[98:99], v[134:135]
	ds_read2st64_b32 v[104:105], v43 offset0:188 offset1:194
	v_pk_fma_f32 v[124:125], v[6:7], v[76:77], v[124:125]
	ds_read_b128 v[108:111], v53 offset:53696
	v_pk_fma_f32 v[126:127], v[6:7], v[92:93], v[126:127]
	ds_read_b128 v[112:115], v53 offset:53712
	v_pk_fma_f32 v[128:129], v[6:7], v[84:85], v[128:129]
	v_pk_fma_f32 v[134:135], v[6:7], v[100:101], v[134:135]
	v_pk_fma_f32 v[124:125], v[8:9], v[78:79], v[124:125]
	v_pk_fma_f32 v[126:127], v[8:9], v[94:95], v[126:127]
	v_pk_fma_f32 v[128:129], v[8:9], v[86:87], v[128:129]
	v_pk_fma_f32 v[134:135], v[8:9], v[102:103], v[134:135]
	v_add_f32_e32 v124, v124, v125
	v_add_f32_e32 v126, v126, v127
	v_add_f32_e32 v128, v128, v129
	v_add_f32_e32 v134, v134, v135
	v_mul_f32_e32 v142, v116, v120
	v_add_f32_dpp v125, v124, v124 row_mirror row_mask:0xf bank_mask:0xf
	v_add_f32_dpp v125, v126, v126 row_mirror row_mask:0xf bank_mask:0xc
	v_add_f32_dpp v127, v128, v128 row_mirror row_mask:0xf bank_mask:0xf
	v_add_f32_dpp v127, v134, v134 row_mirror row_mask:0xf bank_mask:0xc
	v_add_f32_dpp v129, v125, v125 row_half_mirror row_mask:0xf bank_mask:0xf
	v_pk_mul_f32 v[2:3], v[2:3], v[142:143] op_sel_hi:[1,0]
	v_pk_mul_f32 v[4:5], v[4:5], v[142:143] op_sel_hi:[1,0]
	v_add_f32_dpp v129, v127, v127 row_half_mirror row_mask:0xf bank_mask:0xa
	v_pk_mul_f32 v[6:7], v[6:7], v[142:143] op_sel_hi:[1,0]
	v_pk_mul_f32 v[8:9], v[8:9], v[142:143] op_sel_hi:[1,0]
	v_add_f32_dpp v129, v129, v129 quad_perm:[1,0,3,2] row_mask:0xf bank_mask:0xf
	ds_read_b128 v[88:91], v0 offset:47616
	ds_read_b128 v[92:95], v0 offset:47872
	v_add_f32_dpp v129, v129, v129 quad_perm:[2,3,0,1] row_mask:0xf bank_mask:0xf
	ds_read_b128 v[96:99], v0 offset:49152
	ds_read_b128 v[100:103], v0 offset:49408
	v_fmac_f32_dpp v106, -v129, v116 row_newbcast:0 row_mask:0xf bank_mask:0xf
	v_mul_f32_dpp v141, v129, v116 row_newbcast:4 row_mask:0xf bank_mask:0xf
	v_mul_f32_e32 v138, v117, v106
	v_mul_f32_dpp v139, v129, v116 row_newbcast:8 row_mask:0xf bank_mask:0xf
	v_fmac_f32_e32 v141, v119, v138
	v_mul_f32_dpp v143, v129, v116 row_newbcast:12 row_mask:0xf bank_mask:0xf
	v_fma_f32 v107, -v120, v141, v107
	v_mul_f32_e32 v144, v120, v138
	v_mul_f32_e32 v140, v121, v107
	v_fmac_f32_e32 v139, v118, v138
	v_pk_fma_f32 v[2:3], v[72:73], v[144:145], v[2:3] op_sel_hi:[1,0,1]
	v_fmac_f32_e32 v143, v123, v138
	v_pk_fma_f32 v[4:5], v[74:75], v[144:145], v[4:5] op_sel_hi:[1,0,1]
	v_pk_fma_f32 v[6:7], v[76:77], v[144:145], v[6:7] op_sel_hi:[1,0,1]
	v_pk_fma_f32 v[8:9], v[78:79], v[144:145], v[8:9] op_sel_hi:[1,0,1]
	v_pk_fma_f32 v[2:3], v[80:81], v[140:141], v[2:3] op_sel_hi:[1,0,1]
	v_pk_fma_f32 v[4:5], v[82:83], v[140:141], v[4:5] op_sel_hi:[1,0,1]
	v_pk_fma_f32 v[6:7], v[84:85], v[140:141], v[6:7] op_sel_hi:[1,0,1]
	v_pk_fma_f32 v[8:9], v[86:87], v[140:141], v[8:9] op_sel_hi:[1,0,1]
	s_waitcnt lgkmcnt(0)
	v_pk_mul_f32 v[124:125], v[2:3], v[56:57]
	v_mul_f32_e32 v143, v143, v120
	v_pk_mul_f32 v[126:127], v[2:3], v[88:89]
	v_fmac_f32_e32 v143, v122, v140
	v_pk_mul_f32 v[128:129], v[2:3], v[64:65]
	ds_write2_b32 v55, v139, v143 offset0:160 offset1:176
	v_pk_mul_f32 v[134:135], v[2:3], v[96:97]
	ds_read_b128 v[72:75], v0 offset:50176
	v_pk_fma_f32 v[124:125], v[4:5], v[58:59], v[124:125]
	ds_read_b128 v[76:79], v0 offset:50432
	v_pk_fma_f32 v[126:127], v[4:5], v[90:91], v[126:127]
	ds_read_b128 v[80:83], v0 offset:51712
	v_pk_fma_f32 v[128:129], v[4:5], v[66:67], v[128:129]
	ds_read_b128 v[84:87], v0 offset:51968
	v_pk_fma_f32 v[134:135], v[4:5], v[98:99], v[134:135]
	ds_read2st64_b32 v[106:107], v43 offset0:200 offset1:206
	v_pk_fma_f32 v[124:125], v[6:7], v[60:61], v[124:125]
	ds_read_b128 v[116:119], v53 offset:53728
	v_pk_fma_f32 v[126:127], v[6:7], v[92:93], v[126:127]
	ds_read_b128 v[120:123], v53 offset:53744
	v_pk_fma_f32 v[128:129], v[6:7], v[68:69], v[128:129]
	v_pk_fma_f32 v[134:135], v[6:7], v[100:101], v[134:135]
	v_pk_fma_f32 v[124:125], v[8:9], v[62:63], v[124:125]
	v_pk_fma_f32 v[126:127], v[8:9], v[94:95], v[126:127]
	v_pk_fma_f32 v[128:129], v[8:9], v[70:71], v[128:129]
	v_pk_fma_f32 v[134:135], v[8:9], v[102:103], v[134:135]
	v_add_f32_e32 v124, v124, v125
	v_add_f32_e32 v126, v126, v127
	v_add_f32_e32 v128, v128, v129
	v_add_f32_e32 v134, v134, v135
	v_mul_f32_e32 v142, v108, v112
	v_add_f32_dpp v125, v124, v124 row_mirror row_mask:0xf bank_mask:0xf
	v_add_f32_dpp v125, v126, v126 row_mirror row_mask:0xf bank_mask:0xc
	v_add_f32_dpp v127, v128, v128 row_mirror row_mask:0xf bank_mask:0xf
	v_add_f32_dpp v127, v134, v134 row_mirror row_mask:0xf bank_mask:0xc
	v_add_f32_dpp v129, v125, v125 row_half_mirror row_mask:0xf bank_mask:0xf
	v_pk_mul_f32 v[2:3], v[2:3], v[142:143] op_sel_hi:[1,0]
	v_pk_mul_f32 v[4:5], v[4:5], v[142:143] op_sel_hi:[1,0]
	v_add_f32_dpp v129, v127, v127 row_half_mirror row_mask:0xf bank_mask:0xa
	v_pk_mul_f32 v[6:7], v[6:7], v[142:143] op_sel_hi:[1,0]
	v_pk_mul_f32 v[8:9], v[8:9], v[142:143] op_sel_hi:[1,0]
	v_add_f32_dpp v129, v129, v129 quad_perm:[1,0,3,2] row_mask:0xf bank_mask:0xf
	ds_read_b128 v[88:91], v0 offset:50688
	ds_read_b128 v[92:95], v0 offset:50944
	v_add_f32_dpp v129, v129, v129 quad_perm:[2,3,0,1] row_mask:0xf bank_mask:0xf
	ds_read_b128 v[96:99], v0 offset:52224
	ds_read_b128 v[100:103], v0 offset:52480
	v_fmac_f32_dpp v104, -v129, v108 row_newbcast:0 row_mask:0xf bank_mask:0xf
	v_mul_f32_dpp v141, v129, v108 row_newbcast:4 row_mask:0xf bank_mask:0xf
	v_mul_f32_e32 v138, v109, v104
	v_mul_f32_dpp v139, v129, v108 row_newbcast:8 row_mask:0xf bank_mask:0xf
	v_fmac_f32_e32 v141, v111, v138
	v_mul_f32_dpp v143, v129, v108 row_newbcast:12 row_mask:0xf bank_mask:0xf
	v_fma_f32 v105, -v112, v141, v105
	v_mul_f32_e32 v144, v112, v138
	v_mul_f32_e32 v140, v113, v105
	v_fmac_f32_e32 v139, v110, v138
	v_pk_fma_f32 v[2:3], v[56:57], v[144:145], v[2:3] op_sel_hi:[1,0,1]
	v_fmac_f32_e32 v143, v115, v138
	v_pk_fma_f32 v[4:5], v[58:59], v[144:145], v[4:5] op_sel_hi:[1,0,1]
	v_pk_fma_f32 v[6:7], v[60:61], v[144:145], v[6:7] op_sel_hi:[1,0,1]
	v_pk_fma_f32 v[8:9], v[62:63], v[144:145], v[8:9] op_sel_hi:[1,0,1]
	v_pk_fma_f32 v[2:3], v[64:65], v[140:141], v[2:3] op_sel_hi:[1,0,1]
	v_pk_fma_f32 v[4:5], v[66:67], v[140:141], v[4:5] op_sel_hi:[1,0,1]
	v_pk_fma_f32 v[6:7], v[68:69], v[140:141], v[6:7] op_sel_hi:[1,0,1]
	v_pk_fma_f32 v[8:9], v[70:71], v[140:141], v[8:9] op_sel_hi:[1,0,1]
	s_waitcnt lgkmcnt(0)
	v_pk_mul_f32 v[124:125], v[2:3], v[72:73]
	v_mul_f32_e32 v143, v143, v112
	v_pk_mul_f32 v[126:127], v[2:3], v[88:89]
	v_fmac_f32_e32 v143, v114, v140
	v_pk_mul_f32 v[128:129], v[2:3], v[80:81]
	ds_write2_b32 v55, v139, v143 offset0:192 offset1:208
	v_pk_mul_f32 v[134:135], v[2:3], v[96:97]
	v_pk_fma_f32 v[124:125], v[4:5], v[74:75], v[124:125]
	v_pk_fma_f32 v[126:127], v[4:5], v[90:91], v[126:127]
	v_pk_fma_f32 v[128:129], v[4:5], v[82:83], v[128:129]
	v_pk_fma_f32 v[134:135], v[4:5], v[98:99], v[134:135]
	v_pk_fma_f32 v[124:125], v[6:7], v[76:77], v[124:125]
	v_pk_fma_f32 v[126:127], v[6:7], v[92:93], v[126:127]
	v_pk_fma_f32 v[128:129], v[6:7], v[84:85], v[128:129]
	v_pk_fma_f32 v[134:135], v[6:7], v[100:101], v[134:135]
	v_pk_fma_f32 v[124:125], v[8:9], v[78:79], v[124:125]
	v_pk_fma_f32 v[126:127], v[8:9], v[94:95], v[126:127]
	v_pk_fma_f32 v[128:129], v[8:9], v[86:87], v[128:129]
	v_pk_fma_f32 v[134:135], v[8:9], v[102:103], v[134:135]
	v_add_f32_e32 v124, v124, v125
	v_add_f32_e32 v126, v126, v127
	v_add_f32_e32 v128, v128, v129
	v_add_f32_e32 v134, v134, v135
	v_mul_f32_e32 v142, v116, v120
	v_add_f32_dpp v125, v124, v124 row_mirror row_mask:0xf bank_mask:0xf
	v_add_f32_dpp v125, v126, v126 row_mirror row_mask:0xf bank_mask:0xc
	v_add_f32_dpp v127, v128, v128 row_mirror row_mask:0xf bank_mask:0xf
	v_add_f32_dpp v127, v134, v134 row_mirror row_mask:0xf bank_mask:0xc
	v_add_f32_dpp v129, v125, v125 row_half_mirror row_mask:0xf bank_mask:0xf
	v_pk_mul_f32 v[2:3], v[2:3], v[142:143] op_sel_hi:[1,0]
	v_pk_mul_f32 v[4:5], v[4:5], v[142:143] op_sel_hi:[1,0]
	v_add_f32_dpp v129, v127, v127 row_half_mirror row_mask:0xf bank_mask:0xa
	v_pk_mul_f32 v[6:7], v[6:7], v[142:143] op_sel_hi:[1,0]
	v_pk_mul_f32 v[8:9], v[8:9], v[142:143] op_sel_hi:[1,0]
	v_add_f32_dpp v129, v129, v129 quad_perm:[1,0,3,2] row_mask:0xf bank_mask:0xf
	s_nop 1
	v_add_f32_dpp v129, v129, v129 quad_perm:[2,3,0,1] row_mask:0xf bank_mask:0xf
	s_nop 1
	v_fmac_f32_dpp v106, -v129, v116 row_newbcast:0 row_mask:0xf bank_mask:0xf
	v_mul_f32_dpp v141, v129, v116 row_newbcast:4 row_mask:0xf bank_mask:0xf
	v_mul_f32_e32 v138, v117, v106
	v_mul_f32_dpp v139, v129, v116 row_newbcast:8 row_mask:0xf bank_mask:0xf
	v_fmac_f32_e32 v141, v119, v138
	v_mul_f32_dpp v143, v129, v116 row_newbcast:12 row_mask:0xf bank_mask:0xf
	v_fma_f32 v107, -v120, v141, v107
	v_mul_f32_e32 v144, v120, v138
	v_mul_f32_e32 v140, v121, v107
	v_fmac_f32_e32 v139, v118, v138
	v_pk_fma_f32 v[2:3], v[72:73], v[144:145], v[2:3] op_sel_hi:[1,0,1]
	v_fmac_f32_e32 v143, v123, v138
	v_pk_fma_f32 v[4:5], v[74:75], v[144:145], v[4:5] op_sel_hi:[1,0,1]
	v_pk_fma_f32 v[6:7], v[76:77], v[144:145], v[6:7] op_sel_hi:[1,0,1]
	v_pk_fma_f32 v[8:9], v[78:79], v[144:145], v[8:9] op_sel_hi:[1,0,1]
	v_pk_fma_f32 v[2:3], v[80:81], v[140:141], v[2:3] op_sel_hi:[1,0,1]
	v_pk_fma_f32 v[4:5], v[82:83], v[140:141], v[4:5] op_sel_hi:[1,0,1]
	v_pk_fma_f32 v[6:7], v[84:85], v[140:141], v[6:7] op_sel_hi:[1,0,1]
	v_pk_fma_f32 v[8:9], v[86:87], v[140:141], v[8:9] op_sel_hi:[1,0,1]
	v_mul_f32_e32 v143, v143, v120
	v_fmac_f32_e32 v143, v122, v140
	ds_write2_b32 v55, v139, v143 offset0:224 offset1:240

.LBB0_853:
	s_add_i32 s41, s14, 1
	s_and_saveexec_b64 s[26:27], s[44:45]
	s_xor_b64 vcc, exec, s[26:27]
	s_cbranch_execz .LBB0_855
	s_and_b32 s26, s41, 1
	s_mul_i32 s27, s26, 0xc200
	s_add_i32 s27, s27, 0
	v_add_u32_e32 v0, s27, v155
	v_add_u32_e32 v158, s27, v156
	v_mov_b32_e32 v123, s27
	v_lshl_add_u32 v159, s26, 11, v154
	v_add_u32_e32 v166, 0x400, v159
	ds_read_b128 v[6:9], v0 offset:4096
	ds_read_b128 v[10:13], v0 offset:4352
	ds_read_b128 v[14:17], v0 offset:4608
	ds_read_b128 v[18:21], v0 offset:4864
	ds_read2st64_b32 v[62:63], v158 offset0:25 offset1:26
	ds_read_b128 v[64:67], v123 offset:53248
	ds_read_b128 v[68:71], v123 offset:53264
	ds_read_b128 v[22:25], v0 offset:5120
	ds_read_b128 v[26:29], v0 offset:5376
	ds_read_b128 v[30:33], v0 offset:5632
	ds_read_b128 v[34:37], v0 offset:5888
	ds_read_b128 v[38:41], v0 offset:6144
	s_waitcnt lgkmcnt(0)
	v_pk_mul_f32 v[82:83], v[138:139], v[6:7]
	ds_read_b128 v[42:45], v0 offset:8192
	v_pk_mul_f32 v[84:85], v[138:139], v[10:11]
	ds_read_b128 v[46:49], v0 offset:8448
	v_pk_mul_f32 v[86:87], v[138:139], v[14:15]
	ds_read_b128 v[50:53], v0 offset:8704
	v_pk_mul_f32 v[88:89], v[138:139], v[18:19]
	ds_read_b128 v[54:57], v0 offset:8960
	v_pk_fma_f32 v[82:83], v[140:141], v[8:9], v[82:83]
	ds_read_b128 v[58:61], v0 offset:9216
	v_pk_fma_f32 v[84:85], v[140:141], v[12:13], v[84:85]
	ds_read2st64_b32 v[72:73], v158 offset0:37 offset1:38
	v_pk_fma_f32 v[86:87], v[140:141], v[16:17], v[86:87]
	ds_read_b128 v[74:77], v123 offset:53280
	v_pk_fma_f32 v[88:89], v[140:141], v[20:21], v[88:89]
	ds_read_b128 v[78:81], v123 offset:53296
	v_pk_mul_f32 v[138:139], v[138:139], v[22:23]
	v_pk_mul_f32 v[140:141], v[140:141], v[24:25]
	v_add_f32_e32 v82, v82, v83
	v_add_f32_e32 v84, v84, v85
	v_add_f32_e32 v86, v86, v87
	v_add_f32_e32 v88, v88, v89
	ds_read_b128 v[6:9], v0 offset:7168
	ds_read_b128 v[10:13], v0 offset:7424
	ds_read_b128 v[14:17], v0 offset:7680
	ds_read_b128 v[18:21], v0 offset:7936
	v_add_f32_dpp v83, v82, v82 row_mirror row_mask:0xf bank_mask:0xf
	v_add_f32_dpp v83, v84, v84 row_mirror row_mask:0xf bank_mask:0xc
	v_add_f32_dpp v85, v86, v86 row_mirror row_mask:0xf bank_mask:0xf
	v_add_f32_dpp v85, v88, v88 row_mirror row_mask:0xf bank_mask:0xc
	v_add_f32_dpp v87, v83, v83 row_half_mirror row_mask:0xf bank_mask:0xf
	v_pk_fma_f32 v[138:139], v[30:31], v[62:63], v[138:139] op_sel_hi:[1,0,1]
	v_pk_fma_f32 v[140:141], v[32:33], v[62:63], v[140:141] op_sel_hi:[1,0,1]
	v_add_f32_dpp v87, v85, v85 row_half_mirror row_mask:0xf bank_mask:0xa
	v_pk_fma_f32 v[138:139], v[38:39], v[62:63], v[138:139] op_sel:[0,1,0] op_sel_hi:[1,1,1]
	v_pk_fma_f32 v[140:141], v[40:41], v[62:63], v[140:141] op_sel:[0,1,0] op_sel_hi:[1,1,1]
	v_add_f32_dpp v87, v87, v87 quad_perm:[1,0,3,2] row_mask:0xf bank_mask:0xf
	v_mul_f32_e32 v134, v62, v65
	v_mul_f32_e32 v135, v62, v71
	v_add_f32_dpp v87, v87, v87 quad_perm:[2,3,0,1] row_mask:0xf bank_mask:0xf
	v_fmac_f32_e32 v135, v63, v69
	v_mul_f32_e32 v92, v62, v67
	v_mov_b32_dpp v90, v87 row_newbcast:0 row_mask:0xf bank_mask:0xf
	v_add_f32_dpp v92, v87, v92 row_newbcast:4 row_mask:0xf bank_mask:0xf
	v_add_f32_dpp v91, v87, v134 row_newbcast:8 row_mask:0xf bank_mask:0xf
	v_pk_fma_f32 v[138:139], v[26:27], v[90:91], v[138:139] op_sel_hi:[1,0,1] neg_lo:[0,1,0] neg_hi:[0,1,0]
	v_fma_f32 v92, -v90, v66, v92
	v_pk_fma_f32 v[140:141], v[28:29], v[90:91], v[140:141] op_sel_hi:[1,0,1] neg_lo:[0,1,0] neg_hi:[0,1,0]
	v_add_f32_dpp v93, v87, v135 row_newbcast:12 row_mask:0xf bank_mask:0xf
	v_pk_fma_f32 v[138:139], v[34:35], v[92:93], v[138:139] op_sel_hi:[1,0,1] neg_lo:[0,1,0] neg_hi:[0,1,0]
	v_pk_fma_f32 v[140:141], v[36:37], v[92:93], v[140:141] op_sel_hi:[1,0,1] neg_lo:[0,1,0] neg_hi:[0,1,0]
	s_waitcnt lgkmcnt(0)
	v_pk_mul_f32 v[82:83], v[138:139], v[6:7]
	v_fma_f32 v91, -v90, v64, v91
	v_pk_mul_f32 v[84:85], v[138:139], v[10:11]
	v_fma_f32 v93, -v90, v70, v93
	v_pk_mul_f32 v[86:87], v[138:139], v[14:15]
	v_fma_f32 v93, -v92, v68, v93
	v_pk_mul_f32 v[88:89], v[138:139], v[18:19]
	ds_write2_b32 v159, v91, v93 offset0:0 offset1:16
	v_pk_fma_f32 v[82:83], v[140:141], v[8:9], v[82:83]
	ds_read_b128 v[22:25], v0 offset:11264
	v_pk_fma_f32 v[84:85], v[140:141], v[12:13], v[84:85]
	ds_read_b128 v[26:29], v0 offset:11520
	v_pk_fma_f32 v[86:87], v[140:141], v[16:17], v[86:87]
	ds_read_b128 v[30:33], v0 offset:11776
	v_pk_fma_f32 v[88:89], v[140:141], v[20:21], v[88:89]
	ds_read_b128 v[34:37], v0 offset:12032
	v_pk_mul_f32 v[138:139], v[138:139], v[42:43]
	ds_read_b128 v[38:41], v0 offset:12288
	v_pk_mul_f32 v[140:141], v[140:141], v[44:45]
	ds_read2st64_b32 v[62:63], v158 offset0:49 offset1:50
	v_add_f32_e32 v82, v82, v83
	ds_read_b128 v[64:67], v123 offset:53312
	v_add_f32_e32 v84, v84, v85
	ds_read_b128 v[68:71], v123 offset:53328
	v_add_f32_e32 v86, v86, v87
	v_add_f32_e32 v88, v88, v89
	ds_read_b128 v[6:9], v0 offset:10240
	ds_read_b128 v[10:13], v0 offset:10496
	ds_read_b128 v[14:17], v0 offset:10752
	ds_read_b128 v[18:21], v0 offset:11008
	v_add_f32_dpp v83, v82, v82 row_mirror row_mask:0xf bank_mask:0xf
	v_add_f32_dpp v83, v84, v84 row_mirror row_mask:0xf bank_mask:0xc
	v_add_f32_dpp v85, v86, v86 row_mirror row_mask:0xf bank_mask:0xf
	v_add_f32_dpp v85, v88, v88 row_mirror row_mask:0xf bank_mask:0xc
	v_add_f32_dpp v87, v83, v83 row_half_mirror row_mask:0xf bank_mask:0xf
	v_pk_fma_f32 v[138:139], v[50:51], v[72:73], v[138:139] op_sel_hi:[1,0,1]
	v_pk_fma_f32 v[140:141], v[52:53], v[72:73], v[140:141] op_sel_hi:[1,0,1]
	v_add_f32_dpp v87, v85, v85 row_half_mirror row_mask:0xf bank_mask:0xa
	v_pk_fma_f32 v[138:139], v[58:59], v[72:73], v[138:139] op_sel:[0,1,0] op_sel_hi:[1,1,1]
	v_pk_fma_f32 v[140:141], v[60:61], v[72:73], v[140:141] op_sel:[0,1,0] op_sel_hi:[1,1,1]
	v_add_f32_dpp v87, v87, v87 quad_perm:[1,0,3,2] row_mask:0xf bank_mask:0xf
	v_mul_f32_e32 v134, v72, v75
	v_mul_f32_e32 v135, v72, v81
	v_add_f32_dpp v87, v87, v87 quad_perm:[2,3,0,1] row_mask:0xf bank_mask:0xf
	v_fmac_f32_e32 v135, v73, v79
	v_mul_f32_e32 v92, v72, v77
	v_mov_b32_dpp v90, v87 row_newbcast:0 row_mask:0xf bank_mask:0xf
	v_add_f32_dpp v92, v87, v92 row_newbcast:4 row_mask:0xf bank_mask:0xf
	v_add_f32_dpp v91, v87, v134 row_newbcast:8 row_mask:0xf bank_mask:0xf
	v_pk_fma_f32 v[138:139], v[46:47], v[90:91], v[138:139] op_sel_hi:[1,0,1] neg_lo:[0,1,0] neg_hi:[0,1,0]
	v_fma_f32 v92, -v90, v76, v92
	v_pk_fma_f32 v[140:141], v[48:49], v[90:91], v[140:141] op_sel_hi:[1,0,1] neg_lo:[0,1,0] neg_hi:[0,1,0]
	v_add_f32_dpp v93, v87, v135 row_newbcast:12 row_mask:0xf bank_mask:0xf
	v_pk_fma_f32 v[138:139], v[54:55], v[92:93], v[138:139] op_sel_hi:[1,0,1] neg_lo:[0,1,0] neg_hi:[0,1,0]
	v_pk_fma_f32 v[140:141], v[56:57], v[92:93], v[140:141] op_sel_hi:[1,0,1] neg_lo:[0,1,0] neg_hi:[0,1,0]
	s_waitcnt lgkmcnt(0)
	v_pk_mul_f32 v[82:83], v[138:139], v[6:7]
	v_fma_f32 v91, -v90, v74, v91
	v_pk_mul_f32 v[84:85], v[138:139], v[10:11]
	v_fma_f32 v93, -v90, v80, v93
	v_pk_mul_f32 v[86:87], v[138:139], v[14:15]
	v_fma_f32 v93, -v92, v78, v93
	v_pk_mul_f32 v[88:89], v[138:139], v[18:19]
	ds_write2_b32 v159, v91, v93 offset0:32 offset1:48
	v_pk_fma_f32 v[82:83], v[140:141], v[8:9], v[82:83]
	ds_read_b128 v[42:45], v0 offset:14336
	v_pk_fma_f32 v[84:85], v[140:141], v[12:13], v[84:85]
	ds_read_b128 v[46:49], v0 offset:14592
	v_pk_fma_f32 v[86:87], v[140:141], v[16:17], v[86:87]
	ds_read_b128 v[50:53], v0 offset:14848
	v_pk_fma_f32 v[88:89], v[140:141], v[20:21], v[88:89]
	ds_read_b128 v[54:57], v0 offset:15104
	v_pk_mul_f32 v[138:139], v[138:139], v[22:23]
	ds_read_b128 v[58:61], v0 offset:15360
	v_pk_mul_f32 v[140:141], v[140:141], v[24:25]
	ds_read2st64_b32 v[72:73], v158 offset0:61 offset1:62
	v_add_f32_e32 v82, v82, v83
	ds_read_b128 v[74:77], v123 offset:53344
	v_add_f32_e32 v84, v84, v85
	ds_read_b128 v[78:81], v123 offset:53360
	v_add_f32_e32 v86, v86, v87
	v_add_f32_e32 v88, v88, v89
	ds_read_b128 v[6:9], v0 offset:13312
	ds_read_b128 v[10:13], v0 offset:13568
	ds_read_b128 v[14:17], v0 offset:13824
	ds_read_b128 v[18:21], v0 offset:14080
	v_add_f32_dpp v83, v82, v82 row_mirror row_mask:0xf bank_mask:0xf
	v_add_f32_dpp v83, v84, v84 row_mirror row_mask:0xf bank_mask:0xc
	v_add_f32_dpp v85, v86, v86 row_mirror row_mask:0xf bank_mask:0xf
	v_add_f32_dpp v85, v88, v88 row_mirror row_mask:0xf bank_mask:0xc
	v_add_f32_dpp v87, v83, v83 row_half_mirror row_mask:0xf bank_mask:0xf
	v_pk_fma_f32 v[138:139], v[30:31], v[62:63], v[138:139] op_sel_hi:[1,0,1]
	v_pk_fma_f32 v[140:141], v[32:33], v[62:63], v[140:141] op_sel_hi:[1,0,1]
	v_add_f32_dpp v87, v85, v85 row_half_mirror row_mask:0xf bank_mask:0xa
	v_pk_fma_f32 v[138:139], v[38:39], v[62:63], v[138:139] op_sel:[0,1,0] op_sel_hi:[1,1,1]
	v_pk_fma_f32 v[140:141], v[40:41], v[62:63], v[140:141] op_sel:[0,1,0] op_sel_hi:[1,1,1]
	v_add_f32_dpp v87, v87, v87 quad_perm:[1,0,3,2] row_mask:0xf bank_mask:0xf
	v_mul_f32_e32 v134, v62, v65
	v_mul_f32_e32 v135, v62, v71
	v_add_f32_dpp v87, v87, v87 quad_perm:[2,3,0,1] row_mask:0xf bank_mask:0xf
	v_fmac_f32_e32 v135, v63, v69
	v_mul_f32_e32 v92, v62, v67
	v_mov_b32_dpp v90, v87 row_newbcast:0 row_mask:0xf bank_mask:0xf
	v_add_f32_dpp v92, v87, v92 row_newbcast:4 row_mask:0xf bank_mask:0xf
	v_add_f32_dpp v91, v87, v134 row_newbcast:8 row_mask:0xf bank_mask:0xf
	v_pk_fma_f32 v[138:139], v[26:27], v[90:91], v[138:139] op_sel_hi:[1,0,1] neg_lo:[0,1,0] neg_hi:[0,1,0]
	v_fma_f32 v92, -v90, v66, v92
	v_pk_fma_f32 v[140:141], v[28:29], v[90:91], v[140:141] op_sel_hi:[1,0,1] neg_lo:[0,1,0] neg_hi:[0,1,0]
	v_add_f32_dpp v93, v87, v135 row_newbcast:12 row_mask:0xf bank_mask:0xf
	v_pk_fma_f32 v[138:139], v[34:35], v[92:93], v[138:139] op_sel_hi:[1,0,1] neg_lo:[0,1,0] neg_hi:[0,1,0]
	v_pk_fma_f32 v[140:141], v[36:37], v[92:93], v[140:141] op_sel_hi:[1,0,1] neg_lo:[0,1,0] neg_hi:[0,1,0]
	s_waitcnt lgkmcnt(0)
	v_pk_mul_f32 v[82:83], v[138:139], v[6:7]
	v_fma_f32 v91, -v90, v64, v91
	v_pk_mul_f32 v[84:85], v[138:139], v[10:11]
	v_fma_f32 v93, -v90, v70, v93
	v_pk_mul_f32 v[86:87], v[138:139], v[14:15]
	v_fma_f32 v93, -v92, v68, v93
	v_pk_mul_f32 v[88:89], v[138:139], v[18:19]
	ds_write2_b32 v159, v91, v93 offset0:64 offset1:80
	v_pk_fma_f32 v[82:83], v[140:141], v[8:9], v[82:83]
	ds_read_b128 v[22:25], v0 offset:17408
	v_pk_fma_f32 v[84:85], v[140:141], v[12:13], v[84:85]
	ds_read_b128 v[26:29], v0 offset:17664
	v_pk_fma_f32 v[86:87], v[140:141], v[16:17], v[86:87]
	ds_read_b128 v[30:33], v0 offset:17920
	v_pk_fma_f32 v[88:89], v[140:141], v[20:21], v[88:89]
	ds_read_b128 v[34:37], v0 offset:18176
	v_pk_mul_f32 v[138:139], v[138:139], v[42:43]
	ds_read_b128 v[38:41], v0 offset:18432
	v_pk_mul_f32 v[140:141], v[140:141], v[44:45]
	ds_read2st64_b32 v[62:63], v158 offset0:73 offset1:74
	v_add_f32_e32 v82, v82, v83
	ds_read_b128 v[64:67], v123 offset:53376
	v_add_f32_e32 v84, v84, v85
	ds_read_b128 v[68:71], v123 offset:53392
	v_add_f32_e32 v86, v86, v87
	v_add_f32_e32 v88, v88, v89
	ds_read_b128 v[6:9], v0 offset:16384
	ds_read_b128 v[10:13], v0 offset:16640
	ds_read_b128 v[14:17], v0 offset:16896
	ds_read_b128 v[18:21], v0 offset:17152
	v_add_f32_dpp v83, v82, v82 row_mirror row_mask:0xf bank_mask:0xf
	v_add_f32_dpp v83, v84, v84 row_mirror row_mask:0xf bank_mask:0xc
	v_add_f32_dpp v85, v86, v86 row_mirror row_mask:0xf bank_mask:0xf
	v_add_f32_dpp v85, v88, v88 row_mirror row_mask:0xf bank_mask:0xc
	v_add_f32_dpp v87, v83, v83 row_half_mirror row_mask:0xf bank_mask:0xf
	v_pk_fma_f32 v[138:139], v[50:51], v[72:73], v[138:139] op_sel_hi:[1,0,1]
	v_pk_fma_f32 v[140:141], v[52:53], v[72:73], v[140:141] op_sel_hi:[1,0,1]
	v_add_f32_dpp v87, v85, v85 row_half_mirror row_mask:0xf bank_mask:0xa
	v_pk_fma_f32 v[138:139], v[58:59], v[72:73], v[138:139] op_sel:[0,1,0] op_sel_hi:[1,1,1]
	v_pk_fma_f32 v[140:141], v[60:61], v[72:73], v[140:141] op_sel:[0,1,0] op_sel_hi:[1,1,1]
	v_add_f32_dpp v87, v87, v87 quad_perm:[1,0,3,2] row_mask:0xf bank_mask:0xf
	v_mul_f32_e32 v134, v72, v75
	v_mul_f32_e32 v135, v72, v81
	v_add_f32_dpp v87, v87, v87 quad_perm:[2,3,0,1] row_mask:0xf bank_mask:0xf
	v_fmac_f32_e32 v135, v73, v79
	v_mul_f32_e32 v92, v72, v77
	v_mov_b32_dpp v90, v87 row_newbcast:0 row_mask:0xf bank_mask:0xf
	v_add_f32_dpp v92, v87, v92 row_newbcast:4 row_mask:0xf bank_mask:0xf
	v_add_f32_dpp v91, v87, v134 row_newbcast:8 row_mask:0xf bank_mask:0xf
	v_pk_fma_f32 v[138:139], v[46:47], v[90:91], v[138:139] op_sel_hi:[1,0,1] neg_lo:[0,1,0] neg_hi:[0,1,0]
	v_fma_f32 v92, -v90, v76, v92
	v_pk_fma_f32 v[140:141], v[48:49], v[90:91], v[140:141] op_sel_hi:[1,0,1] neg_lo:[0,1,0] neg_hi:[0,1,0]
	v_add_f32_dpp v93, v87, v135 row_newbcast:12 row_mask:0xf bank_mask:0xf
	v_pk_fma_f32 v[138:139], v[54:55], v[92:93], v[138:139] op_sel_hi:[1,0,1] neg_lo:[0,1,0] neg_hi:[0,1,0]
	v_pk_fma_f32 v[140:141], v[56:57], v[92:93], v[140:141] op_sel_hi:[1,0,1] neg_lo:[0,1,0] neg_hi:[0,1,0]
	s_waitcnt lgkmcnt(0)
	v_pk_mul_f32 v[82:83], v[138:139], v[6:7]
	v_fma_f32 v91, -v90, v74, v91
	v_pk_mul_f32 v[84:85], v[138:139], v[10:11]
	v_fma_f32 v93, -v90, v80, v93
	v_pk_mul_f32 v[86:87], v[138:139], v[14:15]
	v_fma_f32 v93, -v92, v78, v93
	v_pk_mul_f32 v[88:89], v[138:139], v[18:19]
	ds_write2_b32 v159, v91, v93 offset0:96 offset1:112
	v_pk_fma_f32 v[82:83], v[140:141], v[8:9], v[82:83]
	ds_read_b128 v[42:45], v0 offset:20480
	v_pk_fma_f32 v[84:85], v[140:141], v[12:13], v[84:85]
	ds_read_b128 v[46:49], v0 offset:20736
	v_pk_fma_f32 v[86:87], v[140:141], v[16:17], v[86:87]
	ds_read_b128 v[50:53], v0 offset:20992
	v_pk_fma_f32 v[88:89], v[140:141], v[20:21], v[88:89]
	ds_read_b128 v[54:57], v0 offset:21248
	v_pk_mul_f32 v[138:139], v[138:139], v[22:23]
	ds_read_b128 v[58:61], v0 offset:21504
	v_pk_mul_f32 v[140:141], v[140:141], v[24:25]
	ds_read2st64_b32 v[72:73], v158 offset0:85 offset1:86
	v_add_f32_e32 v82, v82, v83
	ds_read_b128 v[74:77], v123 offset:53408
	v_add_f32_e32 v84, v84, v85
	ds_read_b128 v[78:81], v123 offset:53424
	v_add_f32_e32 v86, v86, v87
	v_add_f32_e32 v88, v88, v89
	ds_read_b128 v[6:9], v0 offset:19456
	ds_read_b128 v[10:13], v0 offset:19712
	ds_read_b128 v[14:17], v0 offset:19968
	ds_read_b128 v[18:21], v0 offset:20224
	v_add_f32_dpp v83, v82, v82 row_mirror row_mask:0xf bank_mask:0xf
	v_add_f32_dpp v83, v84, v84 row_mirror row_mask:0xf bank_mask:0xc
	v_add_f32_dpp v85, v86, v86 row_mirror row_mask:0xf bank_mask:0xf
	v_add_f32_dpp v85, v88, v88 row_mirror row_mask:0xf bank_mask:0xc
	v_add_f32_dpp v87, v83, v83 row_half_mirror row_mask:0xf bank_mask:0xf
	v_pk_fma_f32 v[138:139], v[30:31], v[62:63], v[138:139] op_sel_hi:[1,0,1]
	v_pk_fma_f32 v[140:141], v[32:33], v[62:63], v[140:141] op_sel_hi:[1,0,1]
	v_add_f32_dpp v87, v85, v85 row_half_mirror row_mask:0xf bank_mask:0xa
	v_pk_fma_f32 v[138:139], v[38:39], v[62:63], v[138:139] op_sel:[0,1,0] op_sel_hi:[1,1,1]
	v_pk_fma_f32 v[140:141], v[40:41], v[62:63], v[140:141] op_sel:[0,1,0] op_sel_hi:[1,1,1]
	v_add_f32_dpp v87, v87, v87 quad_perm:[1,0,3,2] row_mask:0xf bank_mask:0xf
	v_mul_f32_e32 v134, v62, v65
	v_mul_f32_e32 v135, v62, v71
	v_add_f32_dpp v87, v87, v87 quad_perm:[2,3,0,1] row_mask:0xf bank_mask:0xf
	v_fmac_f32_e32 v135, v63, v69
	v_mul_f32_e32 v92, v62, v67
	v_mov_b32_dpp v90, v87 row_newbcast:0 row_mask:0xf bank_mask:0xf
	v_add_f32_dpp v92, v87, v92 row_newbcast:4 row_mask:0xf bank_mask:0xf
	v_add_f32_dpp v91, v87, v134 row_newbcast:8 row_mask:0xf bank_mask:0xf
	v_pk_fma_f32 v[138:139], v[26:27], v[90:91], v[138:139] op_sel_hi:[1,0,1] neg_lo:[0,1,0] neg_hi:[0,1,0]
	v_fma_f32 v92, -v90, v66, v92
	v_pk_fma_f32 v[140:141], v[28:29], v[90:91], v[140:141] op_sel_hi:[1,0,1] neg_lo:[0,1,0] neg_hi:[0,1,0]
	v_add_f32_dpp v93, v87, v135 row_newbcast:12 row_mask:0xf bank_mask:0xf
	v_pk_fma_f32 v[138:139], v[34:35], v[92:93], v[138:139] op_sel_hi:[1,0,1] neg_lo:[0,1,0] neg_hi:[0,1,0]
	v_pk_fma_f32 v[140:141], v[36:37], v[92:93], v[140:141] op_sel_hi:[1,0,1] neg_lo:[0,1,0] neg_hi:[0,1,0]
	s_waitcnt lgkmcnt(0)
	v_pk_mul_f32 v[82:83], v[138:139], v[6:7]
	v_fma_f32 v91, -v90, v64, v91
	v_pk_mul_f32 v[84:85], v[138:139], v[10:11]
	v_fma_f32 v93, -v90, v70, v93
	v_pk_mul_f32 v[86:87], v[138:139], v[14:15]
	v_fma_f32 v93, -v92, v68, v93
	v_pk_mul_f32 v[88:89], v[138:139], v[18:19]
	ds_write2_b32 v159, v91, v93 offset0:128 offset1:144
	v_pk_fma_f32 v[82:83], v[140:141], v[8:9], v[82:83]
	ds_read_b128 v[22:25], v0 offset:23552
	v_pk_fma_f32 v[84:85], v[140:141], v[12:13], v[84:85]
	ds_read_b128 v[26:29], v0 offset:23808
	v_pk_fma_f32 v[86:87], v[140:141], v[16:17], v[86:87]
	ds_read_b128 v[30:33], v0 offset:24064
	v_pk_fma_f32 v[88:89], v[140:141], v[20:21], v[88:89]
	ds_read_b128 v[34:37], v0 offset:24320
	v_pk_mul_f32 v[138:139], v[138:139], v[42:43]
	ds_read_b128 v[38:41], v0 offset:24576
	v_pk_mul_f32 v[140:141], v[140:141], v[44:45]
	ds_read2st64_b32 v[62:63], v158 offset0:97 offset1:98
	v_add_f32_e32 v82, v82, v83
	ds_read_b128 v[64:67], v123 offset:53440
	v_add_f32_e32 v84, v84, v85
	ds_read_b128 v[68:71], v123 offset:53456
	v_add_f32_e32 v86, v86, v87
	v_add_f32_e32 v88, v88, v89
	ds_read_b128 v[6:9], v0 offset:22528
	ds_read_b128 v[10:13], v0 offset:22784
	ds_read_b128 v[14:17], v0 offset:23040
	ds_read_b128 v[18:21], v0 offset:23296
	v_add_f32_dpp v83, v82, v82 row_mirror row_mask:0xf bank_mask:0xf
	v_add_f32_dpp v83, v84, v84 row_mirror row_mask:0xf bank_mask:0xc
	v_add_f32_dpp v85, v86, v86 row_mirror row_mask:0xf bank_mask:0xf
	v_add_f32_dpp v85, v88, v88 row_mirror row_mask:0xf bank_mask:0xc
	v_add_f32_dpp v87, v83, v83 row_half_mirror row_mask:0xf bank_mask:0xf
	v_pk_fma_f32 v[138:139], v[50:51], v[72:73], v[138:139] op_sel_hi:[1,0,1]
	v_pk_fma_f32 v[140:141], v[52:53], v[72:73], v[140:141] op_sel_hi:[1,0,1]
	v_add_f32_dpp v87, v85, v85 row_half_mirror row_mask:0xf bank_mask:0xa
	v_pk_fma_f32 v[138:139], v[58:59], v[72:73], v[138:139] op_sel:[0,1,0] op_sel_hi:[1,1,1]
	v_pk_fma_f32 v[140:141], v[60:61], v[72:73], v[140:141] op_sel:[0,1,0] op_sel_hi:[1,1,1]
	v_add_f32_dpp v87, v87, v87 quad_perm:[1,0,3,2] row_mask:0xf bank_mask:0xf
	v_mul_f32_e32 v134, v72, v75
	v_mul_f32_e32 v135, v72, v81
	v_add_f32_dpp v87, v87, v87 quad_perm:[2,3,0,1] row_mask:0xf bank_mask:0xf
	v_fmac_f32_e32 v135, v73, v79
	v_mul_f32_e32 v92, v72, v77
	v_mov_b32_dpp v90, v87 row_newbcast:0 row_mask:0xf bank_mask:0xf
	v_add_f32_dpp v92, v87, v92 row_newbcast:4 row_mask:0xf bank_mask:0xf
	v_add_f32_dpp v91, v87, v134 row_newbcast:8 row_mask:0xf bank_mask:0xf
	v_pk_fma_f32 v[138:139], v[46:47], v[90:91], v[138:139] op_sel_hi:[1,0,1] neg_lo:[0,1,0] neg_hi:[0,1,0]
	v_fma_f32 v92, -v90, v76, v92
	v_pk_fma_f32 v[140:141], v[48:49], v[90:91], v[140:141] op_sel_hi:[1,0,1] neg_lo:[0,1,0] neg_hi:[0,1,0]
	v_add_f32_dpp v93, v87, v135 row_newbcast:12 row_mask:0xf bank_mask:0xf
	v_pk_fma_f32 v[138:139], v[54:55], v[92:93], v[138:139] op_sel_hi:[1,0,1] neg_lo:[0,1,0] neg_hi:[0,1,0]
	v_pk_fma_f32 v[140:141], v[56:57], v[92:93], v[140:141] op_sel_hi:[1,0,1] neg_lo:[0,1,0] neg_hi:[0,1,0]
	s_waitcnt lgkmcnt(0)
	v_pk_mul_f32 v[82:83], v[138:139], v[6:7]
	v_fma_f32 v91, -v90, v74, v91
	v_pk_mul_f32 v[84:85], v[138:139], v[10:11]
	v_fma_f32 v93, -v90, v80, v93
	v_pk_mul_f32 v[86:87], v[138:139], v[14:15]
	v_fma_f32 v93, -v92, v78, v93
	v_pk_mul_f32 v[88:89], v[138:139], v[18:19]
	ds_write2_b32 v159, v91, v93 offset0:160 offset1:176
	v_pk_fma_f32 v[82:83], v[140:141], v[8:9], v[82:83]
	ds_read_b128 v[42:45], v0 offset:26624
	v_pk_fma_f32 v[84:85], v[140:141], v[12:13], v[84:85]
	ds_read_b128 v[46:49], v0 offset:26880
	v_pk_fma_f32 v[86:87], v[140:141], v[16:17], v[86:87]
	ds_read_b128 v[50:53], v0 offset:27136
	v_pk_fma_f32 v[88:89], v[140:141], v[20:21], v[88:89]
	ds_read_b128 v[54:57], v0 offset:27392
	v_pk_mul_f32 v[138:139], v[138:139], v[22:23]
	ds_read_b128 v[58:61], v0 offset:27648
	v_pk_mul_f32 v[140:141], v[140:141], v[24:25]
	ds_read2st64_b32 v[72:73], v158 offset0:109 offset1:110
	v_add_f32_e32 v82, v82, v83
	ds_read_b128 v[74:77], v123 offset:53472
	v_add_f32_e32 v84, v84, v85
	ds_read_b128 v[78:81], v123 offset:53488
	v_add_f32_e32 v86, v86, v87
	v_add_f32_e32 v88, v88, v89
	ds_read_b128 v[6:9], v0 offset:25600
	ds_read_b128 v[10:13], v0 offset:25856
	ds_read_b128 v[14:17], v0 offset:26112
	ds_read_b128 v[18:21], v0 offset:26368
	v_add_f32_dpp v83, v82, v82 row_mirror row_mask:0xf bank_mask:0xf
	v_add_f32_dpp v83, v84, v84 row_mirror row_mask:0xf bank_mask:0xc
	v_add_f32_dpp v85, v86, v86 row_mirror row_mask:0xf bank_mask:0xf
	v_add_f32_dpp v85, v88, v88 row_mirror row_mask:0xf bank_mask:0xc
	v_add_f32_dpp v87, v83, v83 row_half_mirror row_mask:0xf bank_mask:0xf
	v_pk_fma_f32 v[138:139], v[30:31], v[62:63], v[138:139] op_sel_hi:[1,0,1]
	v_pk_fma_f32 v[140:141], v[32:33], v[62:63], v[140:141] op_sel_hi:[1,0,1]
	v_add_f32_dpp v87, v85, v85 row_half_mirror row_mask:0xf bank_mask:0xa
	v_pk_fma_f32 v[138:139], v[38:39], v[62:63], v[138:139] op_sel:[0,1,0] op_sel_hi:[1,1,1]
	v_pk_fma_f32 v[140:141], v[40:41], v[62:63], v[140:141] op_sel:[0,1,0] op_sel_hi:[1,1,1]
	v_add_f32_dpp v87, v87, v87 quad_perm:[1,0,3,2] row_mask:0xf bank_mask:0xf
	v_mul_f32_e32 v134, v62, v65
	v_mul_f32_e32 v135, v62, v71
	v_add_f32_dpp v87, v87, v87 quad_perm:[2,3,0,1] row_mask:0xf bank_mask:0xf
	v_fmac_f32_e32 v135, v63, v69
	v_mul_f32_e32 v92, v62, v67
	v_mov_b32_dpp v90, v87 row_newbcast:0 row_mask:0xf bank_mask:0xf
	v_add_f32_dpp v92, v87, v92 row_newbcast:4 row_mask:0xf bank_mask:0xf
	v_add_f32_dpp v91, v87, v134 row_newbcast:8 row_mask:0xf bank_mask:0xf
	v_pk_fma_f32 v[138:139], v[26:27], v[90:91], v[138:139] op_sel_hi:[1,0,1] neg_lo:[0,1,0] neg_hi:[0,1,0]
	v_fma_f32 v92, -v90, v66, v92
	v_pk_fma_f32 v[140:141], v[28:29], v[90:91], v[140:141] op_sel_hi:[1,0,1] neg_lo:[0,1,0] neg_hi:[0,1,0]
	v_add_f32_dpp v93, v87, v135 row_newbcast:12 row_mask:0xf bank_mask:0xf
	v_pk_fma_f32 v[138:139], v[34:35], v[92:93], v[138:139] op_sel_hi:[1,0,1] neg_lo:[0,1,0] neg_hi:[0,1,0]
	v_pk_fma_f32 v[140:141], v[36:37], v[92:93], v[140:141] op_sel_hi:[1,0,1] neg_lo:[0,1,0] neg_hi:[0,1,0]
	s_waitcnt lgkmcnt(0)
	v_pk_mul_f32 v[82:83], v[138:139], v[6:7]
	v_fma_f32 v91, -v90, v64, v91
	v_pk_mul_f32 v[84:85], v[138:139], v[10:11]
	v_fma_f32 v93, -v90, v70, v93
	v_pk_mul_f32 v[86:87], v[138:139], v[14:15]
	v_fma_f32 v93, -v92, v68, v93
	v_pk_mul_f32 v[88:89], v[138:139], v[18:19]
	ds_write2_b32 v159, v91, v93 offset0:192 offset1:208
	v_pk_fma_f32 v[82:83], v[140:141], v[8:9], v[82:83]
	ds_read_b128 v[22:25], v0 offset:29696
	v_pk_fma_f32 v[84:85], v[140:141], v[12:13], v[84:85]
	ds_read_b128 v[26:29], v0 offset:29952
	v_pk_fma_f32 v[86:87], v[140:141], v[16:17], v[86:87]
	ds_read_b128 v[30:33], v0 offset:30208
	v_pk_fma_f32 v[88:89], v[140:141], v[20:21], v[88:89]
	ds_read_b128 v[34:37], v0 offset:30464
	v_pk_mul_f32 v[138:139], v[138:139], v[42:43]
	ds_read_b128 v[38:41], v0 offset:30720
	v_pk_mul_f32 v[140:141], v[140:141], v[44:45]
	ds_read2st64_b32 v[62:63], v158 offset0:121 offset1:122
	v_add_f32_e32 v82, v82, v83
	ds_read_b128 v[64:67], v123 offset:53504
	v_add_f32_e32 v84, v84, v85
	ds_read_b128 v[68:71], v123 offset:53520
	v_add_f32_e32 v86, v86, v87
	v_add_f32_e32 v88, v88, v89
	ds_read_b128 v[6:9], v0 offset:28672
	ds_read_b128 v[10:13], v0 offset:28928
	ds_read_b128 v[14:17], v0 offset:29184
	ds_read_b128 v[18:21], v0 offset:29440
	v_add_f32_dpp v83, v82, v82 row_mirror row_mask:0xf bank_mask:0xf
	v_add_f32_dpp v83, v84, v84 row_mirror row_mask:0xf bank_mask:0xc
	v_add_f32_dpp v85, v86, v86 row_mirror row_mask:0xf bank_mask:0xf
	v_add_f32_dpp v85, v88, v88 row_mirror row_mask:0xf bank_mask:0xc
	v_add_f32_dpp v87, v83, v83 row_half_mirror row_mask:0xf bank_mask:0xf
	v_pk_fma_f32 v[138:139], v[50:51], v[72:73], v[138:139] op_sel_hi:[1,0,1]
	v_pk_fma_f32 v[140:141], v[52:53], v[72:73], v[140:141] op_sel_hi:[1,0,1]
	v_add_f32_dpp v87, v85, v85 row_half_mirror row_mask:0xf bank_mask:0xa
	v_pk_fma_f32 v[138:139], v[58:59], v[72:73], v[138:139] op_sel:[0,1,0] op_sel_hi:[1,1,1]
	v_pk_fma_f32 v[140:141], v[60:61], v[72:73], v[140:141] op_sel:[0,1,0] op_sel_hi:[1,1,1]
	v_add_f32_dpp v87, v87, v87 quad_perm:[1,0,3,2] row_mask:0xf bank_mask:0xf
	v_mul_f32_e32 v134, v72, v75
	v_mul_f32_e32 v135, v72, v81
	v_add_f32_dpp v87, v87, v87 quad_perm:[2,3,0,1] row_mask:0xf bank_mask:0xf
	v_fmac_f32_e32 v135, v73, v79
	v_mul_f32_e32 v92, v72, v77
	v_mov_b32_dpp v90, v87 row_newbcast:0 row_mask:0xf bank_mask:0xf
	v_add_f32_dpp v92, v87, v92 row_newbcast:4 row_mask:0xf bank_mask:0xf
	v_add_f32_dpp v91, v87, v134 row_newbcast:8 row_mask:0xf bank_mask:0xf
	v_pk_fma_f32 v[138:139], v[46:47], v[90:91], v[138:139] op_sel_hi:[1,0,1] neg_lo:[0,1,0] neg_hi:[0,1,0]
	v_fma_f32 v92, -v90, v76, v92
	v_pk_fma_f32 v[140:141], v[48:49], v[90:91], v[140:141] op_sel_hi:[1,0,1] neg_lo:[0,1,0] neg_hi:[0,1,0]
	v_add_f32_dpp v93, v87, v135 row_newbcast:12 row_mask:0xf bank_mask:0xf
	v_pk_fma_f32 v[138:139], v[54:55], v[92:93], v[138:139] op_sel_hi:[1,0,1] neg_lo:[0,1,0] neg_hi:[0,1,0]
	v_pk_fma_f32 v[140:141], v[56:57], v[92:93], v[140:141] op_sel_hi:[1,0,1] neg_lo:[0,1,0] neg_hi:[0,1,0]
	s_waitcnt lgkmcnt(0)
	v_pk_mul_f32 v[82:83], v[138:139], v[6:7]
	v_fma_f32 v91, -v90, v74, v91
	v_pk_mul_f32 v[84:85], v[138:139], v[10:11]
	v_fma_f32 v93, -v90, v80, v93
	v_pk_mul_f32 v[86:87], v[138:139], v[14:15]
	v_fma_f32 v93, -v92, v78, v93
	v_pk_mul_f32 v[88:89], v[138:139], v[18:19]
	ds_write2_b32 v159, v91, v93 offset0:224 offset1:240
	v_pk_fma_f32 v[82:83], v[140:141], v[8:9], v[82:83]
	ds_read_b128 v[42:45], v0 offset:32768
	v_pk_fma_f32 v[84:85], v[140:141], v[12:13], v[84:85]
	ds_read_b128 v[46:49], v0 offset:33024
	v_pk_fma_f32 v[86:87], v[140:141], v[16:17], v[86:87]
	ds_read_b128 v[50:53], v0 offset:33280
	v_pk_fma_f32 v[88:89], v[140:141], v[20:21], v[88:89]
	ds_read_b128 v[54:57], v0 offset:33536
	v_pk_mul_f32 v[138:139], v[138:139], v[22:23]
	ds_read_b128 v[58:61], v0 offset:33792
	v_pk_mul_f32 v[140:141], v[140:141], v[24:25]
	ds_read2st64_b32 v[72:73], v158 offset0:133 offset1:134
	v_add_f32_e32 v82, v82, v83
	ds_read_b128 v[74:77], v123 offset:53536
	v_add_f32_e32 v84, v84, v85
	ds_read_b128 v[78:81], v123 offset:53552
	v_add_f32_e32 v86, v86, v87
	v_add_f32_e32 v88, v88, v89
	ds_read_b128 v[6:9], v0 offset:31744
	ds_read_b128 v[10:13], v0 offset:32000
	ds_read_b128 v[14:17], v0 offset:32256
	ds_read_b128 v[18:21], v0 offset:32512
	v_add_f32_dpp v83, v82, v82 row_mirror row_mask:0xf bank_mask:0xf
	v_add_f32_dpp v83, v84, v84 row_mirror row_mask:0xf bank_mask:0xc
	v_add_f32_dpp v85, v86, v86 row_mirror row_mask:0xf bank_mask:0xf
	v_add_f32_dpp v85, v88, v88 row_mirror row_mask:0xf bank_mask:0xc
	v_add_f32_dpp v87, v83, v83 row_half_mirror row_mask:0xf bank_mask:0xf
	v_pk_fma_f32 v[138:139], v[30:31], v[62:63], v[138:139] op_sel_hi:[1,0,1]
	v_pk_fma_f32 v[140:141], v[32:33], v[62:63], v[140:141] op_sel_hi:[1,0,1]
	v_add_f32_dpp v87, v85, v85 row_half_mirror row_mask:0xf bank_mask:0xa
	v_pk_fma_f32 v[138:139], v[38:39], v[62:63], v[138:139] op_sel:[0,1,0] op_sel_hi:[1,1,1]
	v_pk_fma_f32 v[140:141], v[40:41], v[62:63], v[140:141] op_sel:[0,1,0] op_sel_hi:[1,1,1]
	v_add_f32_dpp v87, v87, v87 quad_perm:[1,0,3,2] row_mask:0xf bank_mask:0xf
	v_mul_f32_e32 v134, v62, v65
	v_mul_f32_e32 v135, v62, v71
	v_add_f32_dpp v87, v87, v87 quad_perm:[2,3,0,1] row_mask:0xf bank_mask:0xf
	v_fmac_f32_e32 v135, v63, v69
	v_mul_f32_e32 v92, v62, v67
	v_mov_b32_dpp v90, v87 row_newbcast:0 row_mask:0xf bank_mask:0xf
	v_add_f32_dpp v92, v87, v92 row_newbcast:4 row_mask:0xf bank_mask:0xf
	v_add_f32_dpp v91, v87, v134 row_newbcast:8 row_mask:0xf bank_mask:0xf
	v_pk_fma_f32 v[138:139], v[26:27], v[90:91], v[138:139] op_sel_hi:[1,0,1] neg_lo:[0,1,0] neg_hi:[0,1,0]
	v_fma_f32 v92, -v90, v66, v92
	v_pk_fma_f32 v[140:141], v[28:29], v[90:91], v[140:141] op_sel_hi:[1,0,1] neg_lo:[0,1,0] neg_hi:[0,1,0]
	v_add_f32_dpp v93, v87, v135 row_newbcast:12 row_mask:0xf bank_mask:0xf
	v_pk_fma_f32 v[138:139], v[34:35], v[92:93], v[138:139] op_sel_hi:[1,0,1] neg_lo:[0,1,0] neg_hi:[0,1,0]
	v_pk_fma_f32 v[140:141], v[36:37], v[92:93], v[140:141] op_sel_hi:[1,0,1] neg_lo:[0,1,0] neg_hi:[0,1,0]
	s_waitcnt lgkmcnt(0)
	v_pk_mul_f32 v[82:83], v[138:139], v[6:7]
	v_fma_f32 v91, -v90, v64, v91
	v_pk_mul_f32 v[84:85], v[138:139], v[10:11]
	v_fma_f32 v93, -v90, v70, v93
	v_pk_mul_f32 v[86:87], v[138:139], v[14:15]
	v_fma_f32 v93, -v92, v68, v93
	v_pk_mul_f32 v[88:89], v[138:139], v[18:19]
	ds_write2_b32 v166, v91, v93 offset0:0 offset1:16
	v_pk_fma_f32 v[82:83], v[140:141], v[8:9], v[82:83]
	ds_read_b128 v[22:25], v0 offset:35840
	v_pk_fma_f32 v[84:85], v[140:141], v[12:13], v[84:85]
	ds_read_b128 v[26:29], v0 offset:36096
	v_pk_fma_f32 v[86:87], v[140:141], v[16:17], v[86:87]
	ds_read_b128 v[30:33], v0 offset:36352
	v_pk_fma_f32 v[88:89], v[140:141], v[20:21], v[88:89]
	ds_read_b128 v[34:37], v0 offset:36608
	v_pk_mul_f32 v[138:139], v[138:139], v[42:43]
	ds_read_b128 v[38:41], v0 offset:36864
	v_pk_mul_f32 v[140:141], v[140:141], v[44:45]
	ds_read2st64_b32 v[62:63], v158 offset0:145 offset1:146
	v_add_f32_e32 v82, v82, v83
	ds_read_b128 v[64:67], v123 offset:53568
	v_add_f32_e32 v84, v84, v85
	ds_read_b128 v[68:71], v123 offset:53584
	v_add_f32_e32 v86, v86, v87
	v_add_f32_e32 v88, v88, v89
	ds_read_b128 v[6:9], v0 offset:34816
	ds_read_b128 v[10:13], v0 offset:35072
	ds_read_b128 v[14:17], v0 offset:35328
	ds_read_b128 v[18:21], v0 offset:35584
	v_add_f32_dpp v83, v82, v82 row_mirror row_mask:0xf bank_mask:0xf
	v_add_f32_dpp v83, v84, v84 row_mirror row_mask:0xf bank_mask:0xc
	v_add_f32_dpp v85, v86, v86 row_mirror row_mask:0xf bank_mask:0xf
	v_add_f32_dpp v85, v88, v88 row_mirror row_mask:0xf bank_mask:0xc
	v_add_f32_dpp v87, v83, v83 row_half_mirror row_mask:0xf bank_mask:0xf
	v_pk_fma_f32 v[138:139], v[50:51], v[72:73], v[138:139] op_sel_hi:[1,0,1]
	v_pk_fma_f32 v[140:141], v[52:53], v[72:73], v[140:141] op_sel_hi:[1,0,1]
	v_add_f32_dpp v87, v85, v85 row_half_mirror row_mask:0xf bank_mask:0xa
	v_pk_fma_f32 v[138:139], v[58:59], v[72:73], v[138:139] op_sel:[0,1,0] op_sel_hi:[1,1,1]
	v_pk_fma_f32 v[140:141], v[60:61], v[72:73], v[140:141] op_sel:[0,1,0] op_sel_hi:[1,1,1]
	v_add_f32_dpp v87, v87, v87 quad_perm:[1,0,3,2] row_mask:0xf bank_mask:0xf
	v_mul_f32_e32 v134, v72, v75
	v_mul_f32_e32 v135, v72, v81
	v_add_f32_dpp v87, v87, v87 quad_perm:[2,3,0,1] row_mask:0xf bank_mask:0xf
	v_fmac_f32_e32 v135, v73, v79
	v_mul_f32_e32 v92, v72, v77
	v_mov_b32_dpp v90, v87 row_newbcast:0 row_mask:0xf bank_mask:0xf
	v_add_f32_dpp v92, v87, v92 row_newbcast:4 row_mask:0xf bank_mask:0xf
	v_add_f32_dpp v91, v87, v134 row_newbcast:8 row_mask:0xf bank_mask:0xf
	v_pk_fma_f32 v[138:139], v[46:47], v[90:91], v[138:139] op_sel_hi:[1,0,1] neg_lo:[0,1,0] neg_hi:[0,1,0]
	v_fma_f32 v92, -v90, v76, v92
	v_pk_fma_f32 v[140:141], v[48:49], v[90:91], v[140:141] op_sel_hi:[1,0,1] neg_lo:[0,1,0] neg_hi:[0,1,0]
	v_add_f32_dpp v93, v87, v135 row_newbcast:12 row_mask:0xf bank_mask:0xf
	v_pk_fma_f32 v[138:139], v[54:55], v[92:93], v[138:139] op_sel_hi:[1,0,1] neg_lo:[0,1,0] neg_hi:[0,1,0]
	v_pk_fma_f32 v[140:141], v[56:57], v[92:93], v[140:141] op_sel_hi:[1,0,1] neg_lo:[0,1,0] neg_hi:[0,1,0]
	s_waitcnt lgkmcnt(0)
	v_pk_mul_f32 v[82:83], v[138:139], v[6:7]
	v_fma_f32 v91, -v90, v74, v91
	v_pk_mul_f32 v[84:85], v[138:139], v[10:11]
	v_fma_f32 v93, -v90, v80, v93
	v_pk_mul_f32 v[86:87], v[138:139], v[14:15]
	v_fma_f32 v93, -v92, v78, v93
	v_pk_mul_f32 v[88:89], v[138:139], v[18:19]
	ds_write2_b32 v166, v91, v93 offset0:32 offset1:48
	v_pk_fma_f32 v[82:83], v[140:141], v[8:9], v[82:83]
	ds_read_b128 v[42:45], v0 offset:38912
	v_pk_fma_f32 v[84:85], v[140:141], v[12:13], v[84:85]
	ds_read_b128 v[46:49], v0 offset:39168
	v_pk_fma_f32 v[86:87], v[140:141], v[16:17], v[86:87]
	ds_read_b128 v[50:53], v0 offset:39424
	v_pk_fma_f32 v[88:89], v[140:141], v[20:21], v[88:89]
	ds_read_b128 v[54:57], v0 offset:39680
	v_pk_mul_f32 v[138:139], v[138:139], v[22:23]
	ds_read_b128 v[58:61], v0 offset:39936
	v_pk_mul_f32 v[140:141], v[140:141], v[24:25]
	ds_read2st64_b32 v[72:73], v158 offset0:157 offset1:158
	v_add_f32_e32 v82, v82, v83
	ds_read_b128 v[74:77], v123 offset:53600
	v_add_f32_e32 v84, v84, v85
	ds_read_b128 v[78:81], v123 offset:53616
	v_add_f32_e32 v86, v86, v87
	v_add_f32_e32 v88, v88, v89
	ds_read_b128 v[6:9], v0 offset:37888
	ds_read_b128 v[10:13], v0 offset:38144
	ds_read_b128 v[14:17], v0 offset:38400
	ds_read_b128 v[18:21], v0 offset:38656
	v_add_f32_dpp v83, v82, v82 row_mirror row_mask:0xf bank_mask:0xf
	v_add_f32_dpp v83, v84, v84 row_mirror row_mask:0xf bank_mask:0xc
	v_add_f32_dpp v85, v86, v86 row_mirror row_mask:0xf bank_mask:0xf
	v_add_f32_dpp v85, v88, v88 row_mirror row_mask:0xf bank_mask:0xc
	v_add_f32_dpp v87, v83, v83 row_half_mirror row_mask:0xf bank_mask:0xf
	v_pk_fma_f32 v[138:139], v[30:31], v[62:63], v[138:139] op_sel_hi:[1,0,1]
	v_pk_fma_f32 v[140:141], v[32:33], v[62:63], v[140:141] op_sel_hi:[1,0,1]
	v_add_f32_dpp v87, v85, v85 row_half_mirror row_mask:0xf bank_mask:0xa
	v_pk_fma_f32 v[138:139], v[38:39], v[62:63], v[138:139] op_sel:[0,1,0] op_sel_hi:[1,1,1]
	v_pk_fma_f32 v[140:141], v[40:41], v[62:63], v[140:141] op_sel:[0,1,0] op_sel_hi:[1,1,1]
	v_add_f32_dpp v87, v87, v87 quad_perm:[1,0,3,2] row_mask:0xf bank_mask:0xf
	v_mul_f32_e32 v134, v62, v65
	v_mul_f32_e32 v135, v62, v71
	v_add_f32_dpp v87, v87, v87 quad_perm:[2,3,0,1] row_mask:0xf bank_mask:0xf
	v_fmac_f32_e32 v135, v63, v69
	v_mul_f32_e32 v92, v62, v67
	v_mov_b32_dpp v90, v87 row_newbcast:0 row_mask:0xf bank_mask:0xf
	v_add_f32_dpp v92, v87, v92 row_newbcast:4 row_mask:0xf bank_mask:0xf
	v_add_f32_dpp v91, v87, v134 row_newbcast:8 row_mask:0xf bank_mask:0xf
	v_pk_fma_f32 v[138:139], v[26:27], v[90:91], v[138:139] op_sel_hi:[1,0,1] neg_lo:[0,1,0] neg_hi:[0,1,0]
	v_fma_f32 v92, -v90, v66, v92
	v_pk_fma_f32 v[140:141], v[28:29], v[90:91], v[140:141] op_sel_hi:[1,0,1] neg_lo:[0,1,0] neg_hi:[0,1,0]
	v_add_f32_dpp v93, v87, v135 row_newbcast:12 row_mask:0xf bank_mask:0xf
	v_pk_fma_f32 v[138:139], v[34:35], v[92:93], v[138:139] op_sel_hi:[1,0,1] neg_lo:[0,1,0] neg_hi:[0,1,0]
	v_pk_fma_f32 v[140:141], v[36:37], v[92:93], v[140:141] op_sel_hi:[1,0,1] neg_lo:[0,1,0] neg_hi:[0,1,0]
	s_waitcnt lgkmcnt(0)
	v_pk_mul_f32 v[82:83], v[138:139], v[6:7]
	v_fma_f32 v91, -v90, v64, v91
	v_pk_mul_f32 v[84:85], v[138:139], v[10:11]
	v_fma_f32 v93, -v90, v70, v93
	v_pk_mul_f32 v[86:87], v[138:139], v[14:15]
	v_fma_f32 v93, -v92, v68, v93
	v_pk_mul_f32 v[88:89], v[138:139], v[18:19]
	ds_write2_b32 v166, v91, v93 offset0:64 offset1:80
	v_pk_fma_f32 v[82:83], v[140:141], v[8:9], v[82:83]
	ds_read_b128 v[22:25], v0 offset:41984
	v_pk_fma_f32 v[84:85], v[140:141], v[12:13], v[84:85]
	ds_read_b128 v[26:29], v0 offset:42240
	v_pk_fma_f32 v[86:87], v[140:141], v[16:17], v[86:87]
	ds_read_b128 v[30:33], v0 offset:42496
	v_pk_fma_f32 v[88:89], v[140:141], v[20:21], v[88:89]
	ds_read_b128 v[34:37], v0 offset:42752
	v_pk_mul_f32 v[138:139], v[138:139], v[42:43]
	ds_read_b128 v[38:41], v0 offset:43008
	v_pk_mul_f32 v[140:141], v[140:141], v[44:45]
	ds_read2st64_b32 v[62:63], v158 offset0:169 offset1:170
	v_add_f32_e32 v82, v82, v83
	ds_read_b128 v[64:67], v123 offset:53632
	v_add_f32_e32 v84, v84, v85
	ds_read_b128 v[68:71], v123 offset:53648
	v_add_f32_e32 v86, v86, v87
	v_add_f32_e32 v88, v88, v89
	ds_read_b128 v[6:9], v0 offset:40960
	ds_read_b128 v[10:13], v0 offset:41216
	ds_read_b128 v[14:17], v0 offset:41472
	ds_read_b128 v[18:21], v0 offset:41728
	v_add_f32_dpp v83, v82, v82 row_mirror row_mask:0xf bank_mask:0xf
	v_add_f32_dpp v83, v84, v84 row_mirror row_mask:0xf bank_mask:0xc
	v_add_f32_dpp v85, v86, v86 row_mirror row_mask:0xf bank_mask:0xf
	v_add_f32_dpp v85, v88, v88 row_mirror row_mask:0xf bank_mask:0xc
	v_add_f32_dpp v87, v83, v83 row_half_mirror row_mask:0xf bank_mask:0xf
	v_pk_fma_f32 v[138:139], v[50:51], v[72:73], v[138:139] op_sel_hi:[1,0,1]
	v_pk_fma_f32 v[140:141], v[52:53], v[72:73], v[140:141] op_sel_hi:[1,0,1]
	v_add_f32_dpp v87, v85, v85 row_half_mirror row_mask:0xf bank_mask:0xa
	v_pk_fma_f32 v[138:139], v[58:59], v[72:73], v[138:139] op_sel:[0,1,0] op_sel_hi:[1,1,1]
	v_pk_fma_f32 v[140:141], v[60:61], v[72:73], v[140:141] op_sel:[0,1,0] op_sel_hi:[1,1,1]
	v_add_f32_dpp v87, v87, v87 quad_perm:[1,0,3,2] row_mask:0xf bank_mask:0xf
	v_mul_f32_e32 v134, v72, v75
	v_mul_f32_e32 v135, v72, v81
	v_add_f32_dpp v87, v87, v87 quad_perm:[2,3,0,1] row_mask:0xf bank_mask:0xf
	v_fmac_f32_e32 v135, v73, v79
	v_mul_f32_e32 v92, v72, v77
	v_mov_b32_dpp v90, v87 row_newbcast:0 row_mask:0xf bank_mask:0xf
	v_add_f32_dpp v92, v87, v92 row_newbcast:4 row_mask:0xf bank_mask:0xf
	v_add_f32_dpp v91, v87, v134 row_newbcast:8 row_mask:0xf bank_mask:0xf
	v_pk_fma_f32 v[138:139], v[46:47], v[90:91], v[138:139] op_sel_hi:[1,0,1] neg_lo:[0,1,0] neg_hi:[0,1,0]
	v_fma_f32 v92, -v90, v76, v92
	v_pk_fma_f32 v[140:141], v[48:49], v[90:91], v[140:141] op_sel_hi:[1,0,1] neg_lo:[0,1,0] neg_hi:[0,1,0]
	v_add_f32_dpp v93, v87, v135 row_newbcast:12 row_mask:0xf bank_mask:0xf
	v_pk_fma_f32 v[138:139], v[54:55], v[92:93], v[138:139] op_sel_hi:[1,0,1] neg_lo:[0,1,0] neg_hi:[0,1,0]
	v_pk_fma_f32 v[140:141], v[56:57], v[92:93], v[140:141] op_sel_hi:[1,0,1] neg_lo:[0,1,0] neg_hi:[0,1,0]
	s_waitcnt lgkmcnt(0)
	v_pk_mul_f32 v[82:83], v[138:139], v[6:7]
	v_fma_f32 v91, -v90, v74, v91
	v_pk_mul_f32 v[84:85], v[138:139], v[10:11]
	v_fma_f32 v93, -v90, v80, v93
	v_pk_mul_f32 v[86:87], v[138:139], v[14:15]
	v_fma_f32 v93, -v92, v78, v93
	v_pk_mul_f32 v[88:89], v[138:139], v[18:19]
	ds_write2_b32 v166, v91, v93 offset0:96 offset1:112
	v_pk_fma_f32 v[82:83], v[140:141], v[8:9], v[82:83]
	ds_read_b128 v[42:45], v0 offset:45056
	v_pk_fma_f32 v[84:85], v[140:141], v[12:13], v[84:85]
	ds_read_b128 v[46:49], v0 offset:45312
	v_pk_fma_f32 v[86:87], v[140:141], v[16:17], v[86:87]
	ds_read_b128 v[50:53], v0 offset:45568
	v_pk_fma_f32 v[88:89], v[140:141], v[20:21], v[88:89]
	ds_read_b128 v[54:57], v0 offset:45824
	v_pk_mul_f32 v[138:139], v[138:139], v[22:23]
	ds_read_b128 v[58:61], v0 offset:46080
	v_pk_mul_f32 v[140:141], v[140:141], v[24:25]
	ds_read2st64_b32 v[72:73], v158 offset0:181 offset1:182
	v_add_f32_e32 v82, v82, v83
	ds_read_b128 v[74:77], v123 offset:53664
	v_add_f32_e32 v84, v84, v85
	ds_read_b128 v[78:81], v123 offset:53680
	v_add_f32_e32 v86, v86, v87
	v_add_f32_e32 v88, v88, v89
	ds_read_b128 v[6:9], v0 offset:44032
	ds_read_b128 v[10:13], v0 offset:44288
	ds_read_b128 v[14:17], v0 offset:44544
	ds_read_b128 v[18:21], v0 offset:44800
	v_add_f32_dpp v83, v82, v82 row_mirror row_mask:0xf bank_mask:0xf
	v_add_f32_dpp v83, v84, v84 row_mirror row_mask:0xf bank_mask:0xc
	v_add_f32_dpp v85, v86, v86 row_mirror row_mask:0xf bank_mask:0xf
	v_add_f32_dpp v85, v88, v88 row_mirror row_mask:0xf bank_mask:0xc
	v_add_f32_dpp v87, v83, v83 row_half_mirror row_mask:0xf bank_mask:0xf
	v_pk_fma_f32 v[138:139], v[30:31], v[62:63], v[138:139] op_sel_hi:[1,0,1]
	v_pk_fma_f32 v[140:141], v[32:33], v[62:63], v[140:141] op_sel_hi:[1,0,1]
	v_add_f32_dpp v87, v85, v85 row_half_mirror row_mask:0xf bank_mask:0xa
	v_pk_fma_f32 v[138:139], v[38:39], v[62:63], v[138:139] op_sel:[0,1,0] op_sel_hi:[1,1,1]
	v_pk_fma_f32 v[140:141], v[40:41], v[62:63], v[140:141] op_sel:[0,1,0] op_sel_hi:[1,1,1]
	v_add_f32_dpp v87, v87, v87 quad_perm:[1,0,3,2] row_mask:0xf bank_mask:0xf
	v_mul_f32_e32 v134, v62, v65
	v_mul_f32_e32 v135, v62, v71
	v_add_f32_dpp v87, v87, v87 quad_perm:[2,3,0,1] row_mask:0xf bank_mask:0xf
	v_fmac_f32_e32 v135, v63, v69
	v_mul_f32_e32 v92, v62, v67
	v_mov_b32_dpp v90, v87 row_newbcast:0 row_mask:0xf bank_mask:0xf
	v_add_f32_dpp v92, v87, v92 row_newbcast:4 row_mask:0xf bank_mask:0xf
	v_add_f32_dpp v91, v87, v134 row_newbcast:8 row_mask:0xf bank_mask:0xf
	v_pk_fma_f32 v[138:139], v[26:27], v[90:91], v[138:139] op_sel_hi:[1,0,1] neg_lo:[0,1,0] neg_hi:[0,1,0]
	v_fma_f32 v92, -v90, v66, v92
	v_pk_fma_f32 v[140:141], v[28:29], v[90:91], v[140:141] op_sel_hi:[1,0,1] neg_lo:[0,1,0] neg_hi:[0,1,0]
	v_add_f32_dpp v93, v87, v135 row_newbcast:12 row_mask:0xf bank_mask:0xf
	v_pk_fma_f32 v[138:139], v[34:35], v[92:93], v[138:139] op_sel_hi:[1,0,1] neg_lo:[0,1,0] neg_hi:[0,1,0]
	v_pk_fma_f32 v[140:141], v[36:37], v[92:93], v[140:141] op_sel_hi:[1,0,1] neg_lo:[0,1,0] neg_hi:[0,1,0]
	s_waitcnt lgkmcnt(0)
	v_pk_mul_f32 v[82:83], v[138:139], v[6:7]
	v_fma_f32 v91, -v90, v64, v91
	v_pk_mul_f32 v[84:85], v[138:139], v[10:11]
	v_fma_f32 v93, -v90, v70, v93
	v_pk_mul_f32 v[86:87], v[138:139], v[14:15]
	v_fma_f32 v93, -v92, v68, v93
	v_pk_mul_f32 v[88:89], v[138:139], v[18:19]
	ds_write2_b32 v166, v91, v93 offset0:128 offset1:144
	v_pk_fma_f32 v[82:83], v[140:141], v[8:9], v[82:83]
	ds_read_b128 v[22:25], v0 offset:48128
	v_pk_fma_f32 v[84:85], v[140:141], v[12:13], v[84:85]
	ds_read_b128 v[26:29], v0 offset:48384
	v_pk_fma_f32 v[86:87], v[140:141], v[16:17], v[86:87]
	ds_read_b128 v[30:33], v0 offset:48640
	v_pk_fma_f32 v[88:89], v[140:141], v[20:21], v[88:89]
	ds_read_b128 v[34:37], v0 offset:48896
	v_pk_mul_f32 v[138:139], v[138:139], v[42:43]
	ds_read_b128 v[38:41], v0 offset:49152
	v_pk_mul_f32 v[140:141], v[140:141], v[44:45]
	ds_read2st64_b32 v[62:63], v158 offset0:193 offset1:194
	v_add_f32_e32 v82, v82, v83
	ds_read_b128 v[64:67], v123 offset:53696
	v_add_f32_e32 v84, v84, v85
	ds_read_b128 v[68:71], v123 offset:53712
	v_add_f32_e32 v86, v86, v87
	v_add_f32_e32 v88, v88, v89
	ds_read_b128 v[6:9], v0 offset:47104
	ds_read_b128 v[10:13], v0 offset:47360
	ds_read_b128 v[14:17], v0 offset:47616
	ds_read_b128 v[18:21], v0 offset:47872
	v_add_f32_dpp v83, v82, v82 row_mirror row_mask:0xf bank_mask:0xf
	v_add_f32_dpp v83, v84, v84 row_mirror row_mask:0xf bank_mask:0xc
	v_add_f32_dpp v85, v86, v86 row_mirror row_mask:0xf bank_mask:0xf
	v_add_f32_dpp v85, v88, v88 row_mirror row_mask:0xf bank_mask:0xc
	v_add_f32_dpp v87, v83, v83 row_half_mirror row_mask:0xf bank_mask:0xf
	v_pk_fma_f32 v[138:139], v[50:51], v[72:73], v[138:139] op_sel_hi:[1,0,1]
	v_pk_fma_f32 v[140:141], v[52:53], v[72:73], v[140:141] op_sel_hi:[1,0,1]
	v_add_f32_dpp v87, v85, v85 row_half_mirror row_mask:0xf bank_mask:0xa
	v_pk_fma_f32 v[138:139], v[58:59], v[72:73], v[138:139] op_sel:[0,1,0] op_sel_hi:[1,1,1]
	v_pk_fma_f32 v[140:141], v[60:61], v[72:73], v[140:141] op_sel:[0,1,0] op_sel_hi:[1,1,1]
	v_add_f32_dpp v87, v87, v87 quad_perm:[1,0,3,2] row_mask:0xf bank_mask:0xf
	v_mul_f32_e32 v134, v72, v75
	v_mul_f32_e32 v135, v72, v81
	v_add_f32_dpp v87, v87, v87 quad_perm:[2,3,0,1] row_mask:0xf bank_mask:0xf
	v_fmac_f32_e32 v135, v73, v79
	v_mul_f32_e32 v92, v72, v77
	v_mov_b32_dpp v90, v87 row_newbcast:0 row_mask:0xf bank_mask:0xf
	v_add_f32_dpp v92, v87, v92 row_newbcast:4 row_mask:0xf bank_mask:0xf
	v_add_f32_dpp v91, v87, v134 row_newbcast:8 row_mask:0xf bank_mask:0xf
	v_pk_fma_f32 v[138:139], v[46:47], v[90:91], v[138:139] op_sel_hi:[1,0,1] neg_lo:[0,1,0] neg_hi:[0,1,0]
	v_fma_f32 v92, -v90, v76, v92
	v_pk_fma_f32 v[140:141], v[48:49], v[90:91], v[140:141] op_sel_hi:[1,0,1] neg_lo:[0,1,0] neg_hi:[0,1,0]
	v_add_f32_dpp v93, v87, v135 row_newbcast:12 row_mask:0xf bank_mask:0xf
	v_pk_fma_f32 v[138:139], v[54:55], v[92:93], v[138:139] op_sel_hi:[1,0,1] neg_lo:[0,1,0] neg_hi:[0,1,0]
	v_pk_fma_f32 v[140:141], v[56:57], v[92:93], v[140:141] op_sel_hi:[1,0,1] neg_lo:[0,1,0] neg_hi:[0,1,0]
	s_waitcnt lgkmcnt(0)
	v_pk_mul_f32 v[82:83], v[138:139], v[6:7]
	v_fma_f32 v91, -v90, v74, v91
	v_pk_mul_f32 v[84:85], v[138:139], v[10:11]
	v_fma_f32 v93, -v90, v80, v93
	v_pk_mul_f32 v[86:87], v[138:139], v[14:15]
	v_fma_f32 v93, -v92, v78, v93
	v_pk_mul_f32 v[88:89], v[138:139], v[18:19]
	ds_write2_b32 v166, v91, v93 offset0:160 offset1:176
	v_pk_fma_f32 v[82:83], v[140:141], v[8:9], v[82:83]
	ds_read_b128 v[42:45], v0 offset:51200
	v_pk_fma_f32 v[84:85], v[140:141], v[12:13], v[84:85]
	ds_read_b128 v[46:49], v0 offset:51456
	v_pk_fma_f32 v[86:87], v[140:141], v[16:17], v[86:87]
	ds_read_b128 v[50:53], v0 offset:51712
	v_pk_fma_f32 v[88:89], v[140:141], v[20:21], v[88:89]
	ds_read_b128 v[54:57], v0 offset:51968
	v_pk_mul_f32 v[138:139], v[138:139], v[22:23]
	ds_read_b128 v[58:61], v0 offset:52224
	v_pk_mul_f32 v[140:141], v[140:141], v[24:25]
	ds_read2st64_b32 v[72:73], v158 offset0:205 offset1:206
	v_add_f32_e32 v82, v82, v83
	ds_read_b128 v[74:77], v123 offset:53728
	v_add_f32_e32 v84, v84, v85
	ds_read_b128 v[78:81], v123 offset:53744
	v_add_f32_e32 v86, v86, v87
	v_add_f32_e32 v88, v88, v89
	ds_read_b128 v[6:9], v0 offset:50176
	ds_read_b128 v[10:13], v0 offset:50432
	ds_read_b128 v[14:17], v0 offset:50688
	ds_read_b128 v[18:21], v0 offset:50944
	v_add_f32_dpp v83, v82, v82 row_mirror row_mask:0xf bank_mask:0xf
	v_add_f32_dpp v83, v84, v84 row_mirror row_mask:0xf bank_mask:0xc
	v_add_f32_dpp v85, v86, v86 row_mirror row_mask:0xf bank_mask:0xf
	v_add_f32_dpp v85, v88, v88 row_mirror row_mask:0xf bank_mask:0xc
	v_add_f32_dpp v87, v83, v83 row_half_mirror row_mask:0xf bank_mask:0xf
	v_pk_fma_f32 v[138:139], v[30:31], v[62:63], v[138:139] op_sel_hi:[1,0,1]
	v_pk_fma_f32 v[140:141], v[32:33], v[62:63], v[140:141] op_sel_hi:[1,0,1]
	v_add_f32_dpp v87, v85, v85 row_half_mirror row_mask:0xf bank_mask:0xa
	v_pk_fma_f32 v[138:139], v[38:39], v[62:63], v[138:139] op_sel:[0,1,0] op_sel_hi:[1,1,1]
	v_pk_fma_f32 v[140:141], v[40:41], v[62:63], v[140:141] op_sel:[0,1,0] op_sel_hi:[1,1,1]
	v_add_f32_dpp v87, v87, v87 quad_perm:[1,0,3,2] row_mask:0xf bank_mask:0xf
	v_mul_f32_e32 v134, v62, v65
	v_mul_f32_e32 v135, v62, v71
	v_add_f32_dpp v87, v87, v87 quad_perm:[2,3,0,1] row_mask:0xf bank_mask:0xf
	v_fmac_f32_e32 v135, v63, v69
	v_mul_f32_e32 v92, v62, v67
	v_mov_b32_dpp v90, v87 row_newbcast:0 row_mask:0xf bank_mask:0xf
	v_add_f32_dpp v92, v87, v92 row_newbcast:4 row_mask:0xf bank_mask:0xf
	v_add_f32_dpp v91, v87, v134 row_newbcast:8 row_mask:0xf bank_mask:0xf
	v_pk_fma_f32 v[138:139], v[26:27], v[90:91], v[138:139] op_sel_hi:[1,0,1] neg_lo:[0,1,0] neg_hi:[0,1,0]
	v_fma_f32 v92, -v90, v66, v92
	v_pk_fma_f32 v[140:141], v[28:29], v[90:91], v[140:141] op_sel_hi:[1,0,1] neg_lo:[0,1,0] neg_hi:[0,1,0]
	v_add_f32_dpp v93, v87, v135 row_newbcast:12 row_mask:0xf bank_mask:0xf
	v_pk_fma_f32 v[138:139], v[34:35], v[92:93], v[138:139] op_sel_hi:[1,0,1] neg_lo:[0,1,0] neg_hi:[0,1,0]
	v_pk_fma_f32 v[140:141], v[36:37], v[92:93], v[140:141] op_sel_hi:[1,0,1] neg_lo:[0,1,0] neg_hi:[0,1,0]
	s_waitcnt lgkmcnt(0)
	v_pk_mul_f32 v[82:83], v[138:139], v[6:7]
	v_fma_f32 v91, -v90, v64, v91
	v_pk_mul_f32 v[84:85], v[138:139], v[10:11]
	v_fma_f32 v93, -v90, v70, v93
	v_pk_mul_f32 v[86:87], v[138:139], v[14:15]
	v_fma_f32 v93, -v92, v68, v93
	v_pk_mul_f32 v[88:89], v[138:139], v[18:19]
	ds_write2_b32 v166, v91, v93 offset0:192 offset1:208
	v_pk_fma_f32 v[82:83], v[140:141], v[8:9], v[82:83]
	v_pk_fma_f32 v[84:85], v[140:141], v[12:13], v[84:85]
	v_pk_fma_f32 v[86:87], v[140:141], v[16:17], v[86:87]
	v_pk_fma_f32 v[88:89], v[140:141], v[20:21], v[88:89]
	v_pk_mul_f32 v[138:139], v[138:139], v[42:43]
	v_pk_mul_f32 v[140:141], v[140:141], v[44:45]
	v_add_f32_e32 v82, v82, v83
	v_add_f32_e32 v84, v84, v85
	v_add_f32_e32 v86, v86, v87
	v_add_f32_e32 v88, v88, v89
	v_add_f32_dpp v83, v82, v82 row_mirror row_mask:0xf bank_mask:0xf
	v_add_f32_dpp v83, v84, v84 row_mirror row_mask:0xf bank_mask:0xc
	v_add_f32_dpp v85, v86, v86 row_mirror row_mask:0xf bank_mask:0xf
	v_add_f32_dpp v85, v88, v88 row_mirror row_mask:0xf bank_mask:0xc
	v_add_f32_dpp v87, v83, v83 row_half_mirror row_mask:0xf bank_mask:0xf
	v_pk_fma_f32 v[138:139], v[50:51], v[72:73], v[138:139] op_sel_hi:[1,0,1]
	v_pk_fma_f32 v[140:141], v[52:53], v[72:73], v[140:141] op_sel_hi:[1,0,1]
	v_add_f32_dpp v87, v85, v85 row_half_mirror row_mask:0xf bank_mask:0xa
	v_pk_fma_f32 v[138:139], v[58:59], v[72:73], v[138:139] op_sel:[0,1,0] op_sel_hi:[1,1,1]
	v_pk_fma_f32 v[140:141], v[60:61], v[72:73], v[140:141] op_sel:[0,1,0] op_sel_hi:[1,1,1]
	v_add_f32_dpp v87, v87, v87 quad_perm:[1,0,3,2] row_mask:0xf bank_mask:0xf
	v_mul_f32_e32 v134, v72, v75
	v_mul_f32_e32 v135, v72, v81
	v_add_f32_dpp v87, v87, v87 quad_perm:[2,3,0,1] row_mask:0xf bank_mask:0xf
	v_fmac_f32_e32 v135, v73, v79
	v_mul_f32_e32 v92, v72, v77
	v_mov_b32_dpp v90, v87 row_newbcast:0 row_mask:0xf bank_mask:0xf
	v_add_f32_dpp v92, v87, v92 row_newbcast:4 row_mask:0xf bank_mask:0xf
	v_add_f32_dpp v91, v87, v134 row_newbcast:8 row_mask:0xf bank_mask:0xf
	v_pk_fma_f32 v[138:139], v[46:47], v[90:91], v[138:139] op_sel_hi:[1,0,1] neg_lo:[0,1,0] neg_hi:[0,1,0]
	v_fma_f32 v92, -v90, v76, v92
	v_pk_fma_f32 v[140:141], v[48:49], v[90:91], v[140:141] op_sel_hi:[1,0,1] neg_lo:[0,1,0] neg_hi:[0,1,0]
	v_add_f32_dpp v93, v87, v135 row_newbcast:12 row_mask:0xf bank_mask:0xf
	v_pk_fma_f32 v[138:139], v[54:55], v[92:93], v[138:139] op_sel_hi:[1,0,1] neg_lo:[0,1,0] neg_hi:[0,1,0]
	v_pk_fma_f32 v[140:141], v[56:57], v[92:93], v[140:141] op_sel_hi:[1,0,1] neg_lo:[0,1,0] neg_hi:[0,1,0]
	v_fma_f32 v91, -v90, v74, v91
	v_fma_f32 v93, -v90, v80, v93
	v_fma_f32 v93, -v92, v78, v93
	ds_write2_b32 v166, v91, v93 offset0:224 offset1:240

.LBB0_883:
	s_mul_hi_i32 s22, s14, 0x2e8ba2e9
	s_lshr_b32 s23, s22, 31
	s_ashr_i32 s22, s22, 4
	s_add_i32 s23, s22, s23
	s_mul_i32 s22, s23, 0xffffea00
	s_add_i32 s26, s22, s6
	v_add_u32_e32 v8, s26, v2
	s_lshl_b32 s22, s23, 6
	v_ashrrev_i32_e32 v9, 31, v8
	v_lshl_add_u64 v[8:9], v[8:9], 2, s[0:1]
	v_add_u32_e32 v12, s22, v3
	s_movk_i32 s27, 0x5800
	v_mad_i64_i32 v[20:21], s[24:25], v12, s27, v[8:9]
	v_add_u32_e32 v10, 8, v12
	v_mad_i64_i32 v[22:23], s[24:25], v10, s27, v[8:9]
	v_add_u32_e32 v10, 16, v12
	v_mad_i64_i32 v[24:25], s[24:25], v10, s27, v[8:9]
	v_add_u32_e32 v10, 24, v12
	v_mad_i64_i32 v[26:27], s[24:25], v10, s27, v[8:9]
	v_add_u32_e32 v10, 32, v12
	v_mad_i64_i32 v[28:29], s[24:25], v10, s27, v[8:9]
	v_add_u32_e32 v10, 40, v12
	v_mad_i64_i32 v[30:31], s[24:25], v10, s27, v[8:9]
	v_add_u32_e32 v10, 48, v12
	v_mad_i64_i32 v[32:33], s[24:25], v10, s27, v[8:9]
	v_add_u32_e32 v10, 56, v12
	v_mad_i64_i32 v[34:35], s[24:25], v10, s27, v[8:9]
	flat_load_dword v20, v[20:21]
	flat_load_dword v22, v[22:23]
	flat_load_dword v24, v[24:25]
	flat_load_dword v26, v[26:27]
	flat_load_dword v28, v[28:29]
	flat_load_dword v30, v[30:31]
	flat_load_dword v32, v[32:33]
	flat_load_dword v34, v[34:35]
	s_movk_i32 s24, 0x1600
	s_waitcnt vmcnt(0) lgkmcnt(0)
	ds_write_b32 v6, v20
	ds_write_b32 v6, v22 offset:2080
	ds_write_b32 v6, v24 offset:4160
	ds_write_b32 v6, v26 offset:6240
	ds_write_b32 v6, v28 offset:8320
	ds_write_b32 v6, v30 offset:10400
	ds_write_b32 v6, v32 offset:12480
	ds_write_b32 v6, v34 offset:14560
	v_add_u32_e32 v8, s26, v4
	v_cmp_gt_i32_e32 vcc, s24, v8
	s_waitcnt lgkmcnt(0)
	s_barrier
	s_and_saveexec_b64 s[24:25], vcc
	s_cbranch_execz .LBB0_882
	v_add_u32_e32 v9, 0x400, v7
	s_mulk_i32 s23, 0xd400
	ds_read2_b32 v[10:11], v7 offset1:65
	ds_read2_b32 v[12:13], v7 offset0:130 offset1:195
	ds_read2_b32 v[14:15], v9 offset0:4 offset1:69
	ds_read2_b32 v[16:17], v9 offset0:134 offset1:199
	v_add_u32_e32 v9, s23, v5
	v_and_b32_e32 v8, 0x7f, v8
	s_movk_i32 s23, 0xff00
	v_and_or_b32 v8, v9, s23, v8
	v_ashrrev_i32_e32 v9, 31, v8
	v_readlane_b32 s26, v251, 9
	v_lshlrev_b64 v[8:9], 12, v[8:9]
	v_readlane_b32 s27, v251, 10
	s_ashr_i32 s23, s22, 31
	s_waitcnt lgkmcnt(3)
	v_cvt_pk_bf16_f32 v10, v10, v11
	s_waitcnt lgkmcnt(2)
	v_cvt_pk_bf16_f32 v11, v12, v13
	s_waitcnt lgkmcnt(1)
	v_cvt_pk_bf16_f32 v12, v14, v15
	s_waitcnt lgkmcnt(0)
	v_cvt_pk_bf16_f32 v13, v16, v17
	v_lshl_add_u64 v[8:9], s[26:27], 0, v[8:9]
	v_lshl_add_u64 v[8:9], s[22:23], 1, v[8:9]
	v_lshl_add_u64 v[8:9], v[8:9], 0, v[0:1]
	global_store_dwordx4 v[8:9], v[10:13], off
	s_branch .LBB0_882

.LBB0_888:
	s_mul_hi_i32 s22, s14, 0x2e8ba2e9
	s_lshr_b32 s23, s22, 31
	s_ashr_i32 s22, s22, 4
	s_add_i32 s23, s22, s23
	s_mul_i32 s22, s23, 0xffffea00
	s_add_i32 s26, s22, s6
	v_add_u32_e32 v8, s26, v2
	s_lshl_b32 s22, s23, 6
	v_ashrrev_i32_e32 v9, 31, v8
	v_lshl_add_u64 v[8:9], v[8:9], 2, s[0:1]
	v_add_u32_e32 v12, s22, v3
	s_movk_i32 s27, 0x5800
	v_mad_i64_i32 v[20:21], s[24:25], v12, s27, v[8:9]
	v_add_u32_e32 v10, 8, v12
	v_mad_i64_i32 v[22:23], s[24:25], v10, s27, v[8:9]
	v_add_u32_e32 v10, 16, v12
	v_mad_i64_i32 v[24:25], s[24:25], v10, s27, v[8:9]
	v_add_u32_e32 v10, 24, v12
	v_mad_i64_i32 v[26:27], s[24:25], v10, s27, v[8:9]
	v_add_u32_e32 v10, 32, v12
	v_mad_i64_i32 v[28:29], s[24:25], v10, s27, v[8:9]
	v_add_u32_e32 v10, 40, v12
	v_mad_i64_i32 v[30:31], s[24:25], v10, s27, v[8:9]
	v_add_u32_e32 v10, 48, v12
	v_mad_i64_i32 v[32:33], s[24:25], v10, s27, v[8:9]
	v_add_u32_e32 v10, 56, v12
	v_mad_i64_i32 v[34:35], s[24:25], v10, s27, v[8:9]
	flat_load_dword v20, v[20:21]
	flat_load_dword v22, v[22:23]
	flat_load_dword v24, v[24:25]
	flat_load_dword v26, v[26:27]
	flat_load_dword v28, v[28:29]
	flat_load_dword v30, v[30:31]
	flat_load_dword v32, v[32:33]
	flat_load_dword v34, v[34:35]
	s_movk_i32 s24, 0x1600
	s_waitcnt vmcnt(0) lgkmcnt(0)
	ds_write_b32 v6, v20
	ds_write_b32 v6, v22 offset:2080
	ds_write_b32 v6, v24 offset:4160
	ds_write_b32 v6, v26 offset:6240
	ds_write_b32 v6, v28 offset:8320
	ds_write_b32 v6, v30 offset:10400
	ds_write_b32 v6, v32 offset:12480
	ds_write_b32 v6, v34 offset:14560
	v_add_u32_e32 v8, s26, v4
	v_cmp_gt_i32_e32 vcc, s24, v8
	s_waitcnt lgkmcnt(0)
	s_barrier
	s_and_saveexec_b64 s[24:25], vcc
	s_cbranch_execz .LBB0_887
	v_add_u32_e32 v9, 0x400, v7
	s_mulk_i32 s23, 0xd400
	ds_read2_b32 v[10:11], v7 offset1:65
	ds_read2_b32 v[12:13], v7 offset0:130 offset1:195
	ds_read2_b32 v[14:15], v9 offset0:4 offset1:69
	ds_read2_b32 v[16:17], v9 offset0:134 offset1:199
	v_add_u32_e32 v9, s23, v5
	v_and_b32_e32 v9, 0xffffff00, v9
	v_and_b32_e32 v8, 0x7f, v8
	s_movk_i32 s23, 0x80
	v_or3_b32 v8, v8, v9, s23
	v_ashrrev_i32_e32 v9, 31, v8
	v_readlane_b32 s26, v251, 9
	v_lshlrev_b64 v[8:9], 12, v[8:9]
	v_readlane_b32 s27, v251, 10
	s_ashr_i32 s23, s22, 31
	s_waitcnt lgkmcnt(3)
	v_cvt_pk_bf16_f32 v10, v10, v11
	s_waitcnt lgkmcnt(2)
	v_cvt_pk_bf16_f32 v11, v12, v13
	s_waitcnt lgkmcnt(1)
	v_cvt_pk_bf16_f32 v12, v14, v15
	s_waitcnt lgkmcnt(0)
	v_cvt_pk_bf16_f32 v13, v16, v17
	v_lshl_add_u64 v[8:9], s[26:27], 0, v[8:9]
	v_lshl_add_u64 v[8:9], s[22:23], 1, v[8:9]
	v_lshl_add_u64 v[8:9], v[8:9], 0, v[0:1]
	global_store_dwordx4 v[8:9], v[10:13], off
	s_branch .LBB0_887

.LBB0_893:
	s_ashr_i32 s14, s7, 31
	s_lshr_b32 s14, s14, 27
	s_add_i32 s14, s7, s14
	s_ashr_i32 s14, s14, 5
	s_lshl_b32 s22, s14, 11
	s_sub_i32 s23, s4, s22
	s_lshl_b32 s22, s14, 6
	v_add_u32_e32 v8, s23, v2
	v_add_u32_e32 v10, s22, v3
	v_ashrrev_i32_e32 v9, 31, v8
	v_ashrrev_i32_e32 v11, 31, v10
	v_lshl_add_u64 v[8:9], v[8:9], 2, s[0:1]
	v_lshlrev_b64 v[12:13], 13, v[10:11]
	v_lshl_add_u64 v[20:21], v[8:9], 0, v[12:13]
	v_add_u32_e32 v12, 8, v10
	v_ashrrev_i32_e32 v13, 31, v12
	v_lshlrev_b64 v[12:13], 13, v[12:13]
	v_lshl_add_u64 v[22:23], v[8:9], 0, v[12:13]
	v_add_u32_e32 v12, 16, v10
	v_ashrrev_i32_e32 v13, 31, v12
	v_lshlrev_b64 v[12:13], 13, v[12:13]
	v_lshl_add_u64 v[24:25], v[8:9], 0, v[12:13]
	v_add_u32_e32 v12, 24, v10
	v_ashrrev_i32_e32 v13, 31, v12
	v_lshlrev_b64 v[12:13], 13, v[12:13]
	v_lshl_add_u64 v[26:27], v[8:9], 0, v[12:13]
	v_add_u32_e32 v12, 32, v10
	v_ashrrev_i32_e32 v13, 31, v12
	v_lshlrev_b64 v[12:13], 13, v[12:13]
	v_lshl_add_u64 v[28:29], v[8:9], 0, v[12:13]
	v_add_u32_e32 v12, 40, v10
	v_ashrrev_i32_e32 v13, 31, v12
	v_lshlrev_b64 v[12:13], 13, v[12:13]
	v_lshl_add_u64 v[30:31], v[8:9], 0, v[12:13]
	v_add_u32_e32 v12, 48, v10
	v_ashrrev_i32_e32 v13, 31, v12
	v_lshlrev_b64 v[12:13], 13, v[12:13]
	v_lshl_add_u64 v[32:33], v[8:9], 0, v[12:13]
	v_add_u32_e32 v12, 56, v10
	v_ashrrev_i32_e32 v13, 31, v12
	v_lshlrev_b64 v[12:13], 13, v[12:13]
	v_lshl_add_u64 v[34:35], v[8:9], 0, v[12:13]
	flat_load_dword v20, v[20:21]
	flat_load_dword v22, v[22:23]
	flat_load_dword v24, v[24:25]
	flat_load_dword v26, v[26:27]
	flat_load_dword v28, v[28:29]
	flat_load_dword v30, v[30:31]
	flat_load_dword v32, v[32:33]
	flat_load_dword v34, v[34:35]
	s_movk_i32 s14, 0x800
	s_waitcnt vmcnt(0) lgkmcnt(0)
	ds_write_b32 v5, v20
	ds_write_b32 v5, v22 offset:2080
	ds_write_b32 v5, v24 offset:4160
	ds_write_b32 v5, v26 offset:6240
	ds_write_b32 v5, v28 offset:8320
	ds_write_b32 v5, v30 offset:10400
	ds_write_b32 v5, v32 offset:12480
	ds_write_b32 v5, v34 offset:14560
	v_add_u32_e32 v7, s23, v4
	v_cmp_gt_i32_e32 vcc, s14, v7
	s_waitcnt lgkmcnt(0)
	s_barrier
	s_and_saveexec_b64 s[24:25], vcc
	s_cbranch_execz .LBB0_892
	ds_read2_b32 v[8:9], v6 offset1:65
	ds_read2_b32 v[10:11], v6 offset0:130 offset1:195
	v_add_u32_e32 v14, 0x400, v6
	ds_read2_b32 v[12:13], v14 offset0:4 offset1:69
	ds_read2_b32 v[14:15], v14 offset0:134 offset1:199
	v_readlane_b32 s26, v251, 11
	v_readlane_b32 s27, v251, 12
	s_waitcnt lgkmcnt(3)
	v_cvt_pk_bf16_f32 v8, v8, v9
	s_waitcnt lgkmcnt(2)
	v_cvt_pk_bf16_f32 v9, v10, v11
	s_waitcnt lgkmcnt(1)
	v_cvt_pk_bf16_f32 v10, v12, v13
	s_movk_i32 s14, 0x2c00
	s_ashr_i32 s23, s22, 31
	v_mov_b64_e32 v[12:13], s[26:27]
	v_mad_i64_i32 v[12:13], s[26:27], v7, s14, v[12:13]
	v_lshl_add_u64 v[12:13], s[22:23], 1, v[12:13]
	v_lshl_add_u64 v[12:13], v[12:13], 0, v[0:1]
	s_waitcnt lgkmcnt(0)
	v_cvt_pk_bf16_f32 v11, v14, v15
	global_store_dwordx4 v[12:13], v[8:11], off
	s_branch .LBB0_892

.LBB0_1034:
	s_add_u32 s26, s42, 0xfff80080
	s_addc_u32 s27, s43, -1
	s_add_i32 s58, 0, 0x10000
	v_add_u32_e32 v134, s58, v155
	ds_read_b128 v[148:151], v134
	ds_read_b128 v[158:161], v134 offset:1024
	ds_read_b128 v[162:165], v134 offset:2048
	ds_read_b128 v[180:183], v134 offset:3072
	s_cmp_eq_u32 s57, 28
	s_cselect_b32 s45, s23, s27
	s_cselect_b32 s44, s53, s26
	s_cselect_b32 s27, s1, s56
	s_cselect_b32 s26, s54, s55
	v_lshl_add_u64 v[134:135], s[42:43], 0, v[144:145]
	s_add_i32 m0, s7, 0xc000
	ds_read_b128 v[184:187], v157
	ds_read_b128 v[188:191], v157 offset:1024
	ds_read_b128 v[192:195], v157 offset:2048
	ds_read_b128 v[196:199], v157 offset:3072
	ds_read_b128 v[200:203], v157 offset:4096
	ds_read_b128 v[204:207], v157 offset:5120
	ds_read_b128 v[208:211], v157 offset:6144
	ds_read_b128 v[212:215], v157 offset:7168
	global_load_lds_dwordx4 v[134:135], off
	v_lshl_add_u64 v[134:135], s[42:43], 0, v[146:147]
	s_add_i32 m0, s7, 0xe000
	s_nop 0
	global_load_lds_dwordx4 v[134:135], off
	s_waitcnt lgkmcnt(8)
	s_barrier
	s_waitcnt lgkmcnt(0)
	s_setprio 1
	s_waitcnt lgkmcnt(0)
	v_mfma_f32_16x16x32_bf16 v[126:129], v[148:151], v[184:187], v[126:129]
	v_mfma_f32_16x16x32_bf16 v[122:125], v[162:165], v[184:187], v[122:125]
	v_mfma_f32_16x16x32_bf16 v[110:113], v[148:151], v[192:195], v[110:113]
	v_mfma_f32_16x16x32_bf16 v[106:109], v[162:165], v[192:195], v[106:109]
	v_mfma_f32_16x16x32_bf16 v[94:97], v[148:151], v[200:203], v[94:97]
	v_mfma_f32_16x16x32_bf16 v[90:93], v[162:165], v[200:203], v[90:93]
	v_mfma_f32_16x16x32_bf16 v[78:81], v[148:151], v[208:211], v[78:81]
	v_mfma_f32_16x16x32_bf16 v[74:77], v[162:165], v[208:211], v[74:77]
	v_mfma_f32_16x16x32_bf16 v[126:129], v[158:161], v[188:191], v[126:129]
	v_mfma_f32_16x16x32_bf16 v[122:125], v[180:183], v[188:191], v[122:125]
	v_mfma_f32_16x16x32_bf16 v[110:113], v[158:161], v[196:199], v[110:113]
	v_mfma_f32_16x16x32_bf16 v[106:109], v[180:183], v[196:199], v[106:109]
	v_mfma_f32_16x16x32_bf16 v[94:97], v[158:161], v[204:207], v[94:97]
	v_mfma_f32_16x16x32_bf16 v[90:93], v[180:183], v[204:207], v[90:93]
	v_mfma_f32_16x16x32_bf16 v[78:81], v[158:161], v[212:215], v[78:81]
	v_mfma_f32_16x16x32_bf16 v[74:77], v[180:183], v[212:215], v[74:77]
	s_setprio 0
	s_barrier
	s_add_i32 s60, 0, 0x14000
	v_add_u32_e32 v134, s60, v155
	s_add_i32 s58, s58, s6
	ds_read_b128 v[216:219], v134
	ds_read_b128 v[220:223], v134 offset:1024
	ds_read_b128 v[224:227], v134 offset:2048
	ds_read_b128 v[228:231], v134 offset:3072
	v_lshl_add_u64 v[134:135], s[26:27], 0, v[0:1]
	s_mov_b32 m0, s58
	v_lshl_add_u64 v[152:153], s[26:27], 0, v[138:139]
	global_load_lds_dwordx4 v[134:135], off
	s_add_i32 m0, s58, 0x2000
	s_nop 0
	global_load_lds_dwordx4 v[152:153], off
	s_barrier
	s_waitcnt lgkmcnt(0)
	s_setprio 1
	s_waitcnt lgkmcnt(0)
	v_mfma_f32_16x16x32_bf16 v[118:121], v[216:219], v[184:187], v[118:121]
	v_mfma_f32_16x16x32_bf16 v[114:117], v[224:227], v[184:187], v[114:117]
	v_mfma_f32_16x16x32_bf16 v[102:105], v[216:219], v[192:195], v[102:105]
	v_mfma_f32_16x16x32_bf16 v[98:101], v[224:227], v[192:195], v[98:101]
	v_mfma_f32_16x16x32_bf16 v[86:89], v[216:219], v[200:203], v[86:89]
	v_mfma_f32_16x16x32_bf16 v[82:85], v[224:227], v[200:203], v[82:85]
	v_mfma_f32_16x16x32_bf16 v[70:73], v[216:219], v[208:211], v[70:73]
	v_mfma_f32_16x16x32_bf16 v[66:69], v[224:227], v[208:211], v[66:69]
	v_mfma_f32_16x16x32_bf16 v[118:121], v[220:223], v[188:191], v[118:121]
	v_mfma_f32_16x16x32_bf16 v[114:117], v[228:231], v[188:191], v[114:117]
	v_mfma_f32_16x16x32_bf16 v[102:105], v[220:223], v[196:199], v[102:105]
	v_mfma_f32_16x16x32_bf16 v[98:101], v[228:231], v[196:199], v[98:101]
	v_mfma_f32_16x16x32_bf16 v[86:89], v[220:223], v[204:207], v[86:89]
	v_mfma_f32_16x16x32_bf16 v[82:85], v[228:231], v[204:207], v[82:85]
	v_mfma_f32_16x16x32_bf16 v[70:73], v[220:223], v[212:215], v[70:73]
	v_mfma_f32_16x16x32_bf16 v[66:69], v[228:231], v[212:215], v[66:69]
	s_setprio 0
	s_mov_b32 m0, s7
	v_lshl_add_u64 v[166:167], s[44:45], 0, v[142:143]
	s_barrier
	ds_read_b128 v[184:187], v157 offset:16384
	ds_read_b128 v[188:191], v157 offset:17408
	ds_read_b128 v[192:195], v157 offset:18432
	ds_read_b128 v[196:199], v157 offset:19456
	ds_read_b128 v[200:203], v157 offset:20480
	ds_read_b128 v[204:207], v157 offset:21504
	ds_read_b128 v[208:211], v157 offset:22528
	ds_read_b128 v[212:215], v157 offset:23552
	global_load_lds_dwordx4 v[166:167], off
	v_lshl_add_u64 v[232:233], s[44:45], 0, v[140:141]
	s_mov_b32 m0, s14
	s_nop 0
	global_load_lds_dwordx4 v[232:233], off
	s_barrier
	s_waitcnt lgkmcnt(0)
	s_setprio 1
	s_waitcnt lgkmcnt(0)
	v_mfma_f32_16x16x32_bf16 v[62:65], v[148:151], v[184:187], v[62:65]
	v_mfma_f32_16x16x32_bf16 v[58:61], v[162:165], v[184:187], v[58:61]
	v_mfma_f32_16x16x32_bf16 v[46:49], v[148:151], v[192:195], v[46:49]
	v_mfma_f32_16x16x32_bf16 v[42:45], v[162:165], v[192:195], v[42:45]
	v_mfma_f32_16x16x32_bf16 v[30:33], v[148:151], v[200:203], v[30:33]
	v_mfma_f32_16x16x32_bf16 v[26:29], v[162:165], v[200:203], v[26:29]
	v_mfma_f32_16x16x32_bf16 v[14:17], v[148:151], v[208:211], v[14:17]
	v_mfma_f32_16x16x32_bf16 v[10:13], v[162:165], v[208:211], v[10:13]
	v_mfma_f32_16x16x32_bf16 v[62:65], v[158:161], v[188:191], v[62:65]
	v_mfma_f32_16x16x32_bf16 v[58:61], v[180:183], v[188:191], v[58:61]
	v_mfma_f32_16x16x32_bf16 v[46:49], v[158:161], v[196:199], v[46:49]
	v_mfma_f32_16x16x32_bf16 v[42:45], v[180:183], v[196:199], v[42:45]
	v_mfma_f32_16x16x32_bf16 v[30:33], v[158:161], v[204:207], v[30:33]
	v_mfma_f32_16x16x32_bf16 v[26:29], v[180:183], v[204:207], v[26:29]
	v_mfma_f32_16x16x32_bf16 v[14:17], v[158:161], v[212:215], v[14:17]
	v_mfma_f32_16x16x32_bf16 v[10:13], v[180:183], v[212:215], v[10:13]
	s_setprio 0
	s_barrier
	s_add_u32 s58, s26, 0x80000
	s_addc_u32 s59, s27, 0
	s_add_i32 s60, s60, s6
	v_lshl_add_u64 v[148:149], s[58:59], 0, v[0:1]
	s_mov_b32 m0, s60
	s_nop 0
	global_load_lds_dwordx4 v[148:149], off
	v_lshl_add_u64 v[148:149], s[58:59], 0, v[138:139]
	s_add_i32 m0, s60, 0x2000
	s_nop 0
	global_load_lds_dwordx4 v[148:149], off
	s_waitcnt vmcnt(6)
	s_barrier
	s_setprio 1
	v_mfma_f32_16x16x32_bf16 v[54:57], v[216:219], v[184:187], v[54:57]
	v_mfma_f32_16x16x32_bf16 v[50:53], v[224:227], v[184:187], v[50:53]
	v_mfma_f32_16x16x32_bf16 v[38:41], v[216:219], v[192:195], v[38:41]
	v_mfma_f32_16x16x32_bf16 v[34:37], v[224:227], v[192:195], v[34:37]
	v_mfma_f32_16x16x32_bf16 v[22:25], v[216:219], v[200:203], v[22:25]
	v_mfma_f32_16x16x32_bf16 v[18:21], v[224:227], v[200:203], v[18:21]
	v_mfma_f32_16x16x32_bf16 v[6:9], v[216:219], v[208:211], v[6:9]
	v_mfma_f32_16x16x32_bf16 v[2:5], v[224:227], v[208:211], v[2:5]
	v_mfma_f32_16x16x32_bf16 v[54:57], v[220:223], v[188:191], v[54:57]
	v_mfma_f32_16x16x32_bf16 v[50:53], v[228:231], v[188:191], v[50:53]
	v_mfma_f32_16x16x32_bf16 v[38:41], v[220:223], v[196:199], v[38:41]
	v_mfma_f32_16x16x32_bf16 v[34:37], v[228:231], v[196:199], v[34:37]
	v_mfma_f32_16x16x32_bf16 v[22:25], v[220:223], v[204:207], v[22:25]
	v_mfma_f32_16x16x32_bf16 v[18:21], v[228:231], v[204:207], v[18:21]
	v_mfma_f32_16x16x32_bf16 v[6:9], v[220:223], v[212:215], v[6:9]
	v_mfma_f32_16x16x32_bf16 v[2:5], v[228:231], v[212:215], v[2:5]
	s_setprio 0
	s_add_i32 s58, 0, 0x18000
	v_add_u32_e32 v180, s58, v155
	s_barrier
	ds_read_b128 v[148:151], v180
	ds_read_b128 v[158:161], v180 offset:1024
	ds_read_b128 v[162:165], v180 offset:2048
	ds_read_b128 v[180:183], v180 offset:3072
	s_add_u32 s44, s44, 0x80000
	s_addc_u32 s45, s45, 0
	s_mov_b32 m0, s46
	v_lshl_add_u64 v[216:217], s[44:45], 0, v[142:143]
	ds_read_b128 v[184:187], v157 offset:32768
	ds_read_b128 v[188:191], v157 offset:33792
	ds_read_b128 v[192:195], v157 offset:34816
	ds_read_b128 v[196:199], v157 offset:35840
	ds_read_b128 v[200:203], v157 offset:36864
	ds_read_b128 v[204:207], v157 offset:37888
	ds_read_b128 v[208:211], v157 offset:38912
	ds_read_b128 v[212:215], v157 offset:39936
	global_load_lds_dwordx4 v[216:217], off
	v_lshl_add_u64 v[216:217], s[44:45], 0, v[140:141]
	s_mov_b32 m0, s47
	s_nop 0
	global_load_lds_dwordx4 v[216:217], off
	s_waitcnt lgkmcnt(8)
	s_barrier
	s_waitcnt lgkmcnt(0)
	s_setprio 1
	s_waitcnt lgkmcnt(0)
	v_mfma_f32_16x16x32_bf16 v[126:129], v[148:151], v[184:187], v[126:129]
	v_mfma_f32_16x16x32_bf16 v[122:125], v[162:165], v[184:187], v[122:125]
	v_mfma_f32_16x16x32_bf16 v[110:113], v[148:151], v[192:195], v[110:113]
	v_mfma_f32_16x16x32_bf16 v[106:109], v[162:165], v[192:195], v[106:109]
	v_mfma_f32_16x16x32_bf16 v[94:97], v[148:151], v[200:203], v[94:97]
	v_mfma_f32_16x16x32_bf16 v[90:93], v[162:165], v[200:203], v[90:93]
	v_mfma_f32_16x16x32_bf16 v[78:81], v[148:151], v[208:211], v[78:81]
	v_mfma_f32_16x16x32_bf16 v[74:77], v[162:165], v[208:211], v[74:77]
	v_mfma_f32_16x16x32_bf16 v[126:129], v[158:161], v[188:191], v[126:129]
	v_mfma_f32_16x16x32_bf16 v[122:125], v[180:183], v[188:191], v[122:125]
	v_mfma_f32_16x16x32_bf16 v[110:113], v[158:161], v[196:199], v[110:113]
	v_mfma_f32_16x16x32_bf16 v[106:109], v[180:183], v[196:199], v[106:109]
	v_mfma_f32_16x16x32_bf16 v[94:97], v[158:161], v[204:207], v[94:97]
	v_mfma_f32_16x16x32_bf16 v[90:93], v[180:183], v[204:207], v[90:93]
	v_mfma_f32_16x16x32_bf16 v[78:81], v[158:161], v[212:215], v[78:81]
	v_mfma_f32_16x16x32_bf16 v[74:77], v[180:183], v[212:215], v[74:77]
	s_setprio 0
	s_barrier
	s_add_i32 s44, 0, 0x1c000
	s_add_i32 s45, s58, s6
	v_add_u32_e32 v228, s44, v155
	v_lshl_add_u64 v[134:135], v[134:135], 0, s[10:11]
	s_mov_b32 m0, s45
	ds_read_b128 v[216:219], v228
	ds_read_b128 v[220:223], v228 offset:1024
	ds_read_b128 v[224:227], v228 offset:2048
	ds_read_b128 v[228:231], v228 offset:3072
	global_load_lds_dwordx4 v[134:135], off
	v_lshl_add_u64 v[134:135], v[152:153], 0, s[10:11]
	s_add_i32 m0, s45, 0x2000
	s_nop 0
	global_load_lds_dwordx4 v[134:135], off
	s_barrier
	s_waitcnt lgkmcnt(0)
	s_setprio 1
	s_waitcnt lgkmcnt(0)
	v_mfma_f32_16x16x32_bf16 v[118:121], v[216:219], v[184:187], v[118:121]
	v_mfma_f32_16x16x32_bf16 v[114:117], v[224:227], v[184:187], v[114:117]
	v_mfma_f32_16x16x32_bf16 v[102:105], v[216:219], v[192:195], v[102:105]
	v_mfma_f32_16x16x32_bf16 v[98:101], v[224:227], v[192:195], v[98:101]
	v_mfma_f32_16x16x32_bf16 v[86:89], v[216:219], v[200:203], v[86:89]
	v_mfma_f32_16x16x32_bf16 v[82:85], v[224:227], v[200:203], v[82:85]
	v_mfma_f32_16x16x32_bf16 v[70:73], v[216:219], v[208:211], v[70:73]
	v_mfma_f32_16x16x32_bf16 v[66:69], v[224:227], v[208:211], v[66:69]
	v_mfma_f32_16x16x32_bf16 v[118:121], v[220:223], v[188:191], v[118:121]
	v_mfma_f32_16x16x32_bf16 v[114:117], v[228:231], v[188:191], v[114:117]
	v_mfma_f32_16x16x32_bf16 v[102:105], v[220:223], v[196:199], v[102:105]
	v_mfma_f32_16x16x32_bf16 v[98:101], v[228:231], v[196:199], v[98:101]
	v_mfma_f32_16x16x32_bf16 v[86:89], v[220:223], v[204:207], v[86:89]
	v_mfma_f32_16x16x32_bf16 v[82:85], v[228:231], v[204:207], v[82:85]
	v_mfma_f32_16x16x32_bf16 v[70:73], v[220:223], v[212:215], v[70:73]
	v_mfma_f32_16x16x32_bf16 v[66:69], v[228:231], v[212:215], v[66:69]
	s_setprio 0
	s_mov_b32 m0, s48
	v_lshl_add_u64 v[134:135], v[166:167], 0, s[10:11]
	s_barrier
	ds_read_b128 v[184:187], v157 offset:49152
	ds_read_b128 v[188:191], v157 offset:50176
	ds_read_b128 v[192:195], v157 offset:51200
	ds_read_b128 v[196:199], v157 offset:52224
	ds_read_b128 v[200:203], v157 offset:53248
	ds_read_b128 v[204:207], v157 offset:54272
	ds_read_b128 v[208:211], v157 offset:55296
	ds_read_b128 v[212:215], v157 offset:56320
	global_load_lds_dwordx4 v[134:135], off
	v_lshl_add_u64 v[134:135], v[232:233], 0, s[10:11]
	s_mov_b32 m0, s49
	s_nop 0
	global_load_lds_dwordx4 v[134:135], off
	s_barrier
	s_waitcnt lgkmcnt(0)
	s_setprio 1
	s_waitcnt lgkmcnt(0)
	v_mfma_f32_16x16x32_bf16 v[62:65], v[148:151], v[184:187], v[62:65]
	v_mfma_f32_16x16x32_bf16 v[58:61], v[162:165], v[184:187], v[58:61]
	v_mfma_f32_16x16x32_bf16 v[46:49], v[148:151], v[192:195], v[46:49]
	v_mfma_f32_16x16x32_bf16 v[42:45], v[162:165], v[192:195], v[42:45]
	v_mfma_f32_16x16x32_bf16 v[30:33], v[148:151], v[200:203], v[30:33]
	v_mfma_f32_16x16x32_bf16 v[26:29], v[162:165], v[200:203], v[26:29]
	v_mfma_f32_16x16x32_bf16 v[14:17], v[148:151], v[208:211], v[14:17]
	v_mfma_f32_16x16x32_bf16 v[10:13], v[162:165], v[208:211], v[10:13]
	v_mfma_f32_16x16x32_bf16 v[62:65], v[158:161], v[188:191], v[62:65]
	v_mfma_f32_16x16x32_bf16 v[58:61], v[180:183], v[188:191], v[58:61]
	v_mfma_f32_16x16x32_bf16 v[46:49], v[158:161], v[196:199], v[46:49]
	v_mfma_f32_16x16x32_bf16 v[42:45], v[180:183], v[196:199], v[42:45]
	v_mfma_f32_16x16x32_bf16 v[30:33], v[158:161], v[204:207], v[30:33]
	v_mfma_f32_16x16x32_bf16 v[26:29], v[180:183], v[204:207], v[26:29]
	v_mfma_f32_16x16x32_bf16 v[14:17], v[158:161], v[212:215], v[14:17]
	v_mfma_f32_16x16x32_bf16 v[10:13], v[180:183], v[212:215], v[10:13]
	s_setprio 0
	s_barrier
	s_add_u32 s26, s26, 0x80080
	s_addc_u32 s27, s27, 0
	s_add_i32 s44, s44, s6
	v_lshl_add_u64 v[134:135], s[26:27], 0, v[0:1]
	s_mov_b32 m0, s44
	s_nop 0
	global_load_lds_dwordx4 v[134:135], off
	v_lshl_add_u64 v[134:135], s[26:27], 0, v[138:139]
	s_add_i32 m0, s44, 0x2000
	s_nop 0
	global_load_lds_dwordx4 v[134:135], off
	s_waitcnt vmcnt(6)
	s_barrier
	s_setprio 1
	v_mfma_f32_16x16x32_bf16 v[54:57], v[216:219], v[184:187], v[54:57]
	v_mfma_f32_16x16x32_bf16 v[50:53], v[224:227], v[184:187], v[50:53]
	v_mfma_f32_16x16x32_bf16 v[38:41], v[216:219], v[192:195], v[38:41]
	v_mfma_f32_16x16x32_bf16 v[34:37], v[224:227], v[192:195], v[34:37]
	v_mfma_f32_16x16x32_bf16 v[22:25], v[216:219], v[200:203], v[22:25]
	v_mfma_f32_16x16x32_bf16 v[18:21], v[224:227], v[200:203], v[18:21]
	v_mfma_f32_16x16x32_bf16 v[6:9], v[216:219], v[208:211], v[6:9]
	v_mfma_f32_16x16x32_bf16 v[2:5], v[224:227], v[208:211], v[2:5]
	v_mfma_f32_16x16x32_bf16 v[54:57], v[220:223], v[188:191], v[54:57]
	v_mfma_f32_16x16x32_bf16 v[50:53], v[228:231], v[188:191], v[50:53]
	v_mfma_f32_16x16x32_bf16 v[38:41], v[220:223], v[196:199], v[38:41]
	v_mfma_f32_16x16x32_bf16 v[34:37], v[228:231], v[196:199], v[34:37]
	v_mfma_f32_16x16x32_bf16 v[22:25], v[220:223], v[204:207], v[22:25]
	v_mfma_f32_16x16x32_bf16 v[18:21], v[228:231], v[204:207], v[18:21]
	v_mfma_f32_16x16x32_bf16 v[6:9], v[220:223], v[212:215], v[6:9]
	v_mfma_f32_16x16x32_bf16 v[2:5], v[228:231], v[212:215], v[2:5]
	s_setprio 0
	s_add_i32 s57, s57, 2
	s_add_u32 s42, s42, 0x100
	s_addc_u32 s43, s43, 0
	s_add_u32 s55, s55, 0x100
	s_addc_u32 s56, s56, 0
	s_cmp_gt_u32 s57, 29
	s_barrier
	s_cbranch_scc0 .LBB0_1034
	v_lshl_add_u32 v150, s52, 8, v154
	v_lshl_or_b32 v134, s51, 8, v156
	v_ashrrev_i32_e32 v151, 31, v150
	v_ashrrev_i32_e32 v135, 31, v134
	v_lshlrev_b64 v[148:149], 13, v[150:151]
	v_lshl_add_u64 v[148:149], s[76:77], 0, v[148:149]
	v_lshlrev_b64 v[152:153], 2, v[134:135]
	v_lshl_add_u64 v[158:159], v[148:149], 0, v[152:153]
	v_readlane_b32 s56, v254, 30
	v_readlane_b32 s54, v254, 32
	v_readlane_b32 s60, v254, 39
	s_mov_b32 s51, s0
	s_mov_b32 s52, s22
	s_mov_b64 s[42:43], s[24:25]
	v_readlane_b32 s57, v254, 31
	v_readlane_b32 s55, v254, 33
	v_readlane_b32 s44, v254, 46
	v_readlane_b32 s61, v254, 40
	v_readlane_b32 s45, v254, 47
	v_mov_b64_e32 v[162:163], v[158:159]
	global_load_dwordx4 v[180:183], v[162:163], off
	global_load_dwordx4 v[184:187], v[162:163], off offset:16
	global_load_dwordx4 v[188:191], v[162:163], off offset:512
	global_load_dwordx4 v[192:195], v[162:163], off offset:528
	s_mov_b64 s[26:27], 0x20000
	v_lshl_add_u64 v[164:165], v[158:159], 0, s[26:27]
	global_load_dwordx4 v[196:199], v[164:165], off
	global_load_dwordx4 v[200:203], v[164:165], off offset:16
	global_load_dwordx4 v[204:207], v[164:165], off offset:512
	global_load_dwordx4 v[208:211], v[164:165], off offset:528
	s_mov_b64 s[26:27], 0x40000
	v_lshl_add_u64 v[150:151], v[158:159], 0, s[26:27]
	global_load_dwordx4 v[212:215], v[150:151], off
	global_load_dwordx4 v[216:219], v[150:151], off offset:16
	global_load_dwordx4 v[220:223], v[150:151], off offset:512
	global_load_dwordx4 v[224:227], v[150:151], off offset:528
	s_waitcnt vmcnt(8)
	v_pk_add_f32 v[126:127], v[126:127], v[180:181]
	v_pk_add_f32 v[128:129], v[128:129], v[182:183]
	v_pk_add_f32 v[122:123], v[122:123], v[184:185]
	v_pk_add_f32 v[124:125], v[124:125], v[186:187]
	v_pk_add_f32 v[118:119], v[118:119], v[188:189]
	v_pk_add_f32 v[120:121], v[120:121], v[190:191]
	v_pk_add_f32 v[114:115], v[114:115], v[192:193]
	v_pk_add_f32 v[116:117], v[116:117], v[194:195]
	global_store_dwordx4 v[162:163], v[126:129], off
	global_store_dwordx4 v[162:163], v[122:125], off offset:16
	global_store_dwordx4 v[162:163], v[118:121], off offset:512
	global_store_dwordx4 v[162:163], v[114:117], off offset:528
	s_mov_b64 s[26:27], 0x60000
	v_lshl_add_u64 v[228:229], v[158:159], 0, s[26:27]
	global_load_dwordx4 v[180:183], v[228:229], off
	global_load_dwordx4 v[184:187], v[228:229], off offset:16
	global_load_dwordx4 v[188:191], v[228:229], off offset:512
	global_load_dwordx4 v[192:195], v[228:229], off offset:528
	s_waitcnt vmcnt(12)
	v_pk_add_f32 v[110:111], v[110:111], v[196:197]
	v_pk_add_f32 v[112:113], v[112:113], v[198:199]
	v_pk_add_f32 v[106:107], v[106:107], v[200:201]
	v_pk_add_f32 v[108:109], v[108:109], v[202:203]
	v_pk_add_f32 v[102:103], v[102:103], v[204:205]
	v_pk_add_f32 v[104:105], v[104:105], v[206:207]
	v_pk_add_f32 v[98:99], v[98:99], v[208:209]
	v_pk_add_f32 v[100:101], v[100:101], v[210:211]
	global_store_dwordx4 v[164:165], v[110:113], off
	global_store_dwordx4 v[164:165], v[106:109], off offset:16
	global_store_dwordx4 v[164:165], v[102:105], off offset:512
	global_store_dwordx4 v[164:165], v[98:101], off offset:528
	s_mov_b64 s[26:27], 0x100000
	v_lshl_add_u64 v[162:163], v[158:159], 0, s[26:27]
	global_load_dwordx4 v[196:199], v[162:163], off
	global_load_dwordx4 v[200:203], v[162:163], off offset:16
	global_load_dwordx4 v[204:207], v[162:163], off offset:512
	global_load_dwordx4 v[208:211], v[162:163], off offset:528
	s_waitcnt vmcnt(16)
	v_pk_add_f32 v[94:95], v[94:95], v[212:213]
	v_pk_add_f32 v[96:97], v[96:97], v[214:215]
	v_pk_add_f32 v[90:91], v[90:91], v[216:217]
	v_pk_add_f32 v[92:93], v[92:93], v[218:219]
	v_pk_add_f32 v[86:87], v[86:87], v[220:221]
	v_pk_add_f32 v[88:89], v[88:89], v[222:223]
	v_pk_add_f32 v[82:83], v[82:83], v[224:225]
	v_pk_add_f32 v[84:85], v[84:85], v[226:227]
	global_store_dwordx4 v[150:151], v[94:97], off
	global_store_dwordx4 v[150:151], v[90:93], off offset:16
	global_store_dwordx4 v[150:151], v[86:89], off offset:512
	global_store_dwordx4 v[150:151], v[82:85], off offset:528
	s_mov_b64 s[26:27], 0x120000
	v_lshl_add_u64 v[164:165], v[158:159], 0, s[26:27]
	global_load_dwordx4 v[212:215], v[164:165], off
	global_load_dwordx4 v[216:219], v[164:165], off offset:16
	global_load_dwordx4 v[220:223], v[164:165], off offset:512
	global_load_dwordx4 v[224:227], v[164:165], off offset:528
	s_waitcnt vmcnt(16)
	v_pk_add_f32 v[78:79], v[78:79], v[180:181]
	v_pk_add_f32 v[80:81], v[80:81], v[182:183]
	v_pk_add_f32 v[74:75], v[74:75], v[184:185]
	v_pk_add_f32 v[76:77], v[76:77], v[186:187]
	v_pk_add_f32 v[70:71], v[70:71], v[188:189]
	v_pk_add_f32 v[72:73], v[72:73], v[190:191]
	v_pk_add_f32 v[66:67], v[66:67], v[192:193]
	v_pk_add_f32 v[68:69], v[68:69], v[194:195]
	global_store_dwordx4 v[228:229], v[78:81], off
	global_store_dwordx4 v[228:229], v[74:77], off offset:16
	global_store_dwordx4 v[228:229], v[70:73], off offset:512
	global_store_dwordx4 v[228:229], v[66:69], off offset:528
	s_mov_b64 s[26:27], 0x140000
	v_lshl_add_u64 v[150:151], v[158:159], 0, s[26:27]
	global_load_dwordx4 v[180:183], v[150:151], off
	global_load_dwordx4 v[184:187], v[150:151], off offset:16
	global_load_dwordx4 v[188:191], v[150:151], off offset:512
	global_load_dwordx4 v[192:195], v[150:151], off offset:528
	s_waitcnt vmcnt(16)
	v_pk_add_f32 v[62:63], v[62:63], v[196:197]
	v_pk_add_f32 v[64:65], v[64:65], v[198:199]
	v_pk_add_f32 v[58:59], v[58:59], v[200:201]
	v_pk_add_f32 v[60:61], v[60:61], v[202:203]
	v_pk_add_f32 v[54:55], v[54:55], v[204:205]
	v_pk_add_f32 v[56:57], v[56:57], v[206:207]
	v_pk_add_f32 v[50:51], v[50:51], v[208:209]
	v_pk_add_f32 v[52:53], v[52:53], v[210:211]
	global_store_dwordx4 v[162:163], v[62:65], off
	global_store_dwordx4 v[162:163], v[58:61], off offset:16
	global_store_dwordx4 v[162:163], v[54:57], off offset:512
	global_store_dwordx4 v[162:163], v[50:53], off offset:528
	s_mov_b64 s[26:27], 0x160000
	v_lshl_add_u64 v[228:229], v[158:159], 0, s[26:27]
	global_load_dwordx4 v[196:199], v[228:229], off
	global_load_dwordx4 v[200:203], v[228:229], off offset:16
	global_load_dwordx4 v[204:207], v[228:229], off offset:512
	global_load_dwordx4 v[208:211], v[228:229], off offset:528
	s_waitcnt vmcnt(16)
	v_pk_add_f32 v[46:47], v[46:47], v[212:213]
	v_pk_add_f32 v[48:49], v[48:49], v[214:215]
	v_pk_add_f32 v[42:43], v[42:43], v[216:217]
	v_pk_add_f32 v[44:45], v[44:45], v[218:219]
	v_pk_add_f32 v[38:39], v[38:39], v[220:221]
	v_pk_add_f32 v[40:41], v[40:41], v[222:223]
	v_pk_add_f32 v[34:35], v[34:35], v[224:225]
	v_pk_add_f32 v[36:37], v[36:37], v[226:227]
	global_store_dwordx4 v[164:165], v[46:49], off
	global_store_dwordx4 v[164:165], v[42:45], off offset:16
	global_store_dwordx4 v[164:165], v[38:41], off offset:512
	global_store_dwordx4 v[164:165], v[34:37], off offset:528
	s_waitcnt vmcnt(12)
	v_pk_add_f32 v[30:31], v[30:31], v[180:181]
	v_pk_add_f32 v[32:33], v[32:33], v[182:183]
	v_pk_add_f32 v[26:27], v[26:27], v[184:185]
	v_pk_add_f32 v[28:29], v[28:29], v[186:187]
	v_pk_add_f32 v[22:23], v[22:23], v[188:189]
	v_pk_add_f32 v[24:25], v[24:25], v[190:191]
	v_pk_add_f32 v[18:19], v[18:19], v[192:193]
	v_pk_add_f32 v[20:21], v[20:21], v[194:195]
	global_store_dwordx4 v[150:151], v[30:33], off
	global_store_dwordx4 v[150:151], v[26:29], off offset:16
	global_store_dwordx4 v[150:151], v[22:25], off offset:512
	global_store_dwordx4 v[150:151], v[18:21], off offset:528
	s_waitcnt vmcnt(8)
	v_pk_add_f32 v[14:15], v[14:15], v[196:197]
	v_pk_add_f32 v[16:17], v[16:17], v[198:199]
	v_pk_add_f32 v[10:11], v[10:11], v[200:201]
	v_pk_add_f32 v[12:13], v[12:13], v[202:203]
	v_pk_add_f32 v[6:7], v[6:7], v[204:205]
	v_pk_add_f32 v[8:9], v[8:9], v[206:207]
	v_pk_add_f32 v[2:3], v[2:3], v[208:209]
	v_pk_add_f32 v[4:5], v[4:5], v[210:211]
	global_store_dwordx4 v[228:229], v[14:17], off
	global_store_dwordx4 v[228:229], v[10:13], off offset:16
	global_store_dwordx4 v[228:229], v[6:9], off offset:512
	global_store_dwordx4 v[228:229], v[2:5], off offset:528
	s_mov_b32 s1, 0x160000
	s_and_b64 vcc, exec, s[38:39]
	s_mov_b64 s[26:27], s[40:41]
	s_cbranch_vccz .LBB0_1027
	s_waitcnt vmcnt(0)
	v_readlane_b32 s52, v254, 26
	v_readlane_b32 s50, v254, 28
	s_mov_b64 s[58:59], s[84:85]
	s_cmpk_gt_u32 s4, 0xff
	v_readlane_b32 s53, v254, 27
	v_readlane_b32 s51, v254, 29
	s_cbranch_scc1 .LBB0_1038
	s_barrier
